# v28: v13 + 16-deep rolling prefetch in the sample-state streaming loop (128 KB in flight per CU)
# baseline (speedup 1.0000x reference)
;     __host__ __device__ bool next(int i, Unit& u) const { const int L = i * G + c; if (L >= nun) return false; const int tile = L / S; u.ks = L - tile * S; u.pm = 64 + (tile >> 2); u.pn = tile & 3; return true; }
; template <class Epi, class Sched, bool ALIGN_EPI = false, bool SP2 = false>
; __device__ __forceinline__ void gemm_phase(PG8_LAS unsigned char* lds, const Gemm g, const Sched& S, const Epi& E) {
;     ...
;         const bool has_next = S.next(ui + 1, nxt);
;         const char* nA = has_next ? (const char*)g.A + (size_t)nxt.pm * tstep + (size_t)nxt.ks * K * 2 : cA; const char* nB = has_next ? (const char*)g.Bt + (size_t)nxt.pn * tstep + (size_t)nxt.ks * K * 2 : cB;
;         for (int t = 0; t < nt; t += 2) {
;             const bool last = (t == nt - 2);
;             const char* a1 = cA + (size_t)(t + 1) * kstep;
;             const char* a2 = last ? nA : cA + (size_t)(t + 2) * kstep; const char* b2 = last ? nB : cB + (size_t)(t + 2) * kstep;
;             const char* a3 = a2 + kstep; const char* b3 = b2 + kstep;
;     ...
; #pragma unroll
;         for (int a = 0; a < 2; ++a)
; #pragma unroll
;             for (int b = 0; b < 2; ++b)
; #pragma unroll
;                 for (int m = 0; m < 4; ++m)
; #pragma unroll
;                     for (int n = 0; n < 2; ++n) acc[a][b][m][n] = (f32x4){0.f, 0.f, 0.f, 0.f};
;         cur = nxt; cA = nA; cB = nB; ++ui;
.LBB0_286:
	s_ashr_i32 s19, s18, 31
	s_lshl_b64 s[20:21], s[18:19], 19
	s_add_u32 s20, s40, s20
	s_addc_u32 s21, s60, s21
	s_and_b64 s[58:59], s[8:9], exec
	s_cselect_b32 s19, s21, s39
	s_cselect_b32 s83, s20, s38
	s_ashr_i32 s17, s16, 31
	s_lshl_b64 s[58:59], s[16:17], 19
	s_add_u32 s62, s61, s58
	s_addc_u32 s63, s66, s59
	s_and_b64 s[58:59], s[8:9], exec
	s_cselect_b32 s17, s63, s37
	s_cselect_b32 vcc_lo, s62, s36
	s_add_u32 vcc_hi, s36, 0x100
	s_addc_u32 s84, s37, 0
	s_add_u32 s38, s38, 0x40080
	s_addc_u32 s39, s39, 0
	s_mov_b32 s85, -2
	v_mov_b64_e32 v[0:1], 0
	v_mov_b64_e32 v[2:3], 0
	v_mov_b64_e32 v[4:5], 0
	v_mov_b64_e32 v[6:7], 0
	v_mov_b64_e32 v[8:9], 0
	v_mov_b64_e32 v[10:11], 0
	v_mov_b64_e32 v[12:13], 0
	v_mov_b64_e32 v[14:15], 0
	s_waitcnt lgkmcnt(0)
	v_mov_b64_e32 v[18:19], 0
	v_mov_b64_e32 v[20:21], 0
	v_mov_b64_e32 v[22:23], 0
	v_mov_b64_e32 v[24:25], 0
	v_mov_b64_e32 v[26:27], 0
	v_mov_b64_e32 v[28:29], 0
	v_mov_b64_e32 v[30:31], 0
	v_mov_b64_e32 v[32:33], 0
	v_mov_b64_e32 v[34:35], 0
	v_mov_b64_e32 v[36:37], 0
	v_mov_b64_e32 v[38:39], 0
	v_mov_b64_e32 v[40:41], 0
	v_mov_b64_e32 v[42:43], 0
	v_mov_b64_e32 v[44:45], 0
	v_mov_b64_e32 v[46:47], 0
	v_mov_b64_e32 v[48:49], 0
	v_mov_b64_e32 v[50:51], 0
	v_mov_b64_e32 v[52:53], 0
	v_mov_b64_e32 v[54:55], 0
	v_mov_b64_e32 v[56:57], 0
	v_mov_b64_e32 v[58:59], 0
	v_mov_b64_e32 v[60:61], 0
	v_mov_b64_e32 v[62:63], 0
	v_mov_b64_e32 v[64:65], 0
	v_mov_b64_e32 v[66:67], 0
	v_mov_b64_e32 v[68:69], 0
	v_mov_b64_e32 v[70:71], 0
	v_mov_b64_e32 v[72:73], 0
	v_mov_b64_e32 v[74:75], 0
	v_mov_b64_e32 v[76:77], 0
	v_mov_b64_e32 v[78:79], 0
	v_mov_b64_e32 v[80:81], 0
	v_mov_b64_e32 v[82:83], 0
	v_mov_b64_e32 v[84:85], 0
	v_mov_b64_e32 v[86:87], 0
	v_mov_b64_e32 v[88:89], 0
	v_mov_b64_e32 v[90:91], 0
	v_mov_b64_e32 v[92:93], 0
	v_mov_b64_e32 v[94:95], 0
	v_mov_b64_e32 v[96:97], 0
	v_mov_b64_e32 v[98:99], 0
	v_mov_b64_e32 v[100:101], 0
	v_mov_b64_e32 v[102:103], 0
	v_mov_b64_e32 v[104:105], 0
	v_mov_b64_e32 v[106:107], 0
	v_mov_b64_e32 v[108:109], 0
	v_mov_b64_e32 v[110:111], 0
	v_mov_b64_e32 v[112:113], 0
	v_mov_b64_e32 v[114:115], 0
	v_mov_b64_e32 v[116:117], 0
	v_mov_b64_e32 v[118:119], 0
	v_mov_b64_e32 v[120:121], 0
	v_mov_b64_e32 v[122:123], 0
	v_mov_b64_e32 v[124:125], 0
	v_mov_b64_e32 v[126:127], 0
	v_mov_b64_e32 v[128:129], 0

; #define LAS __attribute__((address_space(3)))
; template <int TY> __device__ __forceinline__ void sample_item(const Params& p, ldsp lds, int item) {
;     ...
;     const int e4 = tid % E4, dg = tid / E4;
;     f32x4 v[8], o[8];
; #pragma unroll
;     for (int t = 0; t < 8; ++t) { v[t] = *(const LAS f32x4*)(Vs + t * DV + e4 * 4); o[t] = (f32x4){0.f, 0.f, 0.f, 0.f}; }
;     const float* S0 = (TY == 0 ? p.in[2] : (TY == 1 ? p.in[3] : p.in[4])) + (size_t)item * DK * DV;
;     float* S1 = p.out + (TY == 0 ? OUT_GLA_S : (TY == 1 ? OUT_HGRN_S : OUT_RET_S)) + (size_t)item * DK * DV;
; #pragma unroll 8
;     for (int d = dg; d < DK; d += NG) { const f32x4 s0 = __builtin_nontemporal_load((const f32x4*)(S0 + (size_t)d * DV + e4 * 4));
;         const f32x4 qa = *(const LAS f32x4*)(QK + d * 16), qb = *(const LAS f32x4*)(QK + d * 16 + 4), ka = *(const LAS f32x4*)(QK + d * 16 + 8), kb = *(const LAS f32x4*)(QK + d * 16 + 12);
;         const float dc = DECs[d];
;         o[0] += s0 * qa[0]; o[1] += s0 * qa[1]; o[2] += s0 * qa[2]; o[3] += s0 * qa[3]; o[4] += s0 * qb[0]; o[5] += s0 * qb[1]; o[6] += s0 * qb[2]; o[7] += s0 * qb[3];
;         f32x4 sn = s0 * dc; sn += v[0] * ka[0]; sn += v[1] * ka[1]; sn += v[2] * ka[2]; sn += v[3] * ka[3]; sn += v[4] * kb[0]; sn += v[5] * kb[1]; sn += v[6] * kb[2]; sn += v[7] * kb[3];
;         __builtin_nontemporal_store(sn, (f32x4*)(S1 + (size_t)d * DV + e4 * 4)); }
.LBB0_705:
	s_or_b64 exec, exec, s[8:9]
	v_cmp_lt_u32_e32 vcc, 27, v74
	s_and_saveexec_b64 s[8:9], vcc
	s_cbranch_execz .LBB0_709
	v_lshlrev_b64 v[18:19], 2, v[70:71]
	s_add_i32 s10, 0, 0xa000
	v_lshl_add_u32 v16, v98, 2, s10
	v_lshl_add_u32 v118, v98, 6, 0
	v_lshl_add_u32 v104, v98, 11, v18
	v_add_u32_e32 v105, 0x2000, v104
	v_add_u32_e32 v106, 0x4000, v104
	v_add_u32_e32 v107, 0x6000, v104
	v_add_u32_e32 v108, 0x8000, v104
	v_add_u32_e32 v109, 0xa000, v104
	v_add_u32_e32 v110, 0xc000, v104
	v_add_u32_e32 v111, 0xe000, v104
	v_add_u32_e32 v242, 0x10000, v104
	v_add_u32_e32 v243, 0x12000, v104
	v_add_u32_e32 v244, 0x14000, v104
	v_add_u32_e32 v245, 0x16000, v104
	v_add_u32_e32 v246, 0x18000, v104
	v_add_u32_e32 v247, 0x1a000, v104
	v_add_u32_e32 v248, 0x1c000, v104
	v_add_u32_e32 v249, 0x1e000, v104
	s_mov_b64 s[10:11], 0
	global_load_dwordx4 v[72:75], v104, s[12:13] nt
	global_load_dwordx4 v[76:79], v105, s[12:13] nt
	global_load_dwordx4 v[80:83], v106, s[12:13] nt
	global_load_dwordx4 v[84:87], v107, s[12:13] nt
	global_load_dwordx4 v[88:91], v108, s[12:13] nt
	global_load_dwordx4 v[92:95], v109, s[12:13] nt
	global_load_dwordx4 v[96:99], v110, s[12:13] nt
	global_load_dwordx4 v[100:103], v111, s[12:13] nt
	global_load_dwordx4 v[210:213], v242, s[12:13] nt
	global_load_dwordx4 v[214:217], v243, s[12:13] nt
	global_load_dwordx4 v[218:221], v244, s[12:13] nt
	global_load_dwordx4 v[222:225], v245, s[12:13] nt
	global_load_dwordx4 v[226:229], v246, s[12:13] nt
	global_load_dwordx4 v[230:233], v247, s[12:13] nt
	global_load_dwordx4 v[234:237], v248, s[12:13] nt
	global_load_dwordx4 v[238:241], v249, s[12:13] nt
	ds_read_b128 v[120:123], v118
	ds_read_b128 v[124:127], v118 offset:16
	ds_read_b128 v[128:131], v118 offset:32
	ds_read_b128 v[132:135], v118 offset:48
	ds_read_b32 v136, v16 offset:0
	s_waitcnt vmcnt(15) lgkmcnt(3)
	v_pk_fma_f32 v[64:65], v[72:73], v[120:121], v[64:65] op_sel_hi:[1,0,1]
	v_pk_fma_f32 v[66:67], v[74:75], v[120:121], v[66:67] op_sel_hi:[1,0,1]
	v_pk_fma_f32 v[60:61], v[72:73], v[120:121], v[60:61] op_sel:[0,1,0]
	v_pk_fma_f32 v[62:63], v[74:75], v[120:121], v[62:63] op_sel:[0,1,0]
	v_pk_fma_f32 v[56:57], v[72:73], v[122:123], v[56:57] op_sel_hi:[1,0,1]
	v_pk_fma_f32 v[58:59], v[74:75], v[122:123], v[58:59] op_sel_hi:[1,0,1]
	v_pk_fma_f32 v[52:53], v[72:73], v[122:123], v[52:53] op_sel:[0,1,0]
	v_pk_fma_f32 v[54:55], v[74:75], v[122:123], v[54:55] op_sel:[0,1,0]
	v_pk_fma_f32 v[48:49], v[72:73], v[124:125], v[48:49] op_sel_hi:[1,0,1]
	v_pk_fma_f32 v[50:51], v[74:75], v[124:125], v[50:51] op_sel_hi:[1,0,1]
	v_pk_fma_f32 v[40:41], v[72:73], v[124:125], v[40:41] op_sel:[0,1,0]
	v_pk_fma_f32 v[42:43], v[74:75], v[124:125], v[42:43] op_sel:[0,1,0]
	v_pk_fma_f32 v[36:37], v[72:73], v[126:127], v[36:37] op_sel_hi:[1,0,1]
	v_pk_fma_f32 v[38:39], v[74:75], v[126:127], v[38:39] op_sel_hi:[1,0,1]
	v_pk_fma_f32 v[44:45], v[72:73], v[126:127], v[44:45] op_sel:[0,1,0]
	v_pk_fma_f32 v[46:47], v[74:75], v[126:127], v[46:47] op_sel:[0,1,0]
	ds_read_b128 v[120:123], v118 offset:256
	ds_read_b128 v[124:127], v118 offset:272
	s_waitcnt lgkmcnt(2)
	v_pk_mul_f32 v[72:73], v[72:73], v[136:137] op_sel_hi:[1,0]
	v_pk_mul_f32 v[74:75], v[74:75], v[136:137] op_sel_hi:[1,0]
	v_pk_fma_f32 v[72:73], v[0:1], v[128:129], v[72:73] op_sel_hi:[1,0,1]
	v_pk_fma_f32 v[74:75], v[2:3], v[128:129], v[74:75] op_sel_hi:[1,0,1]
	v_pk_fma_f32 v[72:73], v[4:5], v[128:129], v[72:73] op_sel:[0,1,0]
	v_pk_fma_f32 v[74:75], v[6:7], v[128:129], v[74:75] op_sel:[0,1,0]
	v_pk_fma_f32 v[72:73], v[8:9], v[130:131], v[72:73] op_sel_hi:[1,0,1]
	v_pk_fma_f32 v[74:75], v[10:11], v[130:131], v[74:75] op_sel_hi:[1,0,1]
	v_pk_fma_f32 v[72:73], v[12:13], v[130:131], v[72:73] op_sel:[0,1,0]
	v_pk_fma_f32 v[74:75], v[14:15], v[130:131], v[74:75] op_sel:[0,1,0]
	v_pk_fma_f32 v[72:73], v[20:21], v[132:133], v[72:73] op_sel_hi:[1,0,1]
	v_pk_fma_f32 v[74:75], v[22:23], v[132:133], v[74:75] op_sel_hi:[1,0,1]
	v_pk_fma_f32 v[72:73], v[24:25], v[132:133], v[72:73] op_sel:[0,1,0]
	v_pk_fma_f32 v[74:75], v[26:27], v[132:133], v[74:75] op_sel:[0,1,0]
	v_pk_fma_f32 v[72:73], v[28:29], v[134:135], v[72:73] op_sel_hi:[1,0,1]
	v_pk_fma_f32 v[74:75], v[30:31], v[134:135], v[74:75] op_sel_hi:[1,0,1]
	v_pk_fma_f32 v[72:73], v[32:33], v[134:135], v[72:73] op_sel:[0,1,0]
	v_pk_fma_f32 v[74:75], v[34:35], v[134:135], v[74:75] op_sel:[0,1,0]
	global_store_dwordx4 v104, v[72:75], s[14:15] nt
	v_add_u32_e32 v104, 0x20000, v104
	global_load_dwordx4 v[72:75], v104, s[12:13] nt
	ds_read_b128 v[128:131], v118 offset:288
	ds_read_b128 v[132:135], v118 offset:304
	ds_read_b32 v136, v16 offset:16
	s_waitcnt vmcnt(16) lgkmcnt(3)
	v_pk_fma_f32 v[64:65], v[76:77], v[120:121], v[64:65] op_sel_hi:[1,0,1]
	v_pk_fma_f32 v[66:67], v[78:79], v[120:121], v[66:67] op_sel_hi:[1,0,1]
	v_pk_fma_f32 v[60:61], v[76:77], v[120:121], v[60:61] op_sel:[0,1,0]
	v_pk_fma_f32 v[62:63], v[78:79], v[120:121], v[62:63] op_sel:[0,1,0]
	v_pk_fma_f32 v[56:57], v[76:77], v[122:123], v[56:57] op_sel_hi:[1,0,1]
	v_pk_fma_f32 v[58:59], v[78:79], v[122:123], v[58:59] op_sel_hi:[1,0,1]
	v_pk_fma_f32 v[52:53], v[76:77], v[122:123], v[52:53] op_sel:[0,1,0]
	v_pk_fma_f32 v[54:55], v[78:79], v[122:123], v[54:55] op_sel:[0,1,0]
	v_pk_fma_f32 v[48:49], v[76:77], v[124:125], v[48:49] op_sel_hi:[1,0,1]
	v_pk_fma_f32 v[50:51], v[78:79], v[124:125], v[50:51] op_sel_hi:[1,0,1]
	v_pk_fma_f32 v[40:41], v[76:77], v[124:125], v[40:41] op_sel:[0,1,0]
	v_pk_fma_f32 v[42:43], v[78:79], v[124:125], v[42:43] op_sel:[0,1,0]
	v_pk_fma_f32 v[36:37], v[76:77], v[126:127], v[36:37] op_sel_hi:[1,0,1]
	v_pk_fma_f32 v[38:39], v[78:79], v[126:127], v[38:39] op_sel_hi:[1,0,1]
	v_pk_fma_f32 v[44:45], v[76:77], v[126:127], v[44:45] op_sel:[0,1,0]
	v_pk_fma_f32 v[46:47], v[78:79], v[126:127], v[46:47] op_sel:[0,1,0]
	ds_read_b128 v[120:123], v118 offset:512
	ds_read_b128 v[124:127], v118 offset:528
	s_waitcnt lgkmcnt(2)
; #define LAS __attribute__((address_space(3)))
; template <int TY> __device__ __forceinline__ void sample_item(const Params& p, ldsp lds, int item) {
;     ...
; #pragma unroll 8
;     for (int d = dg; d < DK; d += NG) { const f32x4 s0 = __builtin_nontemporal_load((const f32x4*)(S0 + (size_t)d * DV + e4 * 4));
;         const f32x4 qa = *(const LAS f32x4*)(QK + d * 16), qb = *(const LAS f32x4*)(QK + d * 16 + 4), ka = *(const LAS f32x4*)(QK + d * 16 + 8), kb = *(const LAS f32x4*)(QK + d * 16 + 12);
;         const float dc = DECs[d];
;         o[0] += s0 * qa[0]; o[1] += s0 * qa[1]; o[2] += s0 * qa[2]; o[3] += s0 * qa[3]; o[4] += s0 * qb[0]; o[5] += s0 * qb[1]; o[6] += s0 * qb[2]; o[7] += s0 * qb[3];
;         f32x4 sn = s0 * dc; sn += v[0] * ka[0]; sn += v[1] * ka[1]; sn += v[2] * ka[2]; sn += v[3] * ka[3]; sn += v[4] * kb[0]; sn += v[5] * kb[1]; sn += v[6] * kb[2]; sn += v[7] * kb[3];
;         __builtin_nontemporal_store(sn, (f32x4*)(S1 + (size_t)d * DV + e4 * 4)); }
	v_pk_mul_f32 v[76:77], v[76:77], v[136:137] op_sel_hi:[1,0]
	v_pk_mul_f32 v[78:79], v[78:79], v[136:137] op_sel_hi:[1,0]
	v_pk_fma_f32 v[76:77], v[0:1], v[128:129], v[76:77] op_sel_hi:[1,0,1]
	v_pk_fma_f32 v[78:79], v[2:3], v[128:129], v[78:79] op_sel_hi:[1,0,1]
	v_pk_fma_f32 v[76:77], v[4:5], v[128:129], v[76:77] op_sel:[0,1,0]
	v_pk_fma_f32 v[78:79], v[6:7], v[128:129], v[78:79] op_sel:[0,1,0]
	v_pk_fma_f32 v[76:77], v[8:9], v[130:131], v[76:77] op_sel_hi:[1,0,1]
	v_pk_fma_f32 v[78:79], v[10:11], v[130:131], v[78:79] op_sel_hi:[1,0,1]
	v_pk_fma_f32 v[76:77], v[12:13], v[130:131], v[76:77] op_sel:[0,1,0]
	v_pk_fma_f32 v[78:79], v[14:15], v[130:131], v[78:79] op_sel:[0,1,0]
	v_pk_fma_f32 v[76:77], v[20:21], v[132:133], v[76:77] op_sel_hi:[1,0,1]
	v_pk_fma_f32 v[78:79], v[22:23], v[132:133], v[78:79] op_sel_hi:[1,0,1]
	v_pk_fma_f32 v[76:77], v[24:25], v[132:133], v[76:77] op_sel:[0,1,0]
	v_pk_fma_f32 v[78:79], v[26:27], v[132:133], v[78:79] op_sel:[0,1,0]
	v_pk_fma_f32 v[76:77], v[28:29], v[134:135], v[76:77] op_sel_hi:[1,0,1]
	v_pk_fma_f32 v[78:79], v[30:31], v[134:135], v[78:79] op_sel_hi:[1,0,1]
	v_pk_fma_f32 v[76:77], v[32:33], v[134:135], v[76:77] op_sel:[0,1,0]
	v_pk_fma_f32 v[78:79], v[34:35], v[134:135], v[78:79] op_sel:[0,1,0]
	global_store_dwordx4 v105, v[76:79], s[14:15] nt
	v_add_u32_e32 v105, 0x20000, v105
	global_load_dwordx4 v[76:79], v105, s[12:13] nt
	ds_read_b128 v[128:131], v118 offset:544
	ds_read_b128 v[132:135], v118 offset:560
	ds_read_b32 v136, v16 offset:32
	s_waitcnt vmcnt(17) lgkmcnt(3)
	v_pk_fma_f32 v[64:65], v[80:81], v[120:121], v[64:65] op_sel_hi:[1,0,1]
	v_pk_fma_f32 v[66:67], v[82:83], v[120:121], v[66:67] op_sel_hi:[1,0,1]
	v_pk_fma_f32 v[60:61], v[80:81], v[120:121], v[60:61] op_sel:[0,1,0]
	v_pk_fma_f32 v[62:63], v[82:83], v[120:121], v[62:63] op_sel:[0,1,0]
	v_pk_fma_f32 v[56:57], v[80:81], v[122:123], v[56:57] op_sel_hi:[1,0,1]
	v_pk_fma_f32 v[58:59], v[82:83], v[122:123], v[58:59] op_sel_hi:[1,0,1]
	v_pk_fma_f32 v[52:53], v[80:81], v[122:123], v[52:53] op_sel:[0,1,0]
	v_pk_fma_f32 v[54:55], v[82:83], v[122:123], v[54:55] op_sel:[0,1,0]
	v_pk_fma_f32 v[48:49], v[80:81], v[124:125], v[48:49] op_sel_hi:[1,0,1]
	v_pk_fma_f32 v[50:51], v[82:83], v[124:125], v[50:51] op_sel_hi:[1,0,1]
	v_pk_fma_f32 v[40:41], v[80:81], v[124:125], v[40:41] op_sel:[0,1,0]
	v_pk_fma_f32 v[42:43], v[82:83], v[124:125], v[42:43] op_sel:[0,1,0]
	v_pk_fma_f32 v[36:37], v[80:81], v[126:127], v[36:37] op_sel_hi:[1,0,1]
	v_pk_fma_f32 v[38:39], v[82:83], v[126:127], v[38:39] op_sel_hi:[1,0,1]
	v_pk_fma_f32 v[44:45], v[80:81], v[126:127], v[44:45] op_sel:[0,1,0]
	v_pk_fma_f32 v[46:47], v[82:83], v[126:127], v[46:47] op_sel:[0,1,0]
	ds_read_b128 v[120:123], v118 offset:768
	ds_read_b128 v[124:127], v118 offset:784
	s_waitcnt lgkmcnt(2)
	v_pk_mul_f32 v[80:81], v[80:81], v[136:137] op_sel_hi:[1,0]
	v_pk_mul_f32 v[82:83], v[82:83], v[136:137] op_sel_hi:[1,0]
	v_pk_fma_f32 v[80:81], v[0:1], v[128:129], v[80:81] op_sel_hi:[1,0,1]
	v_pk_fma_f32 v[82:83], v[2:3], v[128:129], v[82:83] op_sel_hi:[1,0,1]
	v_pk_fma_f32 v[80:81], v[4:5], v[128:129], v[80:81] op_sel:[0,1,0]
	v_pk_fma_f32 v[82:83], v[6:7], v[128:129], v[82:83] op_sel:[0,1,0]
	v_pk_fma_f32 v[80:81], v[8:9], v[130:131], v[80:81] op_sel_hi:[1,0,1]
	v_pk_fma_f32 v[82:83], v[10:11], v[130:131], v[82:83] op_sel_hi:[1,0,1]
	v_pk_fma_f32 v[80:81], v[12:13], v[130:131], v[80:81] op_sel:[0,1,0]
	v_pk_fma_f32 v[82:83], v[14:15], v[130:131], v[82:83] op_sel:[0,1,0]
	v_pk_fma_f32 v[80:81], v[20:21], v[132:133], v[80:81] op_sel_hi:[1,0,1]
	v_pk_fma_f32 v[82:83], v[22:23], v[132:133], v[82:83] op_sel_hi:[1,0,1]
	v_pk_fma_f32 v[80:81], v[24:25], v[132:133], v[80:81] op_sel:[0,1,0]
	v_pk_fma_f32 v[82:83], v[26:27], v[132:133], v[82:83] op_sel:[0,1,0]
	v_pk_fma_f32 v[80:81], v[28:29], v[134:135], v[80:81] op_sel_hi:[1,0,1]
	v_pk_fma_f32 v[82:83], v[30:31], v[134:135], v[82:83] op_sel_hi:[1,0,1]
	v_pk_fma_f32 v[80:81], v[32:33], v[134:135], v[80:81] op_sel:[0,1,0]
	v_pk_fma_f32 v[82:83], v[34:35], v[134:135], v[82:83] op_sel:[0,1,0]
	global_store_dwordx4 v106, v[80:83], s[14:15] nt
	v_add_u32_e32 v106, 0x20000, v106
	global_load_dwordx4 v[80:83], v106, s[12:13] nt
	ds_read_b128 v[128:131], v118 offset:800
	ds_read_b128 v[132:135], v118 offset:816
	ds_read_b32 v136, v16 offset:48
	s_waitcnt vmcnt(18) lgkmcnt(3)
	v_pk_fma_f32 v[64:65], v[84:85], v[120:121], v[64:65] op_sel_hi:[1,0,1]
	v_pk_fma_f32 v[66:67], v[86:87], v[120:121], v[66:67] op_sel_hi:[1,0,1]
	v_pk_fma_f32 v[60:61], v[84:85], v[120:121], v[60:61] op_sel:[0,1,0]
	v_pk_fma_f32 v[62:63], v[86:87], v[120:121], v[62:63] op_sel:[0,1,0]
	v_pk_fma_f32 v[56:57], v[84:85], v[122:123], v[56:57] op_sel_hi:[1,0,1]
	v_pk_fma_f32 v[58:59], v[86:87], v[122:123], v[58:59] op_sel_hi:[1,0,1]
	v_pk_fma_f32 v[52:53], v[84:85], v[122:123], v[52:53] op_sel:[0,1,0]
	v_pk_fma_f32 v[54:55], v[86:87], v[122:123], v[54:55] op_sel:[0,1,0]
	v_pk_fma_f32 v[48:49], v[84:85], v[124:125], v[48:49] op_sel_hi:[1,0,1]
	v_pk_fma_f32 v[50:51], v[86:87], v[124:125], v[50:51] op_sel_hi:[1,0,1]
	v_pk_fma_f32 v[40:41], v[84:85], v[124:125], v[40:41] op_sel:[0,1,0]
	v_pk_fma_f32 v[42:43], v[86:87], v[124:125], v[42:43] op_sel:[0,1,0]
	v_pk_fma_f32 v[36:37], v[84:85], v[126:127], v[36:37] op_sel_hi:[1,0,1]
	v_pk_fma_f32 v[38:39], v[86:87], v[126:127], v[38:39] op_sel_hi:[1,0,1]
	v_pk_fma_f32 v[44:45], v[84:85], v[126:127], v[44:45] op_sel:[0,1,0]
	v_pk_fma_f32 v[46:47], v[86:87], v[126:127], v[46:47] op_sel:[0,1,0]
	ds_read_b128 v[120:123], v118 offset:1024
	ds_read_b128 v[124:127], v118 offset:1040
	s_waitcnt lgkmcnt(2)
; #define LAS __attribute__((address_space(3)))
; template <int TY> __device__ __forceinline__ void sample_item(const Params& p, ldsp lds, int item) {
;     ...
; #pragma unroll 8
;     for (int d = dg; d < DK; d += NG) { const f32x4 s0 = __builtin_nontemporal_load((const f32x4*)(S0 + (size_t)d * DV + e4 * 4));
;         const f32x4 qa = *(const LAS f32x4*)(QK + d * 16), qb = *(const LAS f32x4*)(QK + d * 16 + 4), ka = *(const LAS f32x4*)(QK + d * 16 + 8), kb = *(const LAS f32x4*)(QK + d * 16 + 12);
;         const float dc = DECs[d];
;         o[0] += s0 * qa[0]; o[1] += s0 * qa[1]; o[2] += s0 * qa[2]; o[3] += s0 * qa[3]; o[4] += s0 * qb[0]; o[5] += s0 * qb[1]; o[6] += s0 * qb[2]; o[7] += s0 * qb[3];
;         f32x4 sn = s0 * dc; sn += v[0] * ka[0]; sn += v[1] * ka[1]; sn += v[2] * ka[2]; sn += v[3] * ka[3]; sn += v[4] * kb[0]; sn += v[5] * kb[1]; sn += v[6] * kb[2]; sn += v[7] * kb[3];
;         __builtin_nontemporal_store(sn, (f32x4*)(S1 + (size_t)d * DV + e4 * 4)); }
	v_pk_mul_f32 v[84:85], v[84:85], v[136:137] op_sel_hi:[1,0]
	v_pk_mul_f32 v[86:87], v[86:87], v[136:137] op_sel_hi:[1,0]
	v_pk_fma_f32 v[84:85], v[0:1], v[128:129], v[84:85] op_sel_hi:[1,0,1]
	v_pk_fma_f32 v[86:87], v[2:3], v[128:129], v[86:87] op_sel_hi:[1,0,1]
	v_pk_fma_f32 v[84:85], v[4:5], v[128:129], v[84:85] op_sel:[0,1,0]
	v_pk_fma_f32 v[86:87], v[6:7], v[128:129], v[86:87] op_sel:[0,1,0]
	v_pk_fma_f32 v[84:85], v[8:9], v[130:131], v[84:85] op_sel_hi:[1,0,1]
	v_pk_fma_f32 v[86:87], v[10:11], v[130:131], v[86:87] op_sel_hi:[1,0,1]
	v_pk_fma_f32 v[84:85], v[12:13], v[130:131], v[84:85] op_sel:[0,1,0]
	v_pk_fma_f32 v[86:87], v[14:15], v[130:131], v[86:87] op_sel:[0,1,0]
	v_pk_fma_f32 v[84:85], v[20:21], v[132:133], v[84:85] op_sel_hi:[1,0,1]
	v_pk_fma_f32 v[86:87], v[22:23], v[132:133], v[86:87] op_sel_hi:[1,0,1]
	v_pk_fma_f32 v[84:85], v[24:25], v[132:133], v[84:85] op_sel:[0,1,0]
	v_pk_fma_f32 v[86:87], v[26:27], v[132:133], v[86:87] op_sel:[0,1,0]
	v_pk_fma_f32 v[84:85], v[28:29], v[134:135], v[84:85] op_sel_hi:[1,0,1]
	v_pk_fma_f32 v[86:87], v[30:31], v[134:135], v[86:87] op_sel_hi:[1,0,1]
	v_pk_fma_f32 v[84:85], v[32:33], v[134:135], v[84:85] op_sel:[0,1,0]
	v_pk_fma_f32 v[86:87], v[34:35], v[134:135], v[86:87] op_sel:[0,1,0]
	global_store_dwordx4 v107, v[84:87], s[14:15] nt
	v_add_u32_e32 v107, 0x20000, v107
	global_load_dwordx4 v[84:87], v107, s[12:13] nt
	ds_read_b128 v[128:131], v118 offset:1056
	ds_read_b128 v[132:135], v118 offset:1072
	ds_read_b32 v136, v16 offset:64
	s_waitcnt vmcnt(19) lgkmcnt(3)
	v_pk_fma_f32 v[64:65], v[88:89], v[120:121], v[64:65] op_sel_hi:[1,0,1]
	v_pk_fma_f32 v[66:67], v[90:91], v[120:121], v[66:67] op_sel_hi:[1,0,1]
	v_pk_fma_f32 v[60:61], v[88:89], v[120:121], v[60:61] op_sel:[0,1,0]
	v_pk_fma_f32 v[62:63], v[90:91], v[120:121], v[62:63] op_sel:[0,1,0]
	v_pk_fma_f32 v[56:57], v[88:89], v[122:123], v[56:57] op_sel_hi:[1,0,1]
	v_pk_fma_f32 v[58:59], v[90:91], v[122:123], v[58:59] op_sel_hi:[1,0,1]
	v_pk_fma_f32 v[52:53], v[88:89], v[122:123], v[52:53] op_sel:[0,1,0]
	v_pk_fma_f32 v[54:55], v[90:91], v[122:123], v[54:55] op_sel:[0,1,0]
	v_pk_fma_f32 v[48:49], v[88:89], v[124:125], v[48:49] op_sel_hi:[1,0,1]
	v_pk_fma_f32 v[50:51], v[90:91], v[124:125], v[50:51] op_sel_hi:[1,0,1]
	v_pk_fma_f32 v[40:41], v[88:89], v[124:125], v[40:41] op_sel:[0,1,0]
	v_pk_fma_f32 v[42:43], v[90:91], v[124:125], v[42:43] op_sel:[0,1,0]
	v_pk_fma_f32 v[36:37], v[88:89], v[126:127], v[36:37] op_sel_hi:[1,0,1]
	v_pk_fma_f32 v[38:39], v[90:91], v[126:127], v[38:39] op_sel_hi:[1,0,1]
	v_pk_fma_f32 v[44:45], v[88:89], v[126:127], v[44:45] op_sel:[0,1,0]
	v_pk_fma_f32 v[46:47], v[90:91], v[126:127], v[46:47] op_sel:[0,1,0]
	ds_read_b128 v[120:123], v118 offset:1280
	ds_read_b128 v[124:127], v118 offset:1296
	s_waitcnt lgkmcnt(2)
	v_pk_mul_f32 v[88:89], v[88:89], v[136:137] op_sel_hi:[1,0]
	v_pk_mul_f32 v[90:91], v[90:91], v[136:137] op_sel_hi:[1,0]
	v_pk_fma_f32 v[88:89], v[0:1], v[128:129], v[88:89] op_sel_hi:[1,0,1]
	v_pk_fma_f32 v[90:91], v[2:3], v[128:129], v[90:91] op_sel_hi:[1,0,1]
	v_pk_fma_f32 v[88:89], v[4:5], v[128:129], v[88:89] op_sel:[0,1,0]
	v_pk_fma_f32 v[90:91], v[6:7], v[128:129], v[90:91] op_sel:[0,1,0]
	v_pk_fma_f32 v[88:89], v[8:9], v[130:131], v[88:89] op_sel_hi:[1,0,1]
	v_pk_fma_f32 v[90:91], v[10:11], v[130:131], v[90:91] op_sel_hi:[1,0,1]
	v_pk_fma_f32 v[88:89], v[12:13], v[130:131], v[88:89] op_sel:[0,1,0]
	v_pk_fma_f32 v[90:91], v[14:15], v[130:131], v[90:91] op_sel:[0,1,0]
	v_pk_fma_f32 v[88:89], v[20:21], v[132:133], v[88:89] op_sel_hi:[1,0,1]
	v_pk_fma_f32 v[90:91], v[22:23], v[132:133], v[90:91] op_sel_hi:[1,0,1]
	v_pk_fma_f32 v[88:89], v[24:25], v[132:133], v[88:89] op_sel:[0,1,0]
	v_pk_fma_f32 v[90:91], v[26:27], v[132:133], v[90:91] op_sel:[0,1,0]
	v_pk_fma_f32 v[88:89], v[28:29], v[134:135], v[88:89] op_sel_hi:[1,0,1]
	v_pk_fma_f32 v[90:91], v[30:31], v[134:135], v[90:91] op_sel_hi:[1,0,1]
	v_pk_fma_f32 v[88:89], v[32:33], v[134:135], v[88:89] op_sel:[0,1,0]
	v_pk_fma_f32 v[90:91], v[34:35], v[134:135], v[90:91] op_sel:[0,1,0]
	global_store_dwordx4 v108, v[88:91], s[14:15] nt
	v_add_u32_e32 v108, 0x20000, v108
	global_load_dwordx4 v[88:91], v108, s[12:13] nt
	ds_read_b128 v[128:131], v118 offset:1312
	ds_read_b128 v[132:135], v118 offset:1328
	ds_read_b32 v136, v16 offset:80
	s_waitcnt vmcnt(20) lgkmcnt(3)
	v_pk_fma_f32 v[64:65], v[92:93], v[120:121], v[64:65] op_sel_hi:[1,0,1]
	v_pk_fma_f32 v[66:67], v[94:95], v[120:121], v[66:67] op_sel_hi:[1,0,1]
	v_pk_fma_f32 v[60:61], v[92:93], v[120:121], v[60:61] op_sel:[0,1,0]
	v_pk_fma_f32 v[62:63], v[94:95], v[120:121], v[62:63] op_sel:[0,1,0]
	v_pk_fma_f32 v[56:57], v[92:93], v[122:123], v[56:57] op_sel_hi:[1,0,1]
	v_pk_fma_f32 v[58:59], v[94:95], v[122:123], v[58:59] op_sel_hi:[1,0,1]
	v_pk_fma_f32 v[52:53], v[92:93], v[122:123], v[52:53] op_sel:[0,1,0]
	v_pk_fma_f32 v[54:55], v[94:95], v[122:123], v[54:55] op_sel:[0,1,0]
	v_pk_fma_f32 v[48:49], v[92:93], v[124:125], v[48:49] op_sel_hi:[1,0,1]
	v_pk_fma_f32 v[50:51], v[94:95], v[124:125], v[50:51] op_sel_hi:[1,0,1]
	v_pk_fma_f32 v[40:41], v[92:93], v[124:125], v[40:41] op_sel:[0,1,0]
	v_pk_fma_f32 v[42:43], v[94:95], v[124:125], v[42:43] op_sel:[0,1,0]
	v_pk_fma_f32 v[36:37], v[92:93], v[126:127], v[36:37] op_sel_hi:[1,0,1]
	v_pk_fma_f32 v[38:39], v[94:95], v[126:127], v[38:39] op_sel_hi:[1,0,1]
	v_pk_fma_f32 v[44:45], v[92:93], v[126:127], v[44:45] op_sel:[0,1,0]
	v_pk_fma_f32 v[46:47], v[94:95], v[126:127], v[46:47] op_sel:[0,1,0]
	ds_read_b128 v[120:123], v118 offset:1536
	ds_read_b128 v[124:127], v118 offset:1552
	s_waitcnt lgkmcnt(2)
; #define LAS __attribute__((address_space(3)))
; template <int TY> __device__ __forceinline__ void sample_item(const Params& p, ldsp lds, int item) {
;     ...
; #pragma unroll 8
;     for (int d = dg; d < DK; d += NG) { const f32x4 s0 = __builtin_nontemporal_load((const f32x4*)(S0 + (size_t)d * DV + e4 * 4));
;         const f32x4 qa = *(const LAS f32x4*)(QK + d * 16), qb = *(const LAS f32x4*)(QK + d * 16 + 4), ka = *(const LAS f32x4*)(QK + d * 16 + 8), kb = *(const LAS f32x4*)(QK + d * 16 + 12);
;         const float dc = DECs[d];
;         o[0] += s0 * qa[0]; o[1] += s0 * qa[1]; o[2] += s0 * qa[2]; o[3] += s0 * qa[3]; o[4] += s0 * qb[0]; o[5] += s0 * qb[1]; o[6] += s0 * qb[2]; o[7] += s0 * qb[3];
;         f32x4 sn = s0 * dc; sn += v[0] * ka[0]; sn += v[1] * ka[1]; sn += v[2] * ka[2]; sn += v[3] * ka[3]; sn += v[4] * kb[0]; sn += v[5] * kb[1]; sn += v[6] * kb[2]; sn += v[7] * kb[3];
;         __builtin_nontemporal_store(sn, (f32x4*)(S1 + (size_t)d * DV + e4 * 4)); }
	v_pk_mul_f32 v[92:93], v[92:93], v[136:137] op_sel_hi:[1,0]
	v_pk_mul_f32 v[94:95], v[94:95], v[136:137] op_sel_hi:[1,0]
	v_pk_fma_f32 v[92:93], v[0:1], v[128:129], v[92:93] op_sel_hi:[1,0,1]
	v_pk_fma_f32 v[94:95], v[2:3], v[128:129], v[94:95] op_sel_hi:[1,0,1]
	v_pk_fma_f32 v[92:93], v[4:5], v[128:129], v[92:93] op_sel:[0,1,0]
	v_pk_fma_f32 v[94:95], v[6:7], v[128:129], v[94:95] op_sel:[0,1,0]
	v_pk_fma_f32 v[92:93], v[8:9], v[130:131], v[92:93] op_sel_hi:[1,0,1]
	v_pk_fma_f32 v[94:95], v[10:11], v[130:131], v[94:95] op_sel_hi:[1,0,1]
	v_pk_fma_f32 v[92:93], v[12:13], v[130:131], v[92:93] op_sel:[0,1,0]
	v_pk_fma_f32 v[94:95], v[14:15], v[130:131], v[94:95] op_sel:[0,1,0]
	v_pk_fma_f32 v[92:93], v[20:21], v[132:133], v[92:93] op_sel_hi:[1,0,1]
	v_pk_fma_f32 v[94:95], v[22:23], v[132:133], v[94:95] op_sel_hi:[1,0,1]
	v_pk_fma_f32 v[92:93], v[24:25], v[132:133], v[92:93] op_sel:[0,1,0]
	v_pk_fma_f32 v[94:95], v[26:27], v[132:133], v[94:95] op_sel:[0,1,0]
	v_pk_fma_f32 v[92:93], v[28:29], v[134:135], v[92:93] op_sel_hi:[1,0,1]
	v_pk_fma_f32 v[94:95], v[30:31], v[134:135], v[94:95] op_sel_hi:[1,0,1]
	v_pk_fma_f32 v[92:93], v[32:33], v[134:135], v[92:93] op_sel:[0,1,0]
	v_pk_fma_f32 v[94:95], v[34:35], v[134:135], v[94:95] op_sel:[0,1,0]
	global_store_dwordx4 v109, v[92:95], s[14:15] nt
	v_add_u32_e32 v109, 0x20000, v109
	global_load_dwordx4 v[92:95], v109, s[12:13] nt
	ds_read_b128 v[128:131], v118 offset:1568
	ds_read_b128 v[132:135], v118 offset:1584
	ds_read_b32 v136, v16 offset:96
	s_waitcnt vmcnt(21) lgkmcnt(3)
	v_pk_fma_f32 v[64:65], v[96:97], v[120:121], v[64:65] op_sel_hi:[1,0,1]
	v_pk_fma_f32 v[66:67], v[98:99], v[120:121], v[66:67] op_sel_hi:[1,0,1]
	v_pk_fma_f32 v[60:61], v[96:97], v[120:121], v[60:61] op_sel:[0,1,0]
	v_pk_fma_f32 v[62:63], v[98:99], v[120:121], v[62:63] op_sel:[0,1,0]
	v_pk_fma_f32 v[56:57], v[96:97], v[122:123], v[56:57] op_sel_hi:[1,0,1]
	v_pk_fma_f32 v[58:59], v[98:99], v[122:123], v[58:59] op_sel_hi:[1,0,1]
	v_pk_fma_f32 v[52:53], v[96:97], v[122:123], v[52:53] op_sel:[0,1,0]
	v_pk_fma_f32 v[54:55], v[98:99], v[122:123], v[54:55] op_sel:[0,1,0]
	v_pk_fma_f32 v[48:49], v[96:97], v[124:125], v[48:49] op_sel_hi:[1,0,1]
	v_pk_fma_f32 v[50:51], v[98:99], v[124:125], v[50:51] op_sel_hi:[1,0,1]
	v_pk_fma_f32 v[40:41], v[96:97], v[124:125], v[40:41] op_sel:[0,1,0]
	v_pk_fma_f32 v[42:43], v[98:99], v[124:125], v[42:43] op_sel:[0,1,0]
	v_pk_fma_f32 v[36:37], v[96:97], v[126:127], v[36:37] op_sel_hi:[1,0,1]
	v_pk_fma_f32 v[38:39], v[98:99], v[126:127], v[38:39] op_sel_hi:[1,0,1]
	v_pk_fma_f32 v[44:45], v[96:97], v[126:127], v[44:45] op_sel:[0,1,0]
	v_pk_fma_f32 v[46:47], v[98:99], v[126:127], v[46:47] op_sel:[0,1,0]
	ds_read_b128 v[120:123], v118 offset:1792
	ds_read_b128 v[124:127], v118 offset:1808
	s_waitcnt lgkmcnt(2)
	v_pk_mul_f32 v[96:97], v[96:97], v[136:137] op_sel_hi:[1,0]
	v_pk_mul_f32 v[98:99], v[98:99], v[136:137] op_sel_hi:[1,0]
	v_pk_fma_f32 v[96:97], v[0:1], v[128:129], v[96:97] op_sel_hi:[1,0,1]
	v_pk_fma_f32 v[98:99], v[2:3], v[128:129], v[98:99] op_sel_hi:[1,0,1]
	v_pk_fma_f32 v[96:97], v[4:5], v[128:129], v[96:97] op_sel:[0,1,0]
	v_pk_fma_f32 v[98:99], v[6:7], v[128:129], v[98:99] op_sel:[0,1,0]
	v_pk_fma_f32 v[96:97], v[8:9], v[130:131], v[96:97] op_sel_hi:[1,0,1]
	v_pk_fma_f32 v[98:99], v[10:11], v[130:131], v[98:99] op_sel_hi:[1,0,1]
	v_pk_fma_f32 v[96:97], v[12:13], v[130:131], v[96:97] op_sel:[0,1,0]
	v_pk_fma_f32 v[98:99], v[14:15], v[130:131], v[98:99] op_sel:[0,1,0]
	v_pk_fma_f32 v[96:97], v[20:21], v[132:133], v[96:97] op_sel_hi:[1,0,1]
	v_pk_fma_f32 v[98:99], v[22:23], v[132:133], v[98:99] op_sel_hi:[1,0,1]
	v_pk_fma_f32 v[96:97], v[24:25], v[132:133], v[96:97] op_sel:[0,1,0]
	v_pk_fma_f32 v[98:99], v[26:27], v[132:133], v[98:99] op_sel:[0,1,0]
	v_pk_fma_f32 v[96:97], v[28:29], v[134:135], v[96:97] op_sel_hi:[1,0,1]
	v_pk_fma_f32 v[98:99], v[30:31], v[134:135], v[98:99] op_sel_hi:[1,0,1]
	v_pk_fma_f32 v[96:97], v[32:33], v[134:135], v[96:97] op_sel:[0,1,0]
	v_pk_fma_f32 v[98:99], v[34:35], v[134:135], v[98:99] op_sel:[0,1,0]
	global_store_dwordx4 v110, v[96:99], s[14:15] nt
	v_add_u32_e32 v110, 0x20000, v110
	global_load_dwordx4 v[96:99], v110, s[12:13] nt
	ds_read_b128 v[128:131], v118 offset:1824
	ds_read_b128 v[132:135], v118 offset:1840
	ds_read_b32 v136, v16 offset:112
	s_waitcnt vmcnt(22) lgkmcnt(3)
	v_pk_fma_f32 v[64:65], v[100:101], v[120:121], v[64:65] op_sel_hi:[1,0,1]
	v_pk_fma_f32 v[66:67], v[102:103], v[120:121], v[66:67] op_sel_hi:[1,0,1]
	v_pk_fma_f32 v[60:61], v[100:101], v[120:121], v[60:61] op_sel:[0,1,0]
	v_pk_fma_f32 v[62:63], v[102:103], v[120:121], v[62:63] op_sel:[0,1,0]
	v_pk_fma_f32 v[56:57], v[100:101], v[122:123], v[56:57] op_sel_hi:[1,0,1]
	v_pk_fma_f32 v[58:59], v[102:103], v[122:123], v[58:59] op_sel_hi:[1,0,1]
	v_pk_fma_f32 v[52:53], v[100:101], v[122:123], v[52:53] op_sel:[0,1,0]
	v_pk_fma_f32 v[54:55], v[102:103], v[122:123], v[54:55] op_sel:[0,1,0]
	v_pk_fma_f32 v[48:49], v[100:101], v[124:125], v[48:49] op_sel_hi:[1,0,1]
	v_pk_fma_f32 v[50:51], v[102:103], v[124:125], v[50:51] op_sel_hi:[1,0,1]
	v_pk_fma_f32 v[40:41], v[100:101], v[124:125], v[40:41] op_sel:[0,1,0]
	v_pk_fma_f32 v[42:43], v[102:103], v[124:125], v[42:43] op_sel:[0,1,0]
	v_pk_fma_f32 v[36:37], v[100:101], v[126:127], v[36:37] op_sel_hi:[1,0,1]
	v_pk_fma_f32 v[38:39], v[102:103], v[126:127], v[38:39] op_sel_hi:[1,0,1]
	v_pk_fma_f32 v[44:45], v[100:101], v[126:127], v[44:45] op_sel:[0,1,0]
	v_pk_fma_f32 v[46:47], v[102:103], v[126:127], v[46:47] op_sel:[0,1,0]
	ds_read_b128 v[120:123], v118 offset:2048
	ds_read_b128 v[124:127], v118 offset:2064
	s_waitcnt lgkmcnt(2)
; #define LAS __attribute__((address_space(3)))
; template <int TY> __device__ __forceinline__ void sample_item(const Params& p, ldsp lds, int item) {
;     ...
; #pragma unroll 8
;     for (int d = dg; d < DK; d += NG) { const f32x4 s0 = __builtin_nontemporal_load((const f32x4*)(S0 + (size_t)d * DV + e4 * 4));
;         const f32x4 qa = *(const LAS f32x4*)(QK + d * 16), qb = *(const LAS f32x4*)(QK + d * 16 + 4), ka = *(const LAS f32x4*)(QK + d * 16 + 8), kb = *(const LAS f32x4*)(QK + d * 16 + 12);
;         const float dc = DECs[d];
;         o[0] += s0 * qa[0]; o[1] += s0 * qa[1]; o[2] += s0 * qa[2]; o[3] += s0 * qa[3]; o[4] += s0 * qb[0]; o[5] += s0 * qb[1]; o[6] += s0 * qb[2]; o[7] += s0 * qb[3];
;         f32x4 sn = s0 * dc; sn += v[0] * ka[0]; sn += v[1] * ka[1]; sn += v[2] * ka[2]; sn += v[3] * ka[3]; sn += v[4] * kb[0]; sn += v[5] * kb[1]; sn += v[6] * kb[2]; sn += v[7] * kb[3];
;         __builtin_nontemporal_store(sn, (f32x4*)(S1 + (size_t)d * DV + e4 * 4)); }
	v_pk_mul_f32 v[100:101], v[100:101], v[136:137] op_sel_hi:[1,0]
	v_pk_mul_f32 v[102:103], v[102:103], v[136:137] op_sel_hi:[1,0]
	v_pk_fma_f32 v[100:101], v[0:1], v[128:129], v[100:101] op_sel_hi:[1,0,1]
	v_pk_fma_f32 v[102:103], v[2:3], v[128:129], v[102:103] op_sel_hi:[1,0,1]
	v_pk_fma_f32 v[100:101], v[4:5], v[128:129], v[100:101] op_sel:[0,1,0]
	v_pk_fma_f32 v[102:103], v[6:7], v[128:129], v[102:103] op_sel:[0,1,0]
	v_pk_fma_f32 v[100:101], v[8:9], v[130:131], v[100:101] op_sel_hi:[1,0,1]
	v_pk_fma_f32 v[102:103], v[10:11], v[130:131], v[102:103] op_sel_hi:[1,0,1]
	v_pk_fma_f32 v[100:101], v[12:13], v[130:131], v[100:101] op_sel:[0,1,0]
	v_pk_fma_f32 v[102:103], v[14:15], v[130:131], v[102:103] op_sel:[0,1,0]
	v_pk_fma_f32 v[100:101], v[20:21], v[132:133], v[100:101] op_sel_hi:[1,0,1]
	v_pk_fma_f32 v[102:103], v[22:23], v[132:133], v[102:103] op_sel_hi:[1,0,1]
	v_pk_fma_f32 v[100:101], v[24:25], v[132:133], v[100:101] op_sel:[0,1,0]
	v_pk_fma_f32 v[102:103], v[26:27], v[132:133], v[102:103] op_sel:[0,1,0]
	v_pk_fma_f32 v[100:101], v[28:29], v[134:135], v[100:101] op_sel_hi:[1,0,1]
	v_pk_fma_f32 v[102:103], v[30:31], v[134:135], v[102:103] op_sel_hi:[1,0,1]
	v_pk_fma_f32 v[100:101], v[32:33], v[134:135], v[100:101] op_sel:[0,1,0]
	v_pk_fma_f32 v[102:103], v[34:35], v[134:135], v[102:103] op_sel:[0,1,0]
	global_store_dwordx4 v111, v[100:103], s[14:15] nt
	v_add_u32_e32 v111, 0x20000, v111
	global_load_dwordx4 v[100:103], v111, s[12:13] nt
	ds_read_b128 v[128:131], v118 offset:2080
	ds_read_b128 v[132:135], v118 offset:2096
	ds_read_b32 v136, v16 offset:128
	s_waitcnt vmcnt(23) lgkmcnt(3)
	v_pk_fma_f32 v[64:65], v[210:211], v[120:121], v[64:65] op_sel_hi:[1,0,1]
	v_pk_fma_f32 v[66:67], v[212:213], v[120:121], v[66:67] op_sel_hi:[1,0,1]
	v_pk_fma_f32 v[60:61], v[210:211], v[120:121], v[60:61] op_sel:[0,1,0]
	v_pk_fma_f32 v[62:63], v[212:213], v[120:121], v[62:63] op_sel:[0,1,0]
	v_pk_fma_f32 v[56:57], v[210:211], v[122:123], v[56:57] op_sel_hi:[1,0,1]
	v_pk_fma_f32 v[58:59], v[212:213], v[122:123], v[58:59] op_sel_hi:[1,0,1]
	v_pk_fma_f32 v[52:53], v[210:211], v[122:123], v[52:53] op_sel:[0,1,0]
	v_pk_fma_f32 v[54:55], v[212:213], v[122:123], v[54:55] op_sel:[0,1,0]
	v_pk_fma_f32 v[48:49], v[210:211], v[124:125], v[48:49] op_sel_hi:[1,0,1]
	v_pk_fma_f32 v[50:51], v[212:213], v[124:125], v[50:51] op_sel_hi:[1,0,1]
	v_pk_fma_f32 v[40:41], v[210:211], v[124:125], v[40:41] op_sel:[0,1,0]
	v_pk_fma_f32 v[42:43], v[212:213], v[124:125], v[42:43] op_sel:[0,1,0]
	v_pk_fma_f32 v[36:37], v[210:211], v[126:127], v[36:37] op_sel_hi:[1,0,1]
	v_pk_fma_f32 v[38:39], v[212:213], v[126:127], v[38:39] op_sel_hi:[1,0,1]
	v_pk_fma_f32 v[44:45], v[210:211], v[126:127], v[44:45] op_sel:[0,1,0]
	v_pk_fma_f32 v[46:47], v[212:213], v[126:127], v[46:47] op_sel:[0,1,0]
	ds_read_b128 v[120:123], v118 offset:2304
	ds_read_b128 v[124:127], v118 offset:2320
	s_waitcnt lgkmcnt(2)
	v_pk_mul_f32 v[210:211], v[210:211], v[136:137] op_sel_hi:[1,0]
	v_pk_mul_f32 v[212:213], v[212:213], v[136:137] op_sel_hi:[1,0]
	v_pk_fma_f32 v[210:211], v[0:1], v[128:129], v[210:211] op_sel_hi:[1,0,1]
	v_pk_fma_f32 v[212:213], v[2:3], v[128:129], v[212:213] op_sel_hi:[1,0,1]
	v_pk_fma_f32 v[210:211], v[4:5], v[128:129], v[210:211] op_sel:[0,1,0]
	v_pk_fma_f32 v[212:213], v[6:7], v[128:129], v[212:213] op_sel:[0,1,0]
	v_pk_fma_f32 v[210:211], v[8:9], v[130:131], v[210:211] op_sel_hi:[1,0,1]
	v_pk_fma_f32 v[212:213], v[10:11], v[130:131], v[212:213] op_sel_hi:[1,0,1]
	v_pk_fma_f32 v[210:211], v[12:13], v[130:131], v[210:211] op_sel:[0,1,0]
	v_pk_fma_f32 v[212:213], v[14:15], v[130:131], v[212:213] op_sel:[0,1,0]
	v_pk_fma_f32 v[210:211], v[20:21], v[132:133], v[210:211] op_sel_hi:[1,0,1]
	v_pk_fma_f32 v[212:213], v[22:23], v[132:133], v[212:213] op_sel_hi:[1,0,1]
	v_pk_fma_f32 v[210:211], v[24:25], v[132:133], v[210:211] op_sel:[0,1,0]
	v_pk_fma_f32 v[212:213], v[26:27], v[132:133], v[212:213] op_sel:[0,1,0]
	v_pk_fma_f32 v[210:211], v[28:29], v[134:135], v[210:211] op_sel_hi:[1,0,1]
	v_pk_fma_f32 v[212:213], v[30:31], v[134:135], v[212:213] op_sel_hi:[1,0,1]
	v_pk_fma_f32 v[210:211], v[32:33], v[134:135], v[210:211] op_sel:[0,1,0]
	v_pk_fma_f32 v[212:213], v[34:35], v[134:135], v[212:213] op_sel:[0,1,0]
	global_store_dwordx4 v242, v[210:213], s[14:15] nt
	v_add_u32_e32 v242, 0x20000, v242
	global_load_dwordx4 v[210:213], v242, s[12:13] nt
	ds_read_b128 v[128:131], v118 offset:2336
	ds_read_b128 v[132:135], v118 offset:2352
	ds_read_b32 v136, v16 offset:144
	s_waitcnt vmcnt(24) lgkmcnt(3)
	v_pk_fma_f32 v[64:65], v[214:215], v[120:121], v[64:65] op_sel_hi:[1,0,1]
	v_pk_fma_f32 v[66:67], v[216:217], v[120:121], v[66:67] op_sel_hi:[1,0,1]
	v_pk_fma_f32 v[60:61], v[214:215], v[120:121], v[60:61] op_sel:[0,1,0]
	v_pk_fma_f32 v[62:63], v[216:217], v[120:121], v[62:63] op_sel:[0,1,0]
	v_pk_fma_f32 v[56:57], v[214:215], v[122:123], v[56:57] op_sel_hi:[1,0,1]
	v_pk_fma_f32 v[58:59], v[216:217], v[122:123], v[58:59] op_sel_hi:[1,0,1]
	v_pk_fma_f32 v[52:53], v[214:215], v[122:123], v[52:53] op_sel:[0,1,0]
	v_pk_fma_f32 v[54:55], v[216:217], v[122:123], v[54:55] op_sel:[0,1,0]
	v_pk_fma_f32 v[48:49], v[214:215], v[124:125], v[48:49] op_sel_hi:[1,0,1]
	v_pk_fma_f32 v[50:51], v[216:217], v[124:125], v[50:51] op_sel_hi:[1,0,1]
	v_pk_fma_f32 v[40:41], v[214:215], v[124:125], v[40:41] op_sel:[0,1,0]
	v_pk_fma_f32 v[42:43], v[216:217], v[124:125], v[42:43] op_sel:[0,1,0]
	v_pk_fma_f32 v[36:37], v[214:215], v[126:127], v[36:37] op_sel_hi:[1,0,1]
	v_pk_fma_f32 v[38:39], v[216:217], v[126:127], v[38:39] op_sel_hi:[1,0,1]
	v_pk_fma_f32 v[44:45], v[214:215], v[126:127], v[44:45] op_sel:[0,1,0]
	v_pk_fma_f32 v[46:47], v[216:217], v[126:127], v[46:47] op_sel:[0,1,0]
	ds_read_b128 v[120:123], v118 offset:2560
	ds_read_b128 v[124:127], v118 offset:2576
	s_waitcnt lgkmcnt(2)
; #define LAS __attribute__((address_space(3)))
; template <int TY> __device__ __forceinline__ void sample_item(const Params& p, ldsp lds, int item) {
;     ...
; #pragma unroll 8
;     for (int d = dg; d < DK; d += NG) { const f32x4 s0 = __builtin_nontemporal_load((const f32x4*)(S0 + (size_t)d * DV + e4 * 4));
;         const f32x4 qa = *(const LAS f32x4*)(QK + d * 16), qb = *(const LAS f32x4*)(QK + d * 16 + 4), ka = *(const LAS f32x4*)(QK + d * 16 + 8), kb = *(const LAS f32x4*)(QK + d * 16 + 12);
;         const float dc = DECs[d];
;         o[0] += s0 * qa[0]; o[1] += s0 * qa[1]; o[2] += s0 * qa[2]; o[3] += s0 * qa[3]; o[4] += s0 * qb[0]; o[5] += s0 * qb[1]; o[6] += s0 * qb[2]; o[7] += s0 * qb[3];
;         f32x4 sn = s0 * dc; sn += v[0] * ka[0]; sn += v[1] * ka[1]; sn += v[2] * ka[2]; sn += v[3] * ka[3]; sn += v[4] * kb[0]; sn += v[5] * kb[1]; sn += v[6] * kb[2]; sn += v[7] * kb[3];
;         __builtin_nontemporal_store(sn, (f32x4*)(S1 + (size_t)d * DV + e4 * 4)); }
	v_pk_mul_f32 v[214:215], v[214:215], v[136:137] op_sel_hi:[1,0]
	v_pk_mul_f32 v[216:217], v[216:217], v[136:137] op_sel_hi:[1,0]
	v_pk_fma_f32 v[214:215], v[0:1], v[128:129], v[214:215] op_sel_hi:[1,0,1]
	v_pk_fma_f32 v[216:217], v[2:3], v[128:129], v[216:217] op_sel_hi:[1,0,1]
	v_pk_fma_f32 v[214:215], v[4:5], v[128:129], v[214:215] op_sel:[0,1,0]
	v_pk_fma_f32 v[216:217], v[6:7], v[128:129], v[216:217] op_sel:[0,1,0]
	v_pk_fma_f32 v[214:215], v[8:9], v[130:131], v[214:215] op_sel_hi:[1,0,1]
	v_pk_fma_f32 v[216:217], v[10:11], v[130:131], v[216:217] op_sel_hi:[1,0,1]
	v_pk_fma_f32 v[214:215], v[12:13], v[130:131], v[214:215] op_sel:[0,1,0]
	v_pk_fma_f32 v[216:217], v[14:15], v[130:131], v[216:217] op_sel:[0,1,0]
	v_pk_fma_f32 v[214:215], v[20:21], v[132:133], v[214:215] op_sel_hi:[1,0,1]
	v_pk_fma_f32 v[216:217], v[22:23], v[132:133], v[216:217] op_sel_hi:[1,0,1]
	v_pk_fma_f32 v[214:215], v[24:25], v[132:133], v[214:215] op_sel:[0,1,0]
	v_pk_fma_f32 v[216:217], v[26:27], v[132:133], v[216:217] op_sel:[0,1,0]
	v_pk_fma_f32 v[214:215], v[28:29], v[134:135], v[214:215] op_sel_hi:[1,0,1]
	v_pk_fma_f32 v[216:217], v[30:31], v[134:135], v[216:217] op_sel_hi:[1,0,1]
	v_pk_fma_f32 v[214:215], v[32:33], v[134:135], v[214:215] op_sel:[0,1,0]
	v_pk_fma_f32 v[216:217], v[34:35], v[134:135], v[216:217] op_sel:[0,1,0]
	global_store_dwordx4 v243, v[214:217], s[14:15] nt
	v_add_u32_e32 v243, 0x20000, v243
	global_load_dwordx4 v[214:217], v243, s[12:13] nt
	ds_read_b128 v[128:131], v118 offset:2592
	ds_read_b128 v[132:135], v118 offset:2608
	ds_read_b32 v136, v16 offset:160
	s_waitcnt vmcnt(25) lgkmcnt(3)
	v_pk_fma_f32 v[64:65], v[218:219], v[120:121], v[64:65] op_sel_hi:[1,0,1]
	v_pk_fma_f32 v[66:67], v[220:221], v[120:121], v[66:67] op_sel_hi:[1,0,1]
	v_pk_fma_f32 v[60:61], v[218:219], v[120:121], v[60:61] op_sel:[0,1,0]
	v_pk_fma_f32 v[62:63], v[220:221], v[120:121], v[62:63] op_sel:[0,1,0]
	v_pk_fma_f32 v[56:57], v[218:219], v[122:123], v[56:57] op_sel_hi:[1,0,1]
	v_pk_fma_f32 v[58:59], v[220:221], v[122:123], v[58:59] op_sel_hi:[1,0,1]
	v_pk_fma_f32 v[52:53], v[218:219], v[122:123], v[52:53] op_sel:[0,1,0]
	v_pk_fma_f32 v[54:55], v[220:221], v[122:123], v[54:55] op_sel:[0,1,0]
	v_pk_fma_f32 v[48:49], v[218:219], v[124:125], v[48:49] op_sel_hi:[1,0,1]
	v_pk_fma_f32 v[50:51], v[220:221], v[124:125], v[50:51] op_sel_hi:[1,0,1]
	v_pk_fma_f32 v[40:41], v[218:219], v[124:125], v[40:41] op_sel:[0,1,0]
	v_pk_fma_f32 v[42:43], v[220:221], v[124:125], v[42:43] op_sel:[0,1,0]
	v_pk_fma_f32 v[36:37], v[218:219], v[126:127], v[36:37] op_sel_hi:[1,0,1]
	v_pk_fma_f32 v[38:39], v[220:221], v[126:127], v[38:39] op_sel_hi:[1,0,1]
	v_pk_fma_f32 v[44:45], v[218:219], v[126:127], v[44:45] op_sel:[0,1,0]
	v_pk_fma_f32 v[46:47], v[220:221], v[126:127], v[46:47] op_sel:[0,1,0]
	ds_read_b128 v[120:123], v118 offset:2816
	ds_read_b128 v[124:127], v118 offset:2832
	s_waitcnt lgkmcnt(2)
	v_pk_mul_f32 v[218:219], v[218:219], v[136:137] op_sel_hi:[1,0]
	v_pk_mul_f32 v[220:221], v[220:221], v[136:137] op_sel_hi:[1,0]
	v_pk_fma_f32 v[218:219], v[0:1], v[128:129], v[218:219] op_sel_hi:[1,0,1]
	v_pk_fma_f32 v[220:221], v[2:3], v[128:129], v[220:221] op_sel_hi:[1,0,1]
	v_pk_fma_f32 v[218:219], v[4:5], v[128:129], v[218:219] op_sel:[0,1,0]
	v_pk_fma_f32 v[220:221], v[6:7], v[128:129], v[220:221] op_sel:[0,1,0]
	v_pk_fma_f32 v[218:219], v[8:9], v[130:131], v[218:219] op_sel_hi:[1,0,1]
	v_pk_fma_f32 v[220:221], v[10:11], v[130:131], v[220:221] op_sel_hi:[1,0,1]
	v_pk_fma_f32 v[218:219], v[12:13], v[130:131], v[218:219] op_sel:[0,1,0]
	v_pk_fma_f32 v[220:221], v[14:15], v[130:131], v[220:221] op_sel:[0,1,0]
	v_pk_fma_f32 v[218:219], v[20:21], v[132:133], v[218:219] op_sel_hi:[1,0,1]
	v_pk_fma_f32 v[220:221], v[22:23], v[132:133], v[220:221] op_sel_hi:[1,0,1]
	v_pk_fma_f32 v[218:219], v[24:25], v[132:133], v[218:219] op_sel:[0,1,0]
	v_pk_fma_f32 v[220:221], v[26:27], v[132:133], v[220:221] op_sel:[0,1,0]
	v_pk_fma_f32 v[218:219], v[28:29], v[134:135], v[218:219] op_sel_hi:[1,0,1]
	v_pk_fma_f32 v[220:221], v[30:31], v[134:135], v[220:221] op_sel_hi:[1,0,1]
	v_pk_fma_f32 v[218:219], v[32:33], v[134:135], v[218:219] op_sel:[0,1,0]
	v_pk_fma_f32 v[220:221], v[34:35], v[134:135], v[220:221] op_sel:[0,1,0]
	global_store_dwordx4 v244, v[218:221], s[14:15] nt
	v_add_u32_e32 v244, 0x20000, v244
	global_load_dwordx4 v[218:221], v244, s[12:13] nt
	ds_read_b128 v[128:131], v118 offset:2848
	ds_read_b128 v[132:135], v118 offset:2864
	ds_read_b32 v136, v16 offset:176
	s_waitcnt vmcnt(26) lgkmcnt(3)
	v_pk_fma_f32 v[64:65], v[222:223], v[120:121], v[64:65] op_sel_hi:[1,0,1]
	v_pk_fma_f32 v[66:67], v[224:225], v[120:121], v[66:67] op_sel_hi:[1,0,1]
	v_pk_fma_f32 v[60:61], v[222:223], v[120:121], v[60:61] op_sel:[0,1,0]
	v_pk_fma_f32 v[62:63], v[224:225], v[120:121], v[62:63] op_sel:[0,1,0]
	v_pk_fma_f32 v[56:57], v[222:223], v[122:123], v[56:57] op_sel_hi:[1,0,1]
	v_pk_fma_f32 v[58:59], v[224:225], v[122:123], v[58:59] op_sel_hi:[1,0,1]
	v_pk_fma_f32 v[52:53], v[222:223], v[122:123], v[52:53] op_sel:[0,1,0]
	v_pk_fma_f32 v[54:55], v[224:225], v[122:123], v[54:55] op_sel:[0,1,0]
	v_pk_fma_f32 v[48:49], v[222:223], v[124:125], v[48:49] op_sel_hi:[1,0,1]
	v_pk_fma_f32 v[50:51], v[224:225], v[124:125], v[50:51] op_sel_hi:[1,0,1]
	v_pk_fma_f32 v[40:41], v[222:223], v[124:125], v[40:41] op_sel:[0,1,0]
	v_pk_fma_f32 v[42:43], v[224:225], v[124:125], v[42:43] op_sel:[0,1,0]
	v_pk_fma_f32 v[36:37], v[222:223], v[126:127], v[36:37] op_sel_hi:[1,0,1]
	v_pk_fma_f32 v[38:39], v[224:225], v[126:127], v[38:39] op_sel_hi:[1,0,1]
	v_pk_fma_f32 v[44:45], v[222:223], v[126:127], v[44:45] op_sel:[0,1,0]
	v_pk_fma_f32 v[46:47], v[224:225], v[126:127], v[46:47] op_sel:[0,1,0]
	ds_read_b128 v[120:123], v118 offset:3072
	ds_read_b128 v[124:127], v118 offset:3088
	s_waitcnt lgkmcnt(2)
; #define LAS __attribute__((address_space(3)))
; template <int TY> __device__ __forceinline__ void sample_item(const Params& p, ldsp lds, int item) {
;     ...
; #pragma unroll 8
;     for (int d = dg; d < DK; d += NG) { const f32x4 s0 = __builtin_nontemporal_load((const f32x4*)(S0 + (size_t)d * DV + e4 * 4));
;         const f32x4 qa = *(const LAS f32x4*)(QK + d * 16), qb = *(const LAS f32x4*)(QK + d * 16 + 4), ka = *(const LAS f32x4*)(QK + d * 16 + 8), kb = *(const LAS f32x4*)(QK + d * 16 + 12);
;         const float dc = DECs[d];
;         o[0] += s0 * qa[0]; o[1] += s0 * qa[1]; o[2] += s0 * qa[2]; o[3] += s0 * qa[3]; o[4] += s0 * qb[0]; o[5] += s0 * qb[1]; o[6] += s0 * qb[2]; o[7] += s0 * qb[3];
;         f32x4 sn = s0 * dc; sn += v[0] * ka[0]; sn += v[1] * ka[1]; sn += v[2] * ka[2]; sn += v[3] * ka[3]; sn += v[4] * kb[0]; sn += v[5] * kb[1]; sn += v[6] * kb[2]; sn += v[7] * kb[3];
;         __builtin_nontemporal_store(sn, (f32x4*)(S1 + (size_t)d * DV + e4 * 4)); }
	v_pk_mul_f32 v[222:223], v[222:223], v[136:137] op_sel_hi:[1,0]
	v_pk_mul_f32 v[224:225], v[224:225], v[136:137] op_sel_hi:[1,0]
	v_pk_fma_f32 v[222:223], v[0:1], v[128:129], v[222:223] op_sel_hi:[1,0,1]
	v_pk_fma_f32 v[224:225], v[2:3], v[128:129], v[224:225] op_sel_hi:[1,0,1]
	v_pk_fma_f32 v[222:223], v[4:5], v[128:129], v[222:223] op_sel:[0,1,0]
	v_pk_fma_f32 v[224:225], v[6:7], v[128:129], v[224:225] op_sel:[0,1,0]
	v_pk_fma_f32 v[222:223], v[8:9], v[130:131], v[222:223] op_sel_hi:[1,0,1]
	v_pk_fma_f32 v[224:225], v[10:11], v[130:131], v[224:225] op_sel_hi:[1,0,1]
	v_pk_fma_f32 v[222:223], v[12:13], v[130:131], v[222:223] op_sel:[0,1,0]
	v_pk_fma_f32 v[224:225], v[14:15], v[130:131], v[224:225] op_sel:[0,1,0]
	v_pk_fma_f32 v[222:223], v[20:21], v[132:133], v[222:223] op_sel_hi:[1,0,1]
	v_pk_fma_f32 v[224:225], v[22:23], v[132:133], v[224:225] op_sel_hi:[1,0,1]
	v_pk_fma_f32 v[222:223], v[24:25], v[132:133], v[222:223] op_sel:[0,1,0]
	v_pk_fma_f32 v[224:225], v[26:27], v[132:133], v[224:225] op_sel:[0,1,0]
	v_pk_fma_f32 v[222:223], v[28:29], v[134:135], v[222:223] op_sel_hi:[1,0,1]
	v_pk_fma_f32 v[224:225], v[30:31], v[134:135], v[224:225] op_sel_hi:[1,0,1]
	v_pk_fma_f32 v[222:223], v[32:33], v[134:135], v[222:223] op_sel:[0,1,0]
	v_pk_fma_f32 v[224:225], v[34:35], v[134:135], v[224:225] op_sel:[0,1,0]
	global_store_dwordx4 v245, v[222:225], s[14:15] nt
	v_add_u32_e32 v245, 0x20000, v245
	global_load_dwordx4 v[222:225], v245, s[12:13] nt
	ds_read_b128 v[128:131], v118 offset:3104
	ds_read_b128 v[132:135], v118 offset:3120
	ds_read_b32 v136, v16 offset:192
	s_waitcnt vmcnt(27) lgkmcnt(3)
	v_pk_fma_f32 v[64:65], v[226:227], v[120:121], v[64:65] op_sel_hi:[1,0,1]
	v_pk_fma_f32 v[66:67], v[228:229], v[120:121], v[66:67] op_sel_hi:[1,0,1]
	v_pk_fma_f32 v[60:61], v[226:227], v[120:121], v[60:61] op_sel:[0,1,0]
	v_pk_fma_f32 v[62:63], v[228:229], v[120:121], v[62:63] op_sel:[0,1,0]
	v_pk_fma_f32 v[56:57], v[226:227], v[122:123], v[56:57] op_sel_hi:[1,0,1]
	v_pk_fma_f32 v[58:59], v[228:229], v[122:123], v[58:59] op_sel_hi:[1,0,1]
	v_pk_fma_f32 v[52:53], v[226:227], v[122:123], v[52:53] op_sel:[0,1,0]
	v_pk_fma_f32 v[54:55], v[228:229], v[122:123], v[54:55] op_sel:[0,1,0]
	v_pk_fma_f32 v[48:49], v[226:227], v[124:125], v[48:49] op_sel_hi:[1,0,1]
	v_pk_fma_f32 v[50:51], v[228:229], v[124:125], v[50:51] op_sel_hi:[1,0,1]
	v_pk_fma_f32 v[40:41], v[226:227], v[124:125], v[40:41] op_sel:[0,1,0]
	v_pk_fma_f32 v[42:43], v[228:229], v[124:125], v[42:43] op_sel:[0,1,0]
	v_pk_fma_f32 v[36:37], v[226:227], v[126:127], v[36:37] op_sel_hi:[1,0,1]
	v_pk_fma_f32 v[38:39], v[228:229], v[126:127], v[38:39] op_sel_hi:[1,0,1]
	v_pk_fma_f32 v[44:45], v[226:227], v[126:127], v[44:45] op_sel:[0,1,0]
	v_pk_fma_f32 v[46:47], v[228:229], v[126:127], v[46:47] op_sel:[0,1,0]
	ds_read_b128 v[120:123], v118 offset:3328
	ds_read_b128 v[124:127], v118 offset:3344
	s_waitcnt lgkmcnt(2)
	v_pk_mul_f32 v[226:227], v[226:227], v[136:137] op_sel_hi:[1,0]
	v_pk_mul_f32 v[228:229], v[228:229], v[136:137] op_sel_hi:[1,0]
	v_pk_fma_f32 v[226:227], v[0:1], v[128:129], v[226:227] op_sel_hi:[1,0,1]
	v_pk_fma_f32 v[228:229], v[2:3], v[128:129], v[228:229] op_sel_hi:[1,0,1]
	v_pk_fma_f32 v[226:227], v[4:5], v[128:129], v[226:227] op_sel:[0,1,0]
	v_pk_fma_f32 v[228:229], v[6:7], v[128:129], v[228:229] op_sel:[0,1,0]
	v_pk_fma_f32 v[226:227], v[8:9], v[130:131], v[226:227] op_sel_hi:[1,0,1]
	v_pk_fma_f32 v[228:229], v[10:11], v[130:131], v[228:229] op_sel_hi:[1,0,1]
	v_pk_fma_f32 v[226:227], v[12:13], v[130:131], v[226:227] op_sel:[0,1,0]
	v_pk_fma_f32 v[228:229], v[14:15], v[130:131], v[228:229] op_sel:[0,1,0]
	v_pk_fma_f32 v[226:227], v[20:21], v[132:133], v[226:227] op_sel_hi:[1,0,1]
	v_pk_fma_f32 v[228:229], v[22:23], v[132:133], v[228:229] op_sel_hi:[1,0,1]
	v_pk_fma_f32 v[226:227], v[24:25], v[132:133], v[226:227] op_sel:[0,1,0]
	v_pk_fma_f32 v[228:229], v[26:27], v[132:133], v[228:229] op_sel:[0,1,0]
	v_pk_fma_f32 v[226:227], v[28:29], v[134:135], v[226:227] op_sel_hi:[1,0,1]
	v_pk_fma_f32 v[228:229], v[30:31], v[134:135], v[228:229] op_sel_hi:[1,0,1]
	v_pk_fma_f32 v[226:227], v[32:33], v[134:135], v[226:227] op_sel:[0,1,0]
	v_pk_fma_f32 v[228:229], v[34:35], v[134:135], v[228:229] op_sel:[0,1,0]
	global_store_dwordx4 v246, v[226:229], s[14:15] nt
	v_add_u32_e32 v246, 0x20000, v246
	global_load_dwordx4 v[226:229], v246, s[12:13] nt
	ds_read_b128 v[128:131], v118 offset:3360
	ds_read_b128 v[132:135], v118 offset:3376
	ds_read_b32 v136, v16 offset:208
	s_waitcnt vmcnt(28) lgkmcnt(3)
	v_pk_fma_f32 v[64:65], v[230:231], v[120:121], v[64:65] op_sel_hi:[1,0,1]
	v_pk_fma_f32 v[66:67], v[232:233], v[120:121], v[66:67] op_sel_hi:[1,0,1]
	v_pk_fma_f32 v[60:61], v[230:231], v[120:121], v[60:61] op_sel:[0,1,0]
	v_pk_fma_f32 v[62:63], v[232:233], v[120:121], v[62:63] op_sel:[0,1,0]
	v_pk_fma_f32 v[56:57], v[230:231], v[122:123], v[56:57] op_sel_hi:[1,0,1]
	v_pk_fma_f32 v[58:59], v[232:233], v[122:123], v[58:59] op_sel_hi:[1,0,1]
	v_pk_fma_f32 v[52:53], v[230:231], v[122:123], v[52:53] op_sel:[0,1,0]
	v_pk_fma_f32 v[54:55], v[232:233], v[122:123], v[54:55] op_sel:[0,1,0]
	v_pk_fma_f32 v[48:49], v[230:231], v[124:125], v[48:49] op_sel_hi:[1,0,1]
	v_pk_fma_f32 v[50:51], v[232:233], v[124:125], v[50:51] op_sel_hi:[1,0,1]
	v_pk_fma_f32 v[40:41], v[230:231], v[124:125], v[40:41] op_sel:[0,1,0]
	v_pk_fma_f32 v[42:43], v[232:233], v[124:125], v[42:43] op_sel:[0,1,0]
	v_pk_fma_f32 v[36:37], v[230:231], v[126:127], v[36:37] op_sel_hi:[1,0,1]
	v_pk_fma_f32 v[38:39], v[232:233], v[126:127], v[38:39] op_sel_hi:[1,0,1]
	v_pk_fma_f32 v[44:45], v[230:231], v[126:127], v[44:45] op_sel:[0,1,0]
	v_pk_fma_f32 v[46:47], v[232:233], v[126:127], v[46:47] op_sel:[0,1,0]
	ds_read_b128 v[120:123], v118 offset:3584
	ds_read_b128 v[124:127], v118 offset:3600
	s_waitcnt lgkmcnt(2)
; #define LAS __attribute__((address_space(3)))
; template <int TY> __device__ __forceinline__ void sample_item(const Params& p, ldsp lds, int item) {
;     ...
; #pragma unroll 8
;     for (int d = dg; d < DK; d += NG) { const f32x4 s0 = __builtin_nontemporal_load((const f32x4*)(S0 + (size_t)d * DV + e4 * 4));
;         const f32x4 qa = *(const LAS f32x4*)(QK + d * 16), qb = *(const LAS f32x4*)(QK + d * 16 + 4), ka = *(const LAS f32x4*)(QK + d * 16 + 8), kb = *(const LAS f32x4*)(QK + d * 16 + 12);
;         const float dc = DECs[d];
;         o[0] += s0 * qa[0]; o[1] += s0 * qa[1]; o[2] += s0 * qa[2]; o[3] += s0 * qa[3]; o[4] += s0 * qb[0]; o[5] += s0 * qb[1]; o[6] += s0 * qb[2]; o[7] += s0 * qb[3];
;         f32x4 sn = s0 * dc; sn += v[0] * ka[0]; sn += v[1] * ka[1]; sn += v[2] * ka[2]; sn += v[3] * ka[3]; sn += v[4] * kb[0]; sn += v[5] * kb[1]; sn += v[6] * kb[2]; sn += v[7] * kb[3];
;         __builtin_nontemporal_store(sn, (f32x4*)(S1 + (size_t)d * DV + e4 * 4)); }
	v_pk_mul_f32 v[230:231], v[230:231], v[136:137] op_sel_hi:[1,0]
	v_pk_mul_f32 v[232:233], v[232:233], v[136:137] op_sel_hi:[1,0]
	v_pk_fma_f32 v[230:231], v[0:1], v[128:129], v[230:231] op_sel_hi:[1,0,1]
	v_pk_fma_f32 v[232:233], v[2:3], v[128:129], v[232:233] op_sel_hi:[1,0,1]
	v_pk_fma_f32 v[230:231], v[4:5], v[128:129], v[230:231] op_sel:[0,1,0]
	v_pk_fma_f32 v[232:233], v[6:7], v[128:129], v[232:233] op_sel:[0,1,0]
	v_pk_fma_f32 v[230:231], v[8:9], v[130:131], v[230:231] op_sel_hi:[1,0,1]
	v_pk_fma_f32 v[232:233], v[10:11], v[130:131], v[232:233] op_sel_hi:[1,0,1]
	v_pk_fma_f32 v[230:231], v[12:13], v[130:131], v[230:231] op_sel:[0,1,0]
	v_pk_fma_f32 v[232:233], v[14:15], v[130:131], v[232:233] op_sel:[0,1,0]
	v_pk_fma_f32 v[230:231], v[20:21], v[132:133], v[230:231] op_sel_hi:[1,0,1]
	v_pk_fma_f32 v[232:233], v[22:23], v[132:133], v[232:233] op_sel_hi:[1,0,1]
	v_pk_fma_f32 v[230:231], v[24:25], v[132:133], v[230:231] op_sel:[0,1,0]
	v_pk_fma_f32 v[232:233], v[26:27], v[132:133], v[232:233] op_sel:[0,1,0]
	v_pk_fma_f32 v[230:231], v[28:29], v[134:135], v[230:231] op_sel_hi:[1,0,1]
	v_pk_fma_f32 v[232:233], v[30:31], v[134:135], v[232:233] op_sel_hi:[1,0,1]
	v_pk_fma_f32 v[230:231], v[32:33], v[134:135], v[230:231] op_sel:[0,1,0]
	v_pk_fma_f32 v[232:233], v[34:35], v[134:135], v[232:233] op_sel:[0,1,0]
	global_store_dwordx4 v247, v[230:233], s[14:15] nt
	v_add_u32_e32 v247, 0x20000, v247
	global_load_dwordx4 v[230:233], v247, s[12:13] nt
	ds_read_b128 v[128:131], v118 offset:3616
	ds_read_b128 v[132:135], v118 offset:3632
	ds_read_b32 v136, v16 offset:224
	s_waitcnt vmcnt(29) lgkmcnt(3)
	v_pk_fma_f32 v[64:65], v[234:235], v[120:121], v[64:65] op_sel_hi:[1,0,1]
	v_pk_fma_f32 v[66:67], v[236:237], v[120:121], v[66:67] op_sel_hi:[1,0,1]
	v_pk_fma_f32 v[60:61], v[234:235], v[120:121], v[60:61] op_sel:[0,1,0]
	v_pk_fma_f32 v[62:63], v[236:237], v[120:121], v[62:63] op_sel:[0,1,0]
	v_pk_fma_f32 v[56:57], v[234:235], v[122:123], v[56:57] op_sel_hi:[1,0,1]
	v_pk_fma_f32 v[58:59], v[236:237], v[122:123], v[58:59] op_sel_hi:[1,0,1]
	v_pk_fma_f32 v[52:53], v[234:235], v[122:123], v[52:53] op_sel:[0,1,0]
	v_pk_fma_f32 v[54:55], v[236:237], v[122:123], v[54:55] op_sel:[0,1,0]
	v_pk_fma_f32 v[48:49], v[234:235], v[124:125], v[48:49] op_sel_hi:[1,0,1]
	v_pk_fma_f32 v[50:51], v[236:237], v[124:125], v[50:51] op_sel_hi:[1,0,1]
	v_pk_fma_f32 v[40:41], v[234:235], v[124:125], v[40:41] op_sel:[0,1,0]
	v_pk_fma_f32 v[42:43], v[236:237], v[124:125], v[42:43] op_sel:[0,1,0]
	v_pk_fma_f32 v[36:37], v[234:235], v[126:127], v[36:37] op_sel_hi:[1,0,1]
	v_pk_fma_f32 v[38:39], v[236:237], v[126:127], v[38:39] op_sel_hi:[1,0,1]
	v_pk_fma_f32 v[44:45], v[234:235], v[126:127], v[44:45] op_sel:[0,1,0]
	v_pk_fma_f32 v[46:47], v[236:237], v[126:127], v[46:47] op_sel:[0,1,0]
	ds_read_b128 v[120:123], v118 offset:3840
	ds_read_b128 v[124:127], v118 offset:3856
	s_waitcnt lgkmcnt(2)
	v_pk_mul_f32 v[234:235], v[234:235], v[136:137] op_sel_hi:[1,0]
	v_pk_mul_f32 v[236:237], v[236:237], v[136:137] op_sel_hi:[1,0]
	v_pk_fma_f32 v[234:235], v[0:1], v[128:129], v[234:235] op_sel_hi:[1,0,1]
	v_pk_fma_f32 v[236:237], v[2:3], v[128:129], v[236:237] op_sel_hi:[1,0,1]
	v_pk_fma_f32 v[234:235], v[4:5], v[128:129], v[234:235] op_sel:[0,1,0]
	v_pk_fma_f32 v[236:237], v[6:7], v[128:129], v[236:237] op_sel:[0,1,0]
	v_pk_fma_f32 v[234:235], v[8:9], v[130:131], v[234:235] op_sel_hi:[1,0,1]
	v_pk_fma_f32 v[236:237], v[10:11], v[130:131], v[236:237] op_sel_hi:[1,0,1]
	v_pk_fma_f32 v[234:235], v[12:13], v[130:131], v[234:235] op_sel:[0,1,0]
	v_pk_fma_f32 v[236:237], v[14:15], v[130:131], v[236:237] op_sel:[0,1,0]
	v_pk_fma_f32 v[234:235], v[20:21], v[132:133], v[234:235] op_sel_hi:[1,0,1]
	v_pk_fma_f32 v[236:237], v[22:23], v[132:133], v[236:237] op_sel_hi:[1,0,1]
	v_pk_fma_f32 v[234:235], v[24:25], v[132:133], v[234:235] op_sel:[0,1,0]
	v_pk_fma_f32 v[236:237], v[26:27], v[132:133], v[236:237] op_sel:[0,1,0]
	v_pk_fma_f32 v[234:235], v[28:29], v[134:135], v[234:235] op_sel_hi:[1,0,1]
	v_pk_fma_f32 v[236:237], v[30:31], v[134:135], v[236:237] op_sel_hi:[1,0,1]
	v_pk_fma_f32 v[234:235], v[32:33], v[134:135], v[234:235] op_sel:[0,1,0]
	v_pk_fma_f32 v[236:237], v[34:35], v[134:135], v[236:237] op_sel:[0,1,0]
	global_store_dwordx4 v248, v[234:237], s[14:15] nt
	v_add_u32_e32 v248, 0x20000, v248
	global_load_dwordx4 v[234:237], v248, s[12:13] nt
	ds_read_b128 v[128:131], v118 offset:3872
	ds_read_b128 v[132:135], v118 offset:3888
	ds_read_b32 v136, v16 offset:240
	s_waitcnt vmcnt(30) lgkmcnt(3)
	v_pk_fma_f32 v[64:65], v[238:239], v[120:121], v[64:65] op_sel_hi:[1,0,1]
	v_pk_fma_f32 v[66:67], v[240:241], v[120:121], v[66:67] op_sel_hi:[1,0,1]
	v_pk_fma_f32 v[60:61], v[238:239], v[120:121], v[60:61] op_sel:[0,1,0]
	v_pk_fma_f32 v[62:63], v[240:241], v[120:121], v[62:63] op_sel:[0,1,0]
	v_pk_fma_f32 v[56:57], v[238:239], v[122:123], v[56:57] op_sel_hi:[1,0,1]
	v_pk_fma_f32 v[58:59], v[240:241], v[122:123], v[58:59] op_sel_hi:[1,0,1]
	v_pk_fma_f32 v[52:53], v[238:239], v[122:123], v[52:53] op_sel:[0,1,0]
	v_pk_fma_f32 v[54:55], v[240:241], v[122:123], v[54:55] op_sel:[0,1,0]
	v_pk_fma_f32 v[48:49], v[238:239], v[124:125], v[48:49] op_sel_hi:[1,0,1]
	v_pk_fma_f32 v[50:51], v[240:241], v[124:125], v[50:51] op_sel_hi:[1,0,1]
	v_pk_fma_f32 v[40:41], v[238:239], v[124:125], v[40:41] op_sel:[0,1,0]
	v_pk_fma_f32 v[42:43], v[240:241], v[124:125], v[42:43] op_sel:[0,1,0]
	v_pk_fma_f32 v[36:37], v[238:239], v[126:127], v[36:37] op_sel_hi:[1,0,1]
	v_pk_fma_f32 v[38:39], v[240:241], v[126:127], v[38:39] op_sel_hi:[1,0,1]
	v_pk_fma_f32 v[44:45], v[238:239], v[126:127], v[44:45] op_sel:[0,1,0]
	v_pk_fma_f32 v[46:47], v[240:241], v[126:127], v[46:47] op_sel:[0,1,0]
	ds_read_b128 v[120:123], v118 offset:4096
	ds_read_b128 v[124:127], v118 offset:4112
	s_waitcnt lgkmcnt(2)
; #define LAS __attribute__((address_space(3)))
; template <int TY> __device__ __forceinline__ void sample_item(const Params& p, ldsp lds, int item) {
;     ...
; #pragma unroll 8
;     for (int d = dg; d < DK; d += NG) { const f32x4 s0 = __builtin_nontemporal_load((const f32x4*)(S0 + (size_t)d * DV + e4 * 4));
;         const f32x4 qa = *(const LAS f32x4*)(QK + d * 16), qb = *(const LAS f32x4*)(QK + d * 16 + 4), ka = *(const LAS f32x4*)(QK + d * 16 + 8), kb = *(const LAS f32x4*)(QK + d * 16 + 12);
;         const float dc = DECs[d];
;         o[0] += s0 * qa[0]; o[1] += s0 * qa[1]; o[2] += s0 * qa[2]; o[3] += s0 * qa[3]; o[4] += s0 * qb[0]; o[5] += s0 * qb[1]; o[6] += s0 * qb[2]; o[7] += s0 * qb[3];
;         f32x4 sn = s0 * dc; sn += v[0] * ka[0]; sn += v[1] * ka[1]; sn += v[2] * ka[2]; sn += v[3] * ka[3]; sn += v[4] * kb[0]; sn += v[5] * kb[1]; sn += v[6] * kb[2]; sn += v[7] * kb[3];
;         __builtin_nontemporal_store(sn, (f32x4*)(S1 + (size_t)d * DV + e4 * 4)); }
	v_pk_mul_f32 v[238:239], v[238:239], v[136:137] op_sel_hi:[1,0]
	v_pk_mul_f32 v[240:241], v[240:241], v[136:137] op_sel_hi:[1,0]
	v_pk_fma_f32 v[238:239], v[0:1], v[128:129], v[238:239] op_sel_hi:[1,0,1]
	v_pk_fma_f32 v[240:241], v[2:3], v[128:129], v[240:241] op_sel_hi:[1,0,1]
	v_pk_fma_f32 v[238:239], v[4:5], v[128:129], v[238:239] op_sel:[0,1,0]
	v_pk_fma_f32 v[240:241], v[6:7], v[128:129], v[240:241] op_sel:[0,1,0]
	v_pk_fma_f32 v[238:239], v[8:9], v[130:131], v[238:239] op_sel_hi:[1,0,1]
	v_pk_fma_f32 v[240:241], v[10:11], v[130:131], v[240:241] op_sel_hi:[1,0,1]
	v_pk_fma_f32 v[238:239], v[12:13], v[130:131], v[238:239] op_sel:[0,1,0]
	v_pk_fma_f32 v[240:241], v[14:15], v[130:131], v[240:241] op_sel:[0,1,0]
	v_pk_fma_f32 v[238:239], v[20:21], v[132:133], v[238:239] op_sel_hi:[1,0,1]
	v_pk_fma_f32 v[240:241], v[22:23], v[132:133], v[240:241] op_sel_hi:[1,0,1]
	v_pk_fma_f32 v[238:239], v[24:25], v[132:133], v[238:239] op_sel:[0,1,0]
	v_pk_fma_f32 v[240:241], v[26:27], v[132:133], v[240:241] op_sel:[0,1,0]
	v_pk_fma_f32 v[238:239], v[28:29], v[134:135], v[238:239] op_sel_hi:[1,0,1]
	v_pk_fma_f32 v[240:241], v[30:31], v[134:135], v[240:241] op_sel_hi:[1,0,1]
	v_pk_fma_f32 v[238:239], v[32:33], v[134:135], v[238:239] op_sel:[0,1,0]
	v_pk_fma_f32 v[240:241], v[34:35], v[134:135], v[240:241] op_sel:[0,1,0]
	global_store_dwordx4 v249, v[238:241], s[14:15] nt
	v_add_u32_e32 v249, 0x20000, v249
	global_load_dwordx4 v[238:241], v249, s[12:13] nt
	v_add_u32_e32 v118, 0x1000, v118
	v_add_u32_e32 v16, 0x100, v16
	s_mov_b32 s16, 0
.Lsm2_stream_loop:
	ds_read_b128 v[128:131], v118 offset:32
	ds_read_b128 v[132:135], v118 offset:48
	ds_read_b32 v136, v16 offset:0
	s_waitcnt vmcnt(30) lgkmcnt(3)
	v_pk_fma_f32 v[64:65], v[72:73], v[120:121], v[64:65] op_sel_hi:[1,0,1]
	v_pk_fma_f32 v[66:67], v[74:75], v[120:121], v[66:67] op_sel_hi:[1,0,1]
	v_pk_fma_f32 v[60:61], v[72:73], v[120:121], v[60:61] op_sel:[0,1,0]
	v_pk_fma_f32 v[62:63], v[74:75], v[120:121], v[62:63] op_sel:[0,1,0]
	v_pk_fma_f32 v[56:57], v[72:73], v[122:123], v[56:57] op_sel_hi:[1,0,1]
	v_pk_fma_f32 v[58:59], v[74:75], v[122:123], v[58:59] op_sel_hi:[1,0,1]
	v_pk_fma_f32 v[52:53], v[72:73], v[122:123], v[52:53] op_sel:[0,1,0]
	v_pk_fma_f32 v[54:55], v[74:75], v[122:123], v[54:55] op_sel:[0,1,0]
	v_pk_fma_f32 v[48:49], v[72:73], v[124:125], v[48:49] op_sel_hi:[1,0,1]
	v_pk_fma_f32 v[50:51], v[74:75], v[124:125], v[50:51] op_sel_hi:[1,0,1]
	v_pk_fma_f32 v[40:41], v[72:73], v[124:125], v[40:41] op_sel:[0,1,0]
	v_pk_fma_f32 v[42:43], v[74:75], v[124:125], v[42:43] op_sel:[0,1,0]
	v_pk_fma_f32 v[36:37], v[72:73], v[126:127], v[36:37] op_sel_hi:[1,0,1]
	v_pk_fma_f32 v[38:39], v[74:75], v[126:127], v[38:39] op_sel_hi:[1,0,1]
	v_pk_fma_f32 v[44:45], v[72:73], v[126:127], v[44:45] op_sel:[0,1,0]
	v_pk_fma_f32 v[46:47], v[74:75], v[126:127], v[46:47] op_sel:[0,1,0]
	ds_read_b128 v[120:123], v118 offset:256
	ds_read_b128 v[124:127], v118 offset:272
	s_waitcnt lgkmcnt(2)
	v_pk_mul_f32 v[72:73], v[72:73], v[136:137] op_sel_hi:[1,0]
	v_pk_mul_f32 v[74:75], v[74:75], v[136:137] op_sel_hi:[1,0]
	v_pk_fma_f32 v[72:73], v[0:1], v[128:129], v[72:73] op_sel_hi:[1,0,1]
	v_pk_fma_f32 v[74:75], v[2:3], v[128:129], v[74:75] op_sel_hi:[1,0,1]
	v_pk_fma_f32 v[72:73], v[4:5], v[128:129], v[72:73] op_sel:[0,1,0]
	v_pk_fma_f32 v[74:75], v[6:7], v[128:129], v[74:75] op_sel:[0,1,0]
	v_pk_fma_f32 v[72:73], v[8:9], v[130:131], v[72:73] op_sel_hi:[1,0,1]
	v_pk_fma_f32 v[74:75], v[10:11], v[130:131], v[74:75] op_sel_hi:[1,0,1]
	v_pk_fma_f32 v[72:73], v[12:13], v[130:131], v[72:73] op_sel:[0,1,0]
	v_pk_fma_f32 v[74:75], v[14:15], v[130:131], v[74:75] op_sel:[0,1,0]
	v_pk_fma_f32 v[72:73], v[20:21], v[132:133], v[72:73] op_sel_hi:[1,0,1]
	v_pk_fma_f32 v[74:75], v[22:23], v[132:133], v[74:75] op_sel_hi:[1,0,1]
	v_pk_fma_f32 v[72:73], v[24:25], v[132:133], v[72:73] op_sel:[0,1,0]
	v_pk_fma_f32 v[74:75], v[26:27], v[132:133], v[74:75] op_sel:[0,1,0]
	v_pk_fma_f32 v[72:73], v[28:29], v[134:135], v[72:73] op_sel_hi:[1,0,1]
	v_pk_fma_f32 v[74:75], v[30:31], v[134:135], v[74:75] op_sel_hi:[1,0,1]
	v_pk_fma_f32 v[72:73], v[32:33], v[134:135], v[72:73] op_sel:[0,1,0]
	v_pk_fma_f32 v[74:75], v[34:35], v[134:135], v[74:75] op_sel:[0,1,0]
	global_store_dwordx4 v104, v[72:75], s[14:15] nt
	v_add_u32_e32 v104, 0x20000, v104
	global_load_dwordx4 v[72:75], v104, s[12:13] nt
	ds_read_b128 v[128:131], v118 offset:288
	ds_read_b128 v[132:135], v118 offset:304
	ds_read_b32 v136, v16 offset:16
	s_waitcnt vmcnt(30) lgkmcnt(3)
	v_pk_fma_f32 v[64:65], v[76:77], v[120:121], v[64:65] op_sel_hi:[1,0,1]
	v_pk_fma_f32 v[66:67], v[78:79], v[120:121], v[66:67] op_sel_hi:[1,0,1]
	v_pk_fma_f32 v[60:61], v[76:77], v[120:121], v[60:61] op_sel:[0,1,0]
	v_pk_fma_f32 v[62:63], v[78:79], v[120:121], v[62:63] op_sel:[0,1,0]
	v_pk_fma_f32 v[56:57], v[76:77], v[122:123], v[56:57] op_sel_hi:[1,0,1]
	v_pk_fma_f32 v[58:59], v[78:79], v[122:123], v[58:59] op_sel_hi:[1,0,1]
	v_pk_fma_f32 v[52:53], v[76:77], v[122:123], v[52:53] op_sel:[0,1,0]
	v_pk_fma_f32 v[54:55], v[78:79], v[122:123], v[54:55] op_sel:[0,1,0]
	v_pk_fma_f32 v[48:49], v[76:77], v[124:125], v[48:49] op_sel_hi:[1,0,1]
	v_pk_fma_f32 v[50:51], v[78:79], v[124:125], v[50:51] op_sel_hi:[1,0,1]
	v_pk_fma_f32 v[40:41], v[76:77], v[124:125], v[40:41] op_sel:[0,1,0]
	v_pk_fma_f32 v[42:43], v[78:79], v[124:125], v[42:43] op_sel:[0,1,0]
	v_pk_fma_f32 v[36:37], v[76:77], v[126:127], v[36:37] op_sel_hi:[1,0,1]
	v_pk_fma_f32 v[38:39], v[78:79], v[126:127], v[38:39] op_sel_hi:[1,0,1]
	v_pk_fma_f32 v[44:45], v[76:77], v[126:127], v[44:45] op_sel:[0,1,0]
	v_pk_fma_f32 v[46:47], v[78:79], v[126:127], v[46:47] op_sel:[0,1,0]
	ds_read_b128 v[120:123], v118 offset:512
	ds_read_b128 v[124:127], v118 offset:528
	s_waitcnt lgkmcnt(2)
; #define LAS __attribute__((address_space(3)))
; template <int TY> __device__ __forceinline__ void sample_item(const Params& p, ldsp lds, int item) {
;     ...
; #pragma unroll 8
;     for (int d = dg; d < DK; d += NG) { const f32x4 s0 = __builtin_nontemporal_load((const f32x4*)(S0 + (size_t)d * DV + e4 * 4));
;         const f32x4 qa = *(const LAS f32x4*)(QK + d * 16), qb = *(const LAS f32x4*)(QK + d * 16 + 4), ka = *(const LAS f32x4*)(QK + d * 16 + 8), kb = *(const LAS f32x4*)(QK + d * 16 + 12);
;         const float dc = DECs[d];
;         o[0] += s0 * qa[0]; o[1] += s0 * qa[1]; o[2] += s0 * qa[2]; o[3] += s0 * qa[3]; o[4] += s0 * qb[0]; o[5] += s0 * qb[1]; o[6] += s0 * qb[2]; o[7] += s0 * qb[3];
;         f32x4 sn = s0 * dc; sn += v[0] * ka[0]; sn += v[1] * ka[1]; sn += v[2] * ka[2]; sn += v[3] * ka[3]; sn += v[4] * kb[0]; sn += v[5] * kb[1]; sn += v[6] * kb[2]; sn += v[7] * kb[3];
;         __builtin_nontemporal_store(sn, (f32x4*)(S1 + (size_t)d * DV + e4 * 4)); }
	v_pk_mul_f32 v[76:77], v[76:77], v[136:137] op_sel_hi:[1,0]
	v_pk_mul_f32 v[78:79], v[78:79], v[136:137] op_sel_hi:[1,0]
	v_pk_fma_f32 v[76:77], v[0:1], v[128:129], v[76:77] op_sel_hi:[1,0,1]
	v_pk_fma_f32 v[78:79], v[2:3], v[128:129], v[78:79] op_sel_hi:[1,0,1]
	v_pk_fma_f32 v[76:77], v[4:5], v[128:129], v[76:77] op_sel:[0,1,0]
	v_pk_fma_f32 v[78:79], v[6:7], v[128:129], v[78:79] op_sel:[0,1,0]
	v_pk_fma_f32 v[76:77], v[8:9], v[130:131], v[76:77] op_sel_hi:[1,0,1]
	v_pk_fma_f32 v[78:79], v[10:11], v[130:131], v[78:79] op_sel_hi:[1,0,1]
	v_pk_fma_f32 v[76:77], v[12:13], v[130:131], v[76:77] op_sel:[0,1,0]
	v_pk_fma_f32 v[78:79], v[14:15], v[130:131], v[78:79] op_sel:[0,1,0]
	v_pk_fma_f32 v[76:77], v[20:21], v[132:133], v[76:77] op_sel_hi:[1,0,1]
	v_pk_fma_f32 v[78:79], v[22:23], v[132:133], v[78:79] op_sel_hi:[1,0,1]
	v_pk_fma_f32 v[76:77], v[24:25], v[132:133], v[76:77] op_sel:[0,1,0]
	v_pk_fma_f32 v[78:79], v[26:27], v[132:133], v[78:79] op_sel:[0,1,0]
	v_pk_fma_f32 v[76:77], v[28:29], v[134:135], v[76:77] op_sel_hi:[1,0,1]
	v_pk_fma_f32 v[78:79], v[30:31], v[134:135], v[78:79] op_sel_hi:[1,0,1]
	v_pk_fma_f32 v[76:77], v[32:33], v[134:135], v[76:77] op_sel:[0,1,0]
	v_pk_fma_f32 v[78:79], v[34:35], v[134:135], v[78:79] op_sel:[0,1,0]
	global_store_dwordx4 v105, v[76:79], s[14:15] nt
	v_add_u32_e32 v105, 0x20000, v105
	global_load_dwordx4 v[76:79], v105, s[12:13] nt
	ds_read_b128 v[128:131], v118 offset:544
	ds_read_b128 v[132:135], v118 offset:560
	ds_read_b32 v136, v16 offset:32
	s_waitcnt vmcnt(30) lgkmcnt(3)
	v_pk_fma_f32 v[64:65], v[80:81], v[120:121], v[64:65] op_sel_hi:[1,0,1]
	v_pk_fma_f32 v[66:67], v[82:83], v[120:121], v[66:67] op_sel_hi:[1,0,1]
	v_pk_fma_f32 v[60:61], v[80:81], v[120:121], v[60:61] op_sel:[0,1,0]
	v_pk_fma_f32 v[62:63], v[82:83], v[120:121], v[62:63] op_sel:[0,1,0]
	v_pk_fma_f32 v[56:57], v[80:81], v[122:123], v[56:57] op_sel_hi:[1,0,1]
	v_pk_fma_f32 v[58:59], v[82:83], v[122:123], v[58:59] op_sel_hi:[1,0,1]
	v_pk_fma_f32 v[52:53], v[80:81], v[122:123], v[52:53] op_sel:[0,1,0]
	v_pk_fma_f32 v[54:55], v[82:83], v[122:123], v[54:55] op_sel:[0,1,0]
	v_pk_fma_f32 v[48:49], v[80:81], v[124:125], v[48:49] op_sel_hi:[1,0,1]
	v_pk_fma_f32 v[50:51], v[82:83], v[124:125], v[50:51] op_sel_hi:[1,0,1]
	v_pk_fma_f32 v[40:41], v[80:81], v[124:125], v[40:41] op_sel:[0,1,0]
	v_pk_fma_f32 v[42:43], v[82:83], v[124:125], v[42:43] op_sel:[0,1,0]
	v_pk_fma_f32 v[36:37], v[80:81], v[126:127], v[36:37] op_sel_hi:[1,0,1]
	v_pk_fma_f32 v[38:39], v[82:83], v[126:127], v[38:39] op_sel_hi:[1,0,1]
	v_pk_fma_f32 v[44:45], v[80:81], v[126:127], v[44:45] op_sel:[0,1,0]
	v_pk_fma_f32 v[46:47], v[82:83], v[126:127], v[46:47] op_sel:[0,1,0]
	ds_read_b128 v[120:123], v118 offset:768
	ds_read_b128 v[124:127], v118 offset:784
	s_waitcnt lgkmcnt(2)
	v_pk_mul_f32 v[80:81], v[80:81], v[136:137] op_sel_hi:[1,0]
	v_pk_mul_f32 v[82:83], v[82:83], v[136:137] op_sel_hi:[1,0]
	v_pk_fma_f32 v[80:81], v[0:1], v[128:129], v[80:81] op_sel_hi:[1,0,1]
	v_pk_fma_f32 v[82:83], v[2:3], v[128:129], v[82:83] op_sel_hi:[1,0,1]
	v_pk_fma_f32 v[80:81], v[4:5], v[128:129], v[80:81] op_sel:[0,1,0]
	v_pk_fma_f32 v[82:83], v[6:7], v[128:129], v[82:83] op_sel:[0,1,0]
	v_pk_fma_f32 v[80:81], v[8:9], v[130:131], v[80:81] op_sel_hi:[1,0,1]
	v_pk_fma_f32 v[82:83], v[10:11], v[130:131], v[82:83] op_sel_hi:[1,0,1]
	v_pk_fma_f32 v[80:81], v[12:13], v[130:131], v[80:81] op_sel:[0,1,0]
	v_pk_fma_f32 v[82:83], v[14:15], v[130:131], v[82:83] op_sel:[0,1,0]
	v_pk_fma_f32 v[80:81], v[20:21], v[132:133], v[80:81] op_sel_hi:[1,0,1]
	v_pk_fma_f32 v[82:83], v[22:23], v[132:133], v[82:83] op_sel_hi:[1,0,1]
	v_pk_fma_f32 v[80:81], v[24:25], v[132:133], v[80:81] op_sel:[0,1,0]
	v_pk_fma_f32 v[82:83], v[26:27], v[132:133], v[82:83] op_sel:[0,1,0]
	v_pk_fma_f32 v[80:81], v[28:29], v[134:135], v[80:81] op_sel_hi:[1,0,1]
	v_pk_fma_f32 v[82:83], v[30:31], v[134:135], v[82:83] op_sel_hi:[1,0,1]
	v_pk_fma_f32 v[80:81], v[32:33], v[134:135], v[80:81] op_sel:[0,1,0]
	v_pk_fma_f32 v[82:83], v[34:35], v[134:135], v[82:83] op_sel:[0,1,0]
	global_store_dwordx4 v106, v[80:83], s[14:15] nt
	v_add_u32_e32 v106, 0x20000, v106
	global_load_dwordx4 v[80:83], v106, s[12:13] nt
	ds_read_b128 v[128:131], v118 offset:800
	ds_read_b128 v[132:135], v118 offset:816
	ds_read_b32 v136, v16 offset:48
	s_waitcnt vmcnt(30) lgkmcnt(3)
	v_pk_fma_f32 v[64:65], v[84:85], v[120:121], v[64:65] op_sel_hi:[1,0,1]
	v_pk_fma_f32 v[66:67], v[86:87], v[120:121], v[66:67] op_sel_hi:[1,0,1]
	v_pk_fma_f32 v[60:61], v[84:85], v[120:121], v[60:61] op_sel:[0,1,0]
	v_pk_fma_f32 v[62:63], v[86:87], v[120:121], v[62:63] op_sel:[0,1,0]
	v_pk_fma_f32 v[56:57], v[84:85], v[122:123], v[56:57] op_sel_hi:[1,0,1]
	v_pk_fma_f32 v[58:59], v[86:87], v[122:123], v[58:59] op_sel_hi:[1,0,1]
	v_pk_fma_f32 v[52:53], v[84:85], v[122:123], v[52:53] op_sel:[0,1,0]
	v_pk_fma_f32 v[54:55], v[86:87], v[122:123], v[54:55] op_sel:[0,1,0]
	v_pk_fma_f32 v[48:49], v[84:85], v[124:125], v[48:49] op_sel_hi:[1,0,1]
	v_pk_fma_f32 v[50:51], v[86:87], v[124:125], v[50:51] op_sel_hi:[1,0,1]
	v_pk_fma_f32 v[40:41], v[84:85], v[124:125], v[40:41] op_sel:[0,1,0]
	v_pk_fma_f32 v[42:43], v[86:87], v[124:125], v[42:43] op_sel:[0,1,0]
	v_pk_fma_f32 v[36:37], v[84:85], v[126:127], v[36:37] op_sel_hi:[1,0,1]
	v_pk_fma_f32 v[38:39], v[86:87], v[126:127], v[38:39] op_sel_hi:[1,0,1]
	v_pk_fma_f32 v[44:45], v[84:85], v[126:127], v[44:45] op_sel:[0,1,0]
	v_pk_fma_f32 v[46:47], v[86:87], v[126:127], v[46:47] op_sel:[0,1,0]
	ds_read_b128 v[120:123], v118 offset:1024
	ds_read_b128 v[124:127], v118 offset:1040
	s_waitcnt lgkmcnt(2)
; #define LAS __attribute__((address_space(3)))
; template <int TY> __device__ __forceinline__ void sample_item(const Params& p, ldsp lds, int item) {
;     ...
; #pragma unroll 8
;     for (int d = dg; d < DK; d += NG) { const f32x4 s0 = __builtin_nontemporal_load((const f32x4*)(S0 + (size_t)d * DV + e4 * 4));
;         const f32x4 qa = *(const LAS f32x4*)(QK + d * 16), qb = *(const LAS f32x4*)(QK + d * 16 + 4), ka = *(const LAS f32x4*)(QK + d * 16 + 8), kb = *(const LAS f32x4*)(QK + d * 16 + 12);
;         const float dc = DECs[d];
;         o[0] += s0 * qa[0]; o[1] += s0 * qa[1]; o[2] += s0 * qa[2]; o[3] += s0 * qa[3]; o[4] += s0 * qb[0]; o[5] += s0 * qb[1]; o[6] += s0 * qb[2]; o[7] += s0 * qb[3];
;         f32x4 sn = s0 * dc; sn += v[0] * ka[0]; sn += v[1] * ka[1]; sn += v[2] * ka[2]; sn += v[3] * ka[3]; sn += v[4] * kb[0]; sn += v[5] * kb[1]; sn += v[6] * kb[2]; sn += v[7] * kb[3];
;         __builtin_nontemporal_store(sn, (f32x4*)(S1 + (size_t)d * DV + e4 * 4)); }
	v_pk_mul_f32 v[84:85], v[84:85], v[136:137] op_sel_hi:[1,0]
	v_pk_mul_f32 v[86:87], v[86:87], v[136:137] op_sel_hi:[1,0]
	v_pk_fma_f32 v[84:85], v[0:1], v[128:129], v[84:85] op_sel_hi:[1,0,1]
	v_pk_fma_f32 v[86:87], v[2:3], v[128:129], v[86:87] op_sel_hi:[1,0,1]
	v_pk_fma_f32 v[84:85], v[4:5], v[128:129], v[84:85] op_sel:[0,1,0]
	v_pk_fma_f32 v[86:87], v[6:7], v[128:129], v[86:87] op_sel:[0,1,0]
	v_pk_fma_f32 v[84:85], v[8:9], v[130:131], v[84:85] op_sel_hi:[1,0,1]
	v_pk_fma_f32 v[86:87], v[10:11], v[130:131], v[86:87] op_sel_hi:[1,0,1]
	v_pk_fma_f32 v[84:85], v[12:13], v[130:131], v[84:85] op_sel:[0,1,0]
	v_pk_fma_f32 v[86:87], v[14:15], v[130:131], v[86:87] op_sel:[0,1,0]
	v_pk_fma_f32 v[84:85], v[20:21], v[132:133], v[84:85] op_sel_hi:[1,0,1]
	v_pk_fma_f32 v[86:87], v[22:23], v[132:133], v[86:87] op_sel_hi:[1,0,1]
	v_pk_fma_f32 v[84:85], v[24:25], v[132:133], v[84:85] op_sel:[0,1,0]
	v_pk_fma_f32 v[86:87], v[26:27], v[132:133], v[86:87] op_sel:[0,1,0]
	v_pk_fma_f32 v[84:85], v[28:29], v[134:135], v[84:85] op_sel_hi:[1,0,1]
	v_pk_fma_f32 v[86:87], v[30:31], v[134:135], v[86:87] op_sel_hi:[1,0,1]
	v_pk_fma_f32 v[84:85], v[32:33], v[134:135], v[84:85] op_sel:[0,1,0]
	v_pk_fma_f32 v[86:87], v[34:35], v[134:135], v[86:87] op_sel:[0,1,0]
	global_store_dwordx4 v107, v[84:87], s[14:15] nt
	v_add_u32_e32 v107, 0x20000, v107
	global_load_dwordx4 v[84:87], v107, s[12:13] nt
	ds_read_b128 v[128:131], v118 offset:1056
	ds_read_b128 v[132:135], v118 offset:1072
	ds_read_b32 v136, v16 offset:64
	s_waitcnt vmcnt(30) lgkmcnt(3)
	v_pk_fma_f32 v[64:65], v[88:89], v[120:121], v[64:65] op_sel_hi:[1,0,1]
	v_pk_fma_f32 v[66:67], v[90:91], v[120:121], v[66:67] op_sel_hi:[1,0,1]
	v_pk_fma_f32 v[60:61], v[88:89], v[120:121], v[60:61] op_sel:[0,1,0]
	v_pk_fma_f32 v[62:63], v[90:91], v[120:121], v[62:63] op_sel:[0,1,0]
	v_pk_fma_f32 v[56:57], v[88:89], v[122:123], v[56:57] op_sel_hi:[1,0,1]
	v_pk_fma_f32 v[58:59], v[90:91], v[122:123], v[58:59] op_sel_hi:[1,0,1]
	v_pk_fma_f32 v[52:53], v[88:89], v[122:123], v[52:53] op_sel:[0,1,0]
	v_pk_fma_f32 v[54:55], v[90:91], v[122:123], v[54:55] op_sel:[0,1,0]
	v_pk_fma_f32 v[48:49], v[88:89], v[124:125], v[48:49] op_sel_hi:[1,0,1]
	v_pk_fma_f32 v[50:51], v[90:91], v[124:125], v[50:51] op_sel_hi:[1,0,1]
	v_pk_fma_f32 v[40:41], v[88:89], v[124:125], v[40:41] op_sel:[0,1,0]
	v_pk_fma_f32 v[42:43], v[90:91], v[124:125], v[42:43] op_sel:[0,1,0]
	v_pk_fma_f32 v[36:37], v[88:89], v[126:127], v[36:37] op_sel_hi:[1,0,1]
	v_pk_fma_f32 v[38:39], v[90:91], v[126:127], v[38:39] op_sel_hi:[1,0,1]
	v_pk_fma_f32 v[44:45], v[88:89], v[126:127], v[44:45] op_sel:[0,1,0]
	v_pk_fma_f32 v[46:47], v[90:91], v[126:127], v[46:47] op_sel:[0,1,0]
	ds_read_b128 v[120:123], v118 offset:1280
	ds_read_b128 v[124:127], v118 offset:1296
	s_waitcnt lgkmcnt(2)
	v_pk_mul_f32 v[88:89], v[88:89], v[136:137] op_sel_hi:[1,0]
	v_pk_mul_f32 v[90:91], v[90:91], v[136:137] op_sel_hi:[1,0]
	v_pk_fma_f32 v[88:89], v[0:1], v[128:129], v[88:89] op_sel_hi:[1,0,1]
	v_pk_fma_f32 v[90:91], v[2:3], v[128:129], v[90:91] op_sel_hi:[1,0,1]
	v_pk_fma_f32 v[88:89], v[4:5], v[128:129], v[88:89] op_sel:[0,1,0]
	v_pk_fma_f32 v[90:91], v[6:7], v[128:129], v[90:91] op_sel:[0,1,0]
	v_pk_fma_f32 v[88:89], v[8:9], v[130:131], v[88:89] op_sel_hi:[1,0,1]
	v_pk_fma_f32 v[90:91], v[10:11], v[130:131], v[90:91] op_sel_hi:[1,0,1]
	v_pk_fma_f32 v[88:89], v[12:13], v[130:131], v[88:89] op_sel:[0,1,0]
	v_pk_fma_f32 v[90:91], v[14:15], v[130:131], v[90:91] op_sel:[0,1,0]
	v_pk_fma_f32 v[88:89], v[20:21], v[132:133], v[88:89] op_sel_hi:[1,0,1]
	v_pk_fma_f32 v[90:91], v[22:23], v[132:133], v[90:91] op_sel_hi:[1,0,1]
	v_pk_fma_f32 v[88:89], v[24:25], v[132:133], v[88:89] op_sel:[0,1,0]
	v_pk_fma_f32 v[90:91], v[26:27], v[132:133], v[90:91] op_sel:[0,1,0]
	v_pk_fma_f32 v[88:89], v[28:29], v[134:135], v[88:89] op_sel_hi:[1,0,1]
	v_pk_fma_f32 v[90:91], v[30:31], v[134:135], v[90:91] op_sel_hi:[1,0,1]
	v_pk_fma_f32 v[88:89], v[32:33], v[134:135], v[88:89] op_sel:[0,1,0]
	v_pk_fma_f32 v[90:91], v[34:35], v[134:135], v[90:91] op_sel:[0,1,0]
	global_store_dwordx4 v108, v[88:91], s[14:15] nt
	v_add_u32_e32 v108, 0x20000, v108
	global_load_dwordx4 v[88:91], v108, s[12:13] nt
	ds_read_b128 v[128:131], v118 offset:1312
	ds_read_b128 v[132:135], v118 offset:1328
	ds_read_b32 v136, v16 offset:80
	s_waitcnt vmcnt(30) lgkmcnt(3)
	v_pk_fma_f32 v[64:65], v[92:93], v[120:121], v[64:65] op_sel_hi:[1,0,1]
	v_pk_fma_f32 v[66:67], v[94:95], v[120:121], v[66:67] op_sel_hi:[1,0,1]
	v_pk_fma_f32 v[60:61], v[92:93], v[120:121], v[60:61] op_sel:[0,1,0]
	v_pk_fma_f32 v[62:63], v[94:95], v[120:121], v[62:63] op_sel:[0,1,0]
	v_pk_fma_f32 v[56:57], v[92:93], v[122:123], v[56:57] op_sel_hi:[1,0,1]
	v_pk_fma_f32 v[58:59], v[94:95], v[122:123], v[58:59] op_sel_hi:[1,0,1]
	v_pk_fma_f32 v[52:53], v[92:93], v[122:123], v[52:53] op_sel:[0,1,0]
	v_pk_fma_f32 v[54:55], v[94:95], v[122:123], v[54:55] op_sel:[0,1,0]
	v_pk_fma_f32 v[48:49], v[92:93], v[124:125], v[48:49] op_sel_hi:[1,0,1]
	v_pk_fma_f32 v[50:51], v[94:95], v[124:125], v[50:51] op_sel_hi:[1,0,1]
	v_pk_fma_f32 v[40:41], v[92:93], v[124:125], v[40:41] op_sel:[0,1,0]
	v_pk_fma_f32 v[42:43], v[94:95], v[124:125], v[42:43] op_sel:[0,1,0]
	v_pk_fma_f32 v[36:37], v[92:93], v[126:127], v[36:37] op_sel_hi:[1,0,1]
	v_pk_fma_f32 v[38:39], v[94:95], v[126:127], v[38:39] op_sel_hi:[1,0,1]
	v_pk_fma_f32 v[44:45], v[92:93], v[126:127], v[44:45] op_sel:[0,1,0]
	v_pk_fma_f32 v[46:47], v[94:95], v[126:127], v[46:47] op_sel:[0,1,0]
	ds_read_b128 v[120:123], v118 offset:1536
	ds_read_b128 v[124:127], v118 offset:1552
	s_waitcnt lgkmcnt(2)
; #define LAS __attribute__((address_space(3)))
; template <int TY> __device__ __forceinline__ void sample_item(const Params& p, ldsp lds, int item) {
;     ...
; #pragma unroll 8
;     for (int d = dg; d < DK; d += NG) { const f32x4 s0 = __builtin_nontemporal_load((const f32x4*)(S0 + (size_t)d * DV + e4 * 4));
;         const f32x4 qa = *(const LAS f32x4*)(QK + d * 16), qb = *(const LAS f32x4*)(QK + d * 16 + 4), ka = *(const LAS f32x4*)(QK + d * 16 + 8), kb = *(const LAS f32x4*)(QK + d * 16 + 12);
;         const float dc = DECs[d];
;         o[0] += s0 * qa[0]; o[1] += s0 * qa[1]; o[2] += s0 * qa[2]; o[3] += s0 * qa[3]; o[4] += s0 * qb[0]; o[5] += s0 * qb[1]; o[6] += s0 * qb[2]; o[7] += s0 * qb[3];
;         f32x4 sn = s0 * dc; sn += v[0] * ka[0]; sn += v[1] * ka[1]; sn += v[2] * ka[2]; sn += v[3] * ka[3]; sn += v[4] * kb[0]; sn += v[5] * kb[1]; sn += v[6] * kb[2]; sn += v[7] * kb[3];
;         __builtin_nontemporal_store(sn, (f32x4*)(S1 + (size_t)d * DV + e4 * 4)); }
	v_pk_mul_f32 v[92:93], v[92:93], v[136:137] op_sel_hi:[1,0]
	v_pk_mul_f32 v[94:95], v[94:95], v[136:137] op_sel_hi:[1,0]
	v_pk_fma_f32 v[92:93], v[0:1], v[128:129], v[92:93] op_sel_hi:[1,0,1]
	v_pk_fma_f32 v[94:95], v[2:3], v[128:129], v[94:95] op_sel_hi:[1,0,1]
	v_pk_fma_f32 v[92:93], v[4:5], v[128:129], v[92:93] op_sel:[0,1,0]
	v_pk_fma_f32 v[94:95], v[6:7], v[128:129], v[94:95] op_sel:[0,1,0]
	v_pk_fma_f32 v[92:93], v[8:9], v[130:131], v[92:93] op_sel_hi:[1,0,1]
	v_pk_fma_f32 v[94:95], v[10:11], v[130:131], v[94:95] op_sel_hi:[1,0,1]
	v_pk_fma_f32 v[92:93], v[12:13], v[130:131], v[92:93] op_sel:[0,1,0]
	v_pk_fma_f32 v[94:95], v[14:15], v[130:131], v[94:95] op_sel:[0,1,0]
	v_pk_fma_f32 v[92:93], v[20:21], v[132:133], v[92:93] op_sel_hi:[1,0,1]
	v_pk_fma_f32 v[94:95], v[22:23], v[132:133], v[94:95] op_sel_hi:[1,0,1]
	v_pk_fma_f32 v[92:93], v[24:25], v[132:133], v[92:93] op_sel:[0,1,0]
	v_pk_fma_f32 v[94:95], v[26:27], v[132:133], v[94:95] op_sel:[0,1,0]
	v_pk_fma_f32 v[92:93], v[28:29], v[134:135], v[92:93] op_sel_hi:[1,0,1]
	v_pk_fma_f32 v[94:95], v[30:31], v[134:135], v[94:95] op_sel_hi:[1,0,1]
	v_pk_fma_f32 v[92:93], v[32:33], v[134:135], v[92:93] op_sel:[0,1,0]
	v_pk_fma_f32 v[94:95], v[34:35], v[134:135], v[94:95] op_sel:[0,1,0]
	global_store_dwordx4 v109, v[92:95], s[14:15] nt
	v_add_u32_e32 v109, 0x20000, v109
	global_load_dwordx4 v[92:95], v109, s[12:13] nt
	ds_read_b128 v[128:131], v118 offset:1568
	ds_read_b128 v[132:135], v118 offset:1584
	ds_read_b32 v136, v16 offset:96
	s_waitcnt vmcnt(30) lgkmcnt(3)
	v_pk_fma_f32 v[64:65], v[96:97], v[120:121], v[64:65] op_sel_hi:[1,0,1]
	v_pk_fma_f32 v[66:67], v[98:99], v[120:121], v[66:67] op_sel_hi:[1,0,1]
	v_pk_fma_f32 v[60:61], v[96:97], v[120:121], v[60:61] op_sel:[0,1,0]
	v_pk_fma_f32 v[62:63], v[98:99], v[120:121], v[62:63] op_sel:[0,1,0]
	v_pk_fma_f32 v[56:57], v[96:97], v[122:123], v[56:57] op_sel_hi:[1,0,1]
	v_pk_fma_f32 v[58:59], v[98:99], v[122:123], v[58:59] op_sel_hi:[1,0,1]
	v_pk_fma_f32 v[52:53], v[96:97], v[122:123], v[52:53] op_sel:[0,1,0]
	v_pk_fma_f32 v[54:55], v[98:99], v[122:123], v[54:55] op_sel:[0,1,0]
	v_pk_fma_f32 v[48:49], v[96:97], v[124:125], v[48:49] op_sel_hi:[1,0,1]
	v_pk_fma_f32 v[50:51], v[98:99], v[124:125], v[50:51] op_sel_hi:[1,0,1]
	v_pk_fma_f32 v[40:41], v[96:97], v[124:125], v[40:41] op_sel:[0,1,0]
	v_pk_fma_f32 v[42:43], v[98:99], v[124:125], v[42:43] op_sel:[0,1,0]
	v_pk_fma_f32 v[36:37], v[96:97], v[126:127], v[36:37] op_sel_hi:[1,0,1]
	v_pk_fma_f32 v[38:39], v[98:99], v[126:127], v[38:39] op_sel_hi:[1,0,1]
	v_pk_fma_f32 v[44:45], v[96:97], v[126:127], v[44:45] op_sel:[0,1,0]
	v_pk_fma_f32 v[46:47], v[98:99], v[126:127], v[46:47] op_sel:[0,1,0]
	ds_read_b128 v[120:123], v118 offset:1792
	ds_read_b128 v[124:127], v118 offset:1808
	s_waitcnt lgkmcnt(2)
	v_pk_mul_f32 v[96:97], v[96:97], v[136:137] op_sel_hi:[1,0]
	v_pk_mul_f32 v[98:99], v[98:99], v[136:137] op_sel_hi:[1,0]
	v_pk_fma_f32 v[96:97], v[0:1], v[128:129], v[96:97] op_sel_hi:[1,0,1]
	v_pk_fma_f32 v[98:99], v[2:3], v[128:129], v[98:99] op_sel_hi:[1,0,1]
	v_pk_fma_f32 v[96:97], v[4:5], v[128:129], v[96:97] op_sel:[0,1,0]
	v_pk_fma_f32 v[98:99], v[6:7], v[128:129], v[98:99] op_sel:[0,1,0]
	v_pk_fma_f32 v[96:97], v[8:9], v[130:131], v[96:97] op_sel_hi:[1,0,1]
	v_pk_fma_f32 v[98:99], v[10:11], v[130:131], v[98:99] op_sel_hi:[1,0,1]
	v_pk_fma_f32 v[96:97], v[12:13], v[130:131], v[96:97] op_sel:[0,1,0]
	v_pk_fma_f32 v[98:99], v[14:15], v[130:131], v[98:99] op_sel:[0,1,0]
	v_pk_fma_f32 v[96:97], v[20:21], v[132:133], v[96:97] op_sel_hi:[1,0,1]
	v_pk_fma_f32 v[98:99], v[22:23], v[132:133], v[98:99] op_sel_hi:[1,0,1]
	v_pk_fma_f32 v[96:97], v[24:25], v[132:133], v[96:97] op_sel:[0,1,0]
	v_pk_fma_f32 v[98:99], v[26:27], v[132:133], v[98:99] op_sel:[0,1,0]
	v_pk_fma_f32 v[96:97], v[28:29], v[134:135], v[96:97] op_sel_hi:[1,0,1]
	v_pk_fma_f32 v[98:99], v[30:31], v[134:135], v[98:99] op_sel_hi:[1,0,1]
	v_pk_fma_f32 v[96:97], v[32:33], v[134:135], v[96:97] op_sel:[0,1,0]
	v_pk_fma_f32 v[98:99], v[34:35], v[134:135], v[98:99] op_sel:[0,1,0]
	global_store_dwordx4 v110, v[96:99], s[14:15] nt
	v_add_u32_e32 v110, 0x20000, v110
	global_load_dwordx4 v[96:99], v110, s[12:13] nt
	ds_read_b128 v[128:131], v118 offset:1824
	ds_read_b128 v[132:135], v118 offset:1840
	ds_read_b32 v136, v16 offset:112
	s_waitcnt vmcnt(30) lgkmcnt(3)
	v_pk_fma_f32 v[64:65], v[100:101], v[120:121], v[64:65] op_sel_hi:[1,0,1]
	v_pk_fma_f32 v[66:67], v[102:103], v[120:121], v[66:67] op_sel_hi:[1,0,1]
	v_pk_fma_f32 v[60:61], v[100:101], v[120:121], v[60:61] op_sel:[0,1,0]
	v_pk_fma_f32 v[62:63], v[102:103], v[120:121], v[62:63] op_sel:[0,1,0]
	v_pk_fma_f32 v[56:57], v[100:101], v[122:123], v[56:57] op_sel_hi:[1,0,1]
	v_pk_fma_f32 v[58:59], v[102:103], v[122:123], v[58:59] op_sel_hi:[1,0,1]
	v_pk_fma_f32 v[52:53], v[100:101], v[122:123], v[52:53] op_sel:[0,1,0]
	v_pk_fma_f32 v[54:55], v[102:103], v[122:123], v[54:55] op_sel:[0,1,0]
	v_pk_fma_f32 v[48:49], v[100:101], v[124:125], v[48:49] op_sel_hi:[1,0,1]
	v_pk_fma_f32 v[50:51], v[102:103], v[124:125], v[50:51] op_sel_hi:[1,0,1]
	v_pk_fma_f32 v[40:41], v[100:101], v[124:125], v[40:41] op_sel:[0,1,0]
	v_pk_fma_f32 v[42:43], v[102:103], v[124:125], v[42:43] op_sel:[0,1,0]
	v_pk_fma_f32 v[36:37], v[100:101], v[126:127], v[36:37] op_sel_hi:[1,0,1]
	v_pk_fma_f32 v[38:39], v[102:103], v[126:127], v[38:39] op_sel_hi:[1,0,1]
	v_pk_fma_f32 v[44:45], v[100:101], v[126:127], v[44:45] op_sel:[0,1,0]
	v_pk_fma_f32 v[46:47], v[102:103], v[126:127], v[46:47] op_sel:[0,1,0]
	ds_read_b128 v[120:123], v118 offset:2048
	ds_read_b128 v[124:127], v118 offset:2064
	s_waitcnt lgkmcnt(2)
; #define LAS __attribute__((address_space(3)))
; template <int TY> __device__ __forceinline__ void sample_item(const Params& p, ldsp lds, int item) {
;     ...
; #pragma unroll 8
;     for (int d = dg; d < DK; d += NG) { const f32x4 s0 = __builtin_nontemporal_load((const f32x4*)(S0 + (size_t)d * DV + e4 * 4));
;         const f32x4 qa = *(const LAS f32x4*)(QK + d * 16), qb = *(const LAS f32x4*)(QK + d * 16 + 4), ka = *(const LAS f32x4*)(QK + d * 16 + 8), kb = *(const LAS f32x4*)(QK + d * 16 + 12);
;         const float dc = DECs[d];
;         o[0] += s0 * qa[0]; o[1] += s0 * qa[1]; o[2] += s0 * qa[2]; o[3] += s0 * qa[3]; o[4] += s0 * qb[0]; o[5] += s0 * qb[1]; o[6] += s0 * qb[2]; o[7] += s0 * qb[3];
;         f32x4 sn = s0 * dc; sn += v[0] * ka[0]; sn += v[1] * ka[1]; sn += v[2] * ka[2]; sn += v[3] * ka[3]; sn += v[4] * kb[0]; sn += v[5] * kb[1]; sn += v[6] * kb[2]; sn += v[7] * kb[3];
;         __builtin_nontemporal_store(sn, (f32x4*)(S1 + (size_t)d * DV + e4 * 4)); }
	v_pk_mul_f32 v[100:101], v[100:101], v[136:137] op_sel_hi:[1,0]
	v_pk_mul_f32 v[102:103], v[102:103], v[136:137] op_sel_hi:[1,0]
	v_pk_fma_f32 v[100:101], v[0:1], v[128:129], v[100:101] op_sel_hi:[1,0,1]
	v_pk_fma_f32 v[102:103], v[2:3], v[128:129], v[102:103] op_sel_hi:[1,0,1]
	v_pk_fma_f32 v[100:101], v[4:5], v[128:129], v[100:101] op_sel:[0,1,0]
	v_pk_fma_f32 v[102:103], v[6:7], v[128:129], v[102:103] op_sel:[0,1,0]
	v_pk_fma_f32 v[100:101], v[8:9], v[130:131], v[100:101] op_sel_hi:[1,0,1]
	v_pk_fma_f32 v[102:103], v[10:11], v[130:131], v[102:103] op_sel_hi:[1,0,1]
	v_pk_fma_f32 v[100:101], v[12:13], v[130:131], v[100:101] op_sel:[0,1,0]
	v_pk_fma_f32 v[102:103], v[14:15], v[130:131], v[102:103] op_sel:[0,1,0]
	v_pk_fma_f32 v[100:101], v[20:21], v[132:133], v[100:101] op_sel_hi:[1,0,1]
	v_pk_fma_f32 v[102:103], v[22:23], v[132:133], v[102:103] op_sel_hi:[1,0,1]
	v_pk_fma_f32 v[100:101], v[24:25], v[132:133], v[100:101] op_sel:[0,1,0]
	v_pk_fma_f32 v[102:103], v[26:27], v[132:133], v[102:103] op_sel:[0,1,0]
	v_pk_fma_f32 v[100:101], v[28:29], v[134:135], v[100:101] op_sel_hi:[1,0,1]
	v_pk_fma_f32 v[102:103], v[30:31], v[134:135], v[102:103] op_sel_hi:[1,0,1]
	v_pk_fma_f32 v[100:101], v[32:33], v[134:135], v[100:101] op_sel:[0,1,0]
	v_pk_fma_f32 v[102:103], v[34:35], v[134:135], v[102:103] op_sel:[0,1,0]
	global_store_dwordx4 v111, v[100:103], s[14:15] nt
	v_add_u32_e32 v111, 0x20000, v111
	global_load_dwordx4 v[100:103], v111, s[12:13] nt
	ds_read_b128 v[128:131], v118 offset:2080
	ds_read_b128 v[132:135], v118 offset:2096
	ds_read_b32 v136, v16 offset:128
	s_waitcnt vmcnt(30) lgkmcnt(3)
	v_pk_fma_f32 v[64:65], v[210:211], v[120:121], v[64:65] op_sel_hi:[1,0,1]
	v_pk_fma_f32 v[66:67], v[212:213], v[120:121], v[66:67] op_sel_hi:[1,0,1]
	v_pk_fma_f32 v[60:61], v[210:211], v[120:121], v[60:61] op_sel:[0,1,0]
	v_pk_fma_f32 v[62:63], v[212:213], v[120:121], v[62:63] op_sel:[0,1,0]
	v_pk_fma_f32 v[56:57], v[210:211], v[122:123], v[56:57] op_sel_hi:[1,0,1]
	v_pk_fma_f32 v[58:59], v[212:213], v[122:123], v[58:59] op_sel_hi:[1,0,1]
	v_pk_fma_f32 v[52:53], v[210:211], v[122:123], v[52:53] op_sel:[0,1,0]
	v_pk_fma_f32 v[54:55], v[212:213], v[122:123], v[54:55] op_sel:[0,1,0]
	v_pk_fma_f32 v[48:49], v[210:211], v[124:125], v[48:49] op_sel_hi:[1,0,1]
	v_pk_fma_f32 v[50:51], v[212:213], v[124:125], v[50:51] op_sel_hi:[1,0,1]
	v_pk_fma_f32 v[40:41], v[210:211], v[124:125], v[40:41] op_sel:[0,1,0]
	v_pk_fma_f32 v[42:43], v[212:213], v[124:125], v[42:43] op_sel:[0,1,0]
	v_pk_fma_f32 v[36:37], v[210:211], v[126:127], v[36:37] op_sel_hi:[1,0,1]
	v_pk_fma_f32 v[38:39], v[212:213], v[126:127], v[38:39] op_sel_hi:[1,0,1]
	v_pk_fma_f32 v[44:45], v[210:211], v[126:127], v[44:45] op_sel:[0,1,0]
	v_pk_fma_f32 v[46:47], v[212:213], v[126:127], v[46:47] op_sel:[0,1,0]
	ds_read_b128 v[120:123], v118 offset:2304
	ds_read_b128 v[124:127], v118 offset:2320
	s_waitcnt lgkmcnt(2)
	v_pk_mul_f32 v[210:211], v[210:211], v[136:137] op_sel_hi:[1,0]
	v_pk_mul_f32 v[212:213], v[212:213], v[136:137] op_sel_hi:[1,0]
	v_pk_fma_f32 v[210:211], v[0:1], v[128:129], v[210:211] op_sel_hi:[1,0,1]
	v_pk_fma_f32 v[212:213], v[2:3], v[128:129], v[212:213] op_sel_hi:[1,0,1]
	v_pk_fma_f32 v[210:211], v[4:5], v[128:129], v[210:211] op_sel:[0,1,0]
	v_pk_fma_f32 v[212:213], v[6:7], v[128:129], v[212:213] op_sel:[0,1,0]
	v_pk_fma_f32 v[210:211], v[8:9], v[130:131], v[210:211] op_sel_hi:[1,0,1]
	v_pk_fma_f32 v[212:213], v[10:11], v[130:131], v[212:213] op_sel_hi:[1,0,1]
	v_pk_fma_f32 v[210:211], v[12:13], v[130:131], v[210:211] op_sel:[0,1,0]
	v_pk_fma_f32 v[212:213], v[14:15], v[130:131], v[212:213] op_sel:[0,1,0]
	v_pk_fma_f32 v[210:211], v[20:21], v[132:133], v[210:211] op_sel_hi:[1,0,1]
	v_pk_fma_f32 v[212:213], v[22:23], v[132:133], v[212:213] op_sel_hi:[1,0,1]
	v_pk_fma_f32 v[210:211], v[24:25], v[132:133], v[210:211] op_sel:[0,1,0]
	v_pk_fma_f32 v[212:213], v[26:27], v[132:133], v[212:213] op_sel:[0,1,0]
	v_pk_fma_f32 v[210:211], v[28:29], v[134:135], v[210:211] op_sel_hi:[1,0,1]
	v_pk_fma_f32 v[212:213], v[30:31], v[134:135], v[212:213] op_sel_hi:[1,0,1]
	v_pk_fma_f32 v[210:211], v[32:33], v[134:135], v[210:211] op_sel:[0,1,0]
	v_pk_fma_f32 v[212:213], v[34:35], v[134:135], v[212:213] op_sel:[0,1,0]
	global_store_dwordx4 v242, v[210:213], s[14:15] nt
	v_add_u32_e32 v242, 0x20000, v242
	global_load_dwordx4 v[210:213], v242, s[12:13] nt
	ds_read_b128 v[128:131], v118 offset:2336
	ds_read_b128 v[132:135], v118 offset:2352
	ds_read_b32 v136, v16 offset:144
	s_waitcnt vmcnt(30) lgkmcnt(3)
	v_pk_fma_f32 v[64:65], v[214:215], v[120:121], v[64:65] op_sel_hi:[1,0,1]
	v_pk_fma_f32 v[66:67], v[216:217], v[120:121], v[66:67] op_sel_hi:[1,0,1]
	v_pk_fma_f32 v[60:61], v[214:215], v[120:121], v[60:61] op_sel:[0,1,0]
	v_pk_fma_f32 v[62:63], v[216:217], v[120:121], v[62:63] op_sel:[0,1,0]
	v_pk_fma_f32 v[56:57], v[214:215], v[122:123], v[56:57] op_sel_hi:[1,0,1]
	v_pk_fma_f32 v[58:59], v[216:217], v[122:123], v[58:59] op_sel_hi:[1,0,1]
	v_pk_fma_f32 v[52:53], v[214:215], v[122:123], v[52:53] op_sel:[0,1,0]
	v_pk_fma_f32 v[54:55], v[216:217], v[122:123], v[54:55] op_sel:[0,1,0]
	v_pk_fma_f32 v[48:49], v[214:215], v[124:125], v[48:49] op_sel_hi:[1,0,1]
	v_pk_fma_f32 v[50:51], v[216:217], v[124:125], v[50:51] op_sel_hi:[1,0,1]
	v_pk_fma_f32 v[40:41], v[214:215], v[124:125], v[40:41] op_sel:[0,1,0]
	v_pk_fma_f32 v[42:43], v[216:217], v[124:125], v[42:43] op_sel:[0,1,0]
	v_pk_fma_f32 v[36:37], v[214:215], v[126:127], v[36:37] op_sel_hi:[1,0,1]
	v_pk_fma_f32 v[38:39], v[216:217], v[126:127], v[38:39] op_sel_hi:[1,0,1]
	v_pk_fma_f32 v[44:45], v[214:215], v[126:127], v[44:45] op_sel:[0,1,0]
	v_pk_fma_f32 v[46:47], v[216:217], v[126:127], v[46:47] op_sel:[0,1,0]
	ds_read_b128 v[120:123], v118 offset:2560
	ds_read_b128 v[124:127], v118 offset:2576
	s_waitcnt lgkmcnt(2)
; #define LAS __attribute__((address_space(3)))
; template <int TY> __device__ __forceinline__ void sample_item(const Params& p, ldsp lds, int item) {
;     ...
; #pragma unroll 8
;     for (int d = dg; d < DK; d += NG) { const f32x4 s0 = __builtin_nontemporal_load((const f32x4*)(S0 + (size_t)d * DV + e4 * 4));
;         const f32x4 qa = *(const LAS f32x4*)(QK + d * 16), qb = *(const LAS f32x4*)(QK + d * 16 + 4), ka = *(const LAS f32x4*)(QK + d * 16 + 8), kb = *(const LAS f32x4*)(QK + d * 16 + 12);
;         const float dc = DECs[d];
;         o[0] += s0 * qa[0]; o[1] += s0 * qa[1]; o[2] += s0 * qa[2]; o[3] += s0 * qa[3]; o[4] += s0 * qb[0]; o[5] += s0 * qb[1]; o[6] += s0 * qb[2]; o[7] += s0 * qb[3];
;         f32x4 sn = s0 * dc; sn += v[0] * ka[0]; sn += v[1] * ka[1]; sn += v[2] * ka[2]; sn += v[3] * ka[3]; sn += v[4] * kb[0]; sn += v[5] * kb[1]; sn += v[6] * kb[2]; sn += v[7] * kb[3];
;         __builtin_nontemporal_store(sn, (f32x4*)(S1 + (size_t)d * DV + e4 * 4)); }
	v_pk_mul_f32 v[214:215], v[214:215], v[136:137] op_sel_hi:[1,0]
	v_pk_mul_f32 v[216:217], v[216:217], v[136:137] op_sel_hi:[1,0]
	v_pk_fma_f32 v[214:215], v[0:1], v[128:129], v[214:215] op_sel_hi:[1,0,1]
	v_pk_fma_f32 v[216:217], v[2:3], v[128:129], v[216:217] op_sel_hi:[1,0,1]
	v_pk_fma_f32 v[214:215], v[4:5], v[128:129], v[214:215] op_sel:[0,1,0]
	v_pk_fma_f32 v[216:217], v[6:7], v[128:129], v[216:217] op_sel:[0,1,0]
	v_pk_fma_f32 v[214:215], v[8:9], v[130:131], v[214:215] op_sel_hi:[1,0,1]
	v_pk_fma_f32 v[216:217], v[10:11], v[130:131], v[216:217] op_sel_hi:[1,0,1]
	v_pk_fma_f32 v[214:215], v[12:13], v[130:131], v[214:215] op_sel:[0,1,0]
	v_pk_fma_f32 v[216:217], v[14:15], v[130:131], v[216:217] op_sel:[0,1,0]
	v_pk_fma_f32 v[214:215], v[20:21], v[132:133], v[214:215] op_sel_hi:[1,0,1]
	v_pk_fma_f32 v[216:217], v[22:23], v[132:133], v[216:217] op_sel_hi:[1,0,1]
	v_pk_fma_f32 v[214:215], v[24:25], v[132:133], v[214:215] op_sel:[0,1,0]
	v_pk_fma_f32 v[216:217], v[26:27], v[132:133], v[216:217] op_sel:[0,1,0]
	v_pk_fma_f32 v[214:215], v[28:29], v[134:135], v[214:215] op_sel_hi:[1,0,1]
	v_pk_fma_f32 v[216:217], v[30:31], v[134:135], v[216:217] op_sel_hi:[1,0,1]
	v_pk_fma_f32 v[214:215], v[32:33], v[134:135], v[214:215] op_sel:[0,1,0]
	v_pk_fma_f32 v[216:217], v[34:35], v[134:135], v[216:217] op_sel:[0,1,0]
	global_store_dwordx4 v243, v[214:217], s[14:15] nt
	v_add_u32_e32 v243, 0x20000, v243
	global_load_dwordx4 v[214:217], v243, s[12:13] nt
	ds_read_b128 v[128:131], v118 offset:2592
	ds_read_b128 v[132:135], v118 offset:2608
	ds_read_b32 v136, v16 offset:160
	s_waitcnt vmcnt(30) lgkmcnt(3)
	v_pk_fma_f32 v[64:65], v[218:219], v[120:121], v[64:65] op_sel_hi:[1,0,1]
	v_pk_fma_f32 v[66:67], v[220:221], v[120:121], v[66:67] op_sel_hi:[1,0,1]
	v_pk_fma_f32 v[60:61], v[218:219], v[120:121], v[60:61] op_sel:[0,1,0]
	v_pk_fma_f32 v[62:63], v[220:221], v[120:121], v[62:63] op_sel:[0,1,0]
	v_pk_fma_f32 v[56:57], v[218:219], v[122:123], v[56:57] op_sel_hi:[1,0,1]
	v_pk_fma_f32 v[58:59], v[220:221], v[122:123], v[58:59] op_sel_hi:[1,0,1]
	v_pk_fma_f32 v[52:53], v[218:219], v[122:123], v[52:53] op_sel:[0,1,0]
	v_pk_fma_f32 v[54:55], v[220:221], v[122:123], v[54:55] op_sel:[0,1,0]
	v_pk_fma_f32 v[48:49], v[218:219], v[124:125], v[48:49] op_sel_hi:[1,0,1]
	v_pk_fma_f32 v[50:51], v[220:221], v[124:125], v[50:51] op_sel_hi:[1,0,1]
	v_pk_fma_f32 v[40:41], v[218:219], v[124:125], v[40:41] op_sel:[0,1,0]
	v_pk_fma_f32 v[42:43], v[220:221], v[124:125], v[42:43] op_sel:[0,1,0]
	v_pk_fma_f32 v[36:37], v[218:219], v[126:127], v[36:37] op_sel_hi:[1,0,1]
	v_pk_fma_f32 v[38:39], v[220:221], v[126:127], v[38:39] op_sel_hi:[1,0,1]
	v_pk_fma_f32 v[44:45], v[218:219], v[126:127], v[44:45] op_sel:[0,1,0]
	v_pk_fma_f32 v[46:47], v[220:221], v[126:127], v[46:47] op_sel:[0,1,0]
	ds_read_b128 v[120:123], v118 offset:2816
	ds_read_b128 v[124:127], v118 offset:2832
	s_waitcnt lgkmcnt(2)
	v_pk_mul_f32 v[218:219], v[218:219], v[136:137] op_sel_hi:[1,0]
	v_pk_mul_f32 v[220:221], v[220:221], v[136:137] op_sel_hi:[1,0]
	v_pk_fma_f32 v[218:219], v[0:1], v[128:129], v[218:219] op_sel_hi:[1,0,1]
	v_pk_fma_f32 v[220:221], v[2:3], v[128:129], v[220:221] op_sel_hi:[1,0,1]
	v_pk_fma_f32 v[218:219], v[4:5], v[128:129], v[218:219] op_sel:[0,1,0]
	v_pk_fma_f32 v[220:221], v[6:7], v[128:129], v[220:221] op_sel:[0,1,0]
	v_pk_fma_f32 v[218:219], v[8:9], v[130:131], v[218:219] op_sel_hi:[1,0,1]
	v_pk_fma_f32 v[220:221], v[10:11], v[130:131], v[220:221] op_sel_hi:[1,0,1]
	v_pk_fma_f32 v[218:219], v[12:13], v[130:131], v[218:219] op_sel:[0,1,0]
	v_pk_fma_f32 v[220:221], v[14:15], v[130:131], v[220:221] op_sel:[0,1,0]
	v_pk_fma_f32 v[218:219], v[20:21], v[132:133], v[218:219] op_sel_hi:[1,0,1]
	v_pk_fma_f32 v[220:221], v[22:23], v[132:133], v[220:221] op_sel_hi:[1,0,1]
	v_pk_fma_f32 v[218:219], v[24:25], v[132:133], v[218:219] op_sel:[0,1,0]
	v_pk_fma_f32 v[220:221], v[26:27], v[132:133], v[220:221] op_sel:[0,1,0]
	v_pk_fma_f32 v[218:219], v[28:29], v[134:135], v[218:219] op_sel_hi:[1,0,1]
	v_pk_fma_f32 v[220:221], v[30:31], v[134:135], v[220:221] op_sel_hi:[1,0,1]
	v_pk_fma_f32 v[218:219], v[32:33], v[134:135], v[218:219] op_sel:[0,1,0]
	v_pk_fma_f32 v[220:221], v[34:35], v[134:135], v[220:221] op_sel:[0,1,0]
	global_store_dwordx4 v244, v[218:221], s[14:15] nt
	v_add_u32_e32 v244, 0x20000, v244
	global_load_dwordx4 v[218:221], v244, s[12:13] nt
	ds_read_b128 v[128:131], v118 offset:2848
	ds_read_b128 v[132:135], v118 offset:2864
	ds_read_b32 v136, v16 offset:176
	s_waitcnt vmcnt(30) lgkmcnt(3)
	v_pk_fma_f32 v[64:65], v[222:223], v[120:121], v[64:65] op_sel_hi:[1,0,1]
	v_pk_fma_f32 v[66:67], v[224:225], v[120:121], v[66:67] op_sel_hi:[1,0,1]
	v_pk_fma_f32 v[60:61], v[222:223], v[120:121], v[60:61] op_sel:[0,1,0]
	v_pk_fma_f32 v[62:63], v[224:225], v[120:121], v[62:63] op_sel:[0,1,0]
	v_pk_fma_f32 v[56:57], v[222:223], v[122:123], v[56:57] op_sel_hi:[1,0,1]
	v_pk_fma_f32 v[58:59], v[224:225], v[122:123], v[58:59] op_sel_hi:[1,0,1]
	v_pk_fma_f32 v[52:53], v[222:223], v[122:123], v[52:53] op_sel:[0,1,0]
	v_pk_fma_f32 v[54:55], v[224:225], v[122:123], v[54:55] op_sel:[0,1,0]
	v_pk_fma_f32 v[48:49], v[222:223], v[124:125], v[48:49] op_sel_hi:[1,0,1]
	v_pk_fma_f32 v[50:51], v[224:225], v[124:125], v[50:51] op_sel_hi:[1,0,1]
	v_pk_fma_f32 v[40:41], v[222:223], v[124:125], v[40:41] op_sel:[0,1,0]
	v_pk_fma_f32 v[42:43], v[224:225], v[124:125], v[42:43] op_sel:[0,1,0]
	v_pk_fma_f32 v[36:37], v[222:223], v[126:127], v[36:37] op_sel_hi:[1,0,1]
	v_pk_fma_f32 v[38:39], v[224:225], v[126:127], v[38:39] op_sel_hi:[1,0,1]
	v_pk_fma_f32 v[44:45], v[222:223], v[126:127], v[44:45] op_sel:[0,1,0]
	v_pk_fma_f32 v[46:47], v[224:225], v[126:127], v[46:47] op_sel:[0,1,0]
	ds_read_b128 v[120:123], v118 offset:3072
	ds_read_b128 v[124:127], v118 offset:3088
	s_waitcnt lgkmcnt(2)
; #define LAS __attribute__((address_space(3)))
; template <int TY> __device__ __forceinline__ void sample_item(const Params& p, ldsp lds, int item) {
;     ...
; #pragma unroll 8
;     for (int d = dg; d < DK; d += NG) { const f32x4 s0 = __builtin_nontemporal_load((const f32x4*)(S0 + (size_t)d * DV + e4 * 4));
;         const f32x4 qa = *(const LAS f32x4*)(QK + d * 16), qb = *(const LAS f32x4*)(QK + d * 16 + 4), ka = *(const LAS f32x4*)(QK + d * 16 + 8), kb = *(const LAS f32x4*)(QK + d * 16 + 12);
;         const float dc = DECs[d];
;         o[0] += s0 * qa[0]; o[1] += s0 * qa[1]; o[2] += s0 * qa[2]; o[3] += s0 * qa[3]; o[4] += s0 * qb[0]; o[5] += s0 * qb[1]; o[6] += s0 * qb[2]; o[7] += s0 * qb[3];
;         f32x4 sn = s0 * dc; sn += v[0] * ka[0]; sn += v[1] * ka[1]; sn += v[2] * ka[2]; sn += v[3] * ka[3]; sn += v[4] * kb[0]; sn += v[5] * kb[1]; sn += v[6] * kb[2]; sn += v[7] * kb[3];
;         __builtin_nontemporal_store(sn, (f32x4*)(S1 + (size_t)d * DV + e4 * 4)); }
	v_pk_mul_f32 v[222:223], v[222:223], v[136:137] op_sel_hi:[1,0]
	v_pk_mul_f32 v[224:225], v[224:225], v[136:137] op_sel_hi:[1,0]
	v_pk_fma_f32 v[222:223], v[0:1], v[128:129], v[222:223] op_sel_hi:[1,0,1]
	v_pk_fma_f32 v[224:225], v[2:3], v[128:129], v[224:225] op_sel_hi:[1,0,1]
	v_pk_fma_f32 v[222:223], v[4:5], v[128:129], v[222:223] op_sel:[0,1,0]
	v_pk_fma_f32 v[224:225], v[6:7], v[128:129], v[224:225] op_sel:[0,1,0]
	v_pk_fma_f32 v[222:223], v[8:9], v[130:131], v[222:223] op_sel_hi:[1,0,1]
	v_pk_fma_f32 v[224:225], v[10:11], v[130:131], v[224:225] op_sel_hi:[1,0,1]
	v_pk_fma_f32 v[222:223], v[12:13], v[130:131], v[222:223] op_sel:[0,1,0]
	v_pk_fma_f32 v[224:225], v[14:15], v[130:131], v[224:225] op_sel:[0,1,0]
	v_pk_fma_f32 v[222:223], v[20:21], v[132:133], v[222:223] op_sel_hi:[1,0,1]
	v_pk_fma_f32 v[224:225], v[22:23], v[132:133], v[224:225] op_sel_hi:[1,0,1]
	v_pk_fma_f32 v[222:223], v[24:25], v[132:133], v[222:223] op_sel:[0,1,0]
	v_pk_fma_f32 v[224:225], v[26:27], v[132:133], v[224:225] op_sel:[0,1,0]
	v_pk_fma_f32 v[222:223], v[28:29], v[134:135], v[222:223] op_sel_hi:[1,0,1]
	v_pk_fma_f32 v[224:225], v[30:31], v[134:135], v[224:225] op_sel_hi:[1,0,1]
	v_pk_fma_f32 v[222:223], v[32:33], v[134:135], v[222:223] op_sel:[0,1,0]
	v_pk_fma_f32 v[224:225], v[34:35], v[134:135], v[224:225] op_sel:[0,1,0]
	global_store_dwordx4 v245, v[222:225], s[14:15] nt
	v_add_u32_e32 v245, 0x20000, v245
	global_load_dwordx4 v[222:225], v245, s[12:13] nt
	ds_read_b128 v[128:131], v118 offset:3104
	ds_read_b128 v[132:135], v118 offset:3120
	ds_read_b32 v136, v16 offset:192
	s_waitcnt vmcnt(30) lgkmcnt(3)
	v_pk_fma_f32 v[64:65], v[226:227], v[120:121], v[64:65] op_sel_hi:[1,0,1]
	v_pk_fma_f32 v[66:67], v[228:229], v[120:121], v[66:67] op_sel_hi:[1,0,1]
	v_pk_fma_f32 v[60:61], v[226:227], v[120:121], v[60:61] op_sel:[0,1,0]
	v_pk_fma_f32 v[62:63], v[228:229], v[120:121], v[62:63] op_sel:[0,1,0]
	v_pk_fma_f32 v[56:57], v[226:227], v[122:123], v[56:57] op_sel_hi:[1,0,1]
	v_pk_fma_f32 v[58:59], v[228:229], v[122:123], v[58:59] op_sel_hi:[1,0,1]
	v_pk_fma_f32 v[52:53], v[226:227], v[122:123], v[52:53] op_sel:[0,1,0]
	v_pk_fma_f32 v[54:55], v[228:229], v[122:123], v[54:55] op_sel:[0,1,0]
	v_pk_fma_f32 v[48:49], v[226:227], v[124:125], v[48:49] op_sel_hi:[1,0,1]
	v_pk_fma_f32 v[50:51], v[228:229], v[124:125], v[50:51] op_sel_hi:[1,0,1]
	v_pk_fma_f32 v[40:41], v[226:227], v[124:125], v[40:41] op_sel:[0,1,0]
	v_pk_fma_f32 v[42:43], v[228:229], v[124:125], v[42:43] op_sel:[0,1,0]
	v_pk_fma_f32 v[36:37], v[226:227], v[126:127], v[36:37] op_sel_hi:[1,0,1]
	v_pk_fma_f32 v[38:39], v[228:229], v[126:127], v[38:39] op_sel_hi:[1,0,1]
	v_pk_fma_f32 v[44:45], v[226:227], v[126:127], v[44:45] op_sel:[0,1,0]
	v_pk_fma_f32 v[46:47], v[228:229], v[126:127], v[46:47] op_sel:[0,1,0]
	ds_read_b128 v[120:123], v118 offset:3328
	ds_read_b128 v[124:127], v118 offset:3344
	s_waitcnt lgkmcnt(2)
	v_pk_mul_f32 v[226:227], v[226:227], v[136:137] op_sel_hi:[1,0]
	v_pk_mul_f32 v[228:229], v[228:229], v[136:137] op_sel_hi:[1,0]
	v_pk_fma_f32 v[226:227], v[0:1], v[128:129], v[226:227] op_sel_hi:[1,0,1]
	v_pk_fma_f32 v[228:229], v[2:3], v[128:129], v[228:229] op_sel_hi:[1,0,1]
	v_pk_fma_f32 v[226:227], v[4:5], v[128:129], v[226:227] op_sel:[0,1,0]
	v_pk_fma_f32 v[228:229], v[6:7], v[128:129], v[228:229] op_sel:[0,1,0]
	v_pk_fma_f32 v[226:227], v[8:9], v[130:131], v[226:227] op_sel_hi:[1,0,1]
	v_pk_fma_f32 v[228:229], v[10:11], v[130:131], v[228:229] op_sel_hi:[1,0,1]
	v_pk_fma_f32 v[226:227], v[12:13], v[130:131], v[226:227] op_sel:[0,1,0]
	v_pk_fma_f32 v[228:229], v[14:15], v[130:131], v[228:229] op_sel:[0,1,0]
	v_pk_fma_f32 v[226:227], v[20:21], v[132:133], v[226:227] op_sel_hi:[1,0,1]
	v_pk_fma_f32 v[228:229], v[22:23], v[132:133], v[228:229] op_sel_hi:[1,0,1]
	v_pk_fma_f32 v[226:227], v[24:25], v[132:133], v[226:227] op_sel:[0,1,0]
	v_pk_fma_f32 v[228:229], v[26:27], v[132:133], v[228:229] op_sel:[0,1,0]
	v_pk_fma_f32 v[226:227], v[28:29], v[134:135], v[226:227] op_sel_hi:[1,0,1]
	v_pk_fma_f32 v[228:229], v[30:31], v[134:135], v[228:229] op_sel_hi:[1,0,1]
	v_pk_fma_f32 v[226:227], v[32:33], v[134:135], v[226:227] op_sel:[0,1,0]
	v_pk_fma_f32 v[228:229], v[34:35], v[134:135], v[228:229] op_sel:[0,1,0]
	global_store_dwordx4 v246, v[226:229], s[14:15] nt
	v_add_u32_e32 v246, 0x20000, v246
	global_load_dwordx4 v[226:229], v246, s[12:13] nt
	ds_read_b128 v[128:131], v118 offset:3360
	ds_read_b128 v[132:135], v118 offset:3376
	ds_read_b32 v136, v16 offset:208
	s_waitcnt vmcnt(30) lgkmcnt(3)
	v_pk_fma_f32 v[64:65], v[230:231], v[120:121], v[64:65] op_sel_hi:[1,0,1]
	v_pk_fma_f32 v[66:67], v[232:233], v[120:121], v[66:67] op_sel_hi:[1,0,1]
	v_pk_fma_f32 v[60:61], v[230:231], v[120:121], v[60:61] op_sel:[0,1,0]
	v_pk_fma_f32 v[62:63], v[232:233], v[120:121], v[62:63] op_sel:[0,1,0]
	v_pk_fma_f32 v[56:57], v[230:231], v[122:123], v[56:57] op_sel_hi:[1,0,1]
	v_pk_fma_f32 v[58:59], v[232:233], v[122:123], v[58:59] op_sel_hi:[1,0,1]
	v_pk_fma_f32 v[52:53], v[230:231], v[122:123], v[52:53] op_sel:[0,1,0]
	v_pk_fma_f32 v[54:55], v[232:233], v[122:123], v[54:55] op_sel:[0,1,0]
	v_pk_fma_f32 v[48:49], v[230:231], v[124:125], v[48:49] op_sel_hi:[1,0,1]
	v_pk_fma_f32 v[50:51], v[232:233], v[124:125], v[50:51] op_sel_hi:[1,0,1]
	v_pk_fma_f32 v[40:41], v[230:231], v[124:125], v[40:41] op_sel:[0,1,0]
	v_pk_fma_f32 v[42:43], v[232:233], v[124:125], v[42:43] op_sel:[0,1,0]
	v_pk_fma_f32 v[36:37], v[230:231], v[126:127], v[36:37] op_sel_hi:[1,0,1]
	v_pk_fma_f32 v[38:39], v[232:233], v[126:127], v[38:39] op_sel_hi:[1,0,1]
	v_pk_fma_f32 v[44:45], v[230:231], v[126:127], v[44:45] op_sel:[0,1,0]
	v_pk_fma_f32 v[46:47], v[232:233], v[126:127], v[46:47] op_sel:[0,1,0]
	ds_read_b128 v[120:123], v118 offset:3584
	ds_read_b128 v[124:127], v118 offset:3600
	s_waitcnt lgkmcnt(2)
; #define LAS __attribute__((address_space(3)))
; template <int TY> __device__ __forceinline__ void sample_item(const Params& p, ldsp lds, int item) {
;     ...
; #pragma unroll 8
;     for (int d = dg; d < DK; d += NG) { const f32x4 s0 = __builtin_nontemporal_load((const f32x4*)(S0 + (size_t)d * DV + e4 * 4));
;         const f32x4 qa = *(const LAS f32x4*)(QK + d * 16), qb = *(const LAS f32x4*)(QK + d * 16 + 4), ka = *(const LAS f32x4*)(QK + d * 16 + 8), kb = *(const LAS f32x4*)(QK + d * 16 + 12);
;         const float dc = DECs[d];
;         o[0] += s0 * qa[0]; o[1] += s0 * qa[1]; o[2] += s0 * qa[2]; o[3] += s0 * qa[3]; o[4] += s0 * qb[0]; o[5] += s0 * qb[1]; o[6] += s0 * qb[2]; o[7] += s0 * qb[3];
;         f32x4 sn = s0 * dc; sn += v[0] * ka[0]; sn += v[1] * ka[1]; sn += v[2] * ka[2]; sn += v[3] * ka[3]; sn += v[4] * kb[0]; sn += v[5] * kb[1]; sn += v[6] * kb[2]; sn += v[7] * kb[3];
;         __builtin_nontemporal_store(sn, (f32x4*)(S1 + (size_t)d * DV + e4 * 4)); }
	v_pk_mul_f32 v[230:231], v[230:231], v[136:137] op_sel_hi:[1,0]
	v_pk_mul_f32 v[232:233], v[232:233], v[136:137] op_sel_hi:[1,0]
	v_pk_fma_f32 v[230:231], v[0:1], v[128:129], v[230:231] op_sel_hi:[1,0,1]
	v_pk_fma_f32 v[232:233], v[2:3], v[128:129], v[232:233] op_sel_hi:[1,0,1]
	v_pk_fma_f32 v[230:231], v[4:5], v[128:129], v[230:231] op_sel:[0,1,0]
	v_pk_fma_f32 v[232:233], v[6:7], v[128:129], v[232:233] op_sel:[0,1,0]
	v_pk_fma_f32 v[230:231], v[8:9], v[130:131], v[230:231] op_sel_hi:[1,0,1]
	v_pk_fma_f32 v[232:233], v[10:11], v[130:131], v[232:233] op_sel_hi:[1,0,1]
	v_pk_fma_f32 v[230:231], v[12:13], v[130:131], v[230:231] op_sel:[0,1,0]
	v_pk_fma_f32 v[232:233], v[14:15], v[130:131], v[232:233] op_sel:[0,1,0]
	v_pk_fma_f32 v[230:231], v[20:21], v[132:133], v[230:231] op_sel_hi:[1,0,1]
	v_pk_fma_f32 v[232:233], v[22:23], v[132:133], v[232:233] op_sel_hi:[1,0,1]
	v_pk_fma_f32 v[230:231], v[24:25], v[132:133], v[230:231] op_sel:[0,1,0]
	v_pk_fma_f32 v[232:233], v[26:27], v[132:133], v[232:233] op_sel:[0,1,0]
	v_pk_fma_f32 v[230:231], v[28:29], v[134:135], v[230:231] op_sel_hi:[1,0,1]
	v_pk_fma_f32 v[232:233], v[30:31], v[134:135], v[232:233] op_sel_hi:[1,0,1]
	v_pk_fma_f32 v[230:231], v[32:33], v[134:135], v[230:231] op_sel:[0,1,0]
	v_pk_fma_f32 v[232:233], v[34:35], v[134:135], v[232:233] op_sel:[0,1,0]
	global_store_dwordx4 v247, v[230:233], s[14:15] nt
	v_add_u32_e32 v247, 0x20000, v247
	global_load_dwordx4 v[230:233], v247, s[12:13] nt
	ds_read_b128 v[128:131], v118 offset:3616
	ds_read_b128 v[132:135], v118 offset:3632
	ds_read_b32 v136, v16 offset:224
	s_waitcnt vmcnt(30) lgkmcnt(3)
	v_pk_fma_f32 v[64:65], v[234:235], v[120:121], v[64:65] op_sel_hi:[1,0,1]
	v_pk_fma_f32 v[66:67], v[236:237], v[120:121], v[66:67] op_sel_hi:[1,0,1]
	v_pk_fma_f32 v[60:61], v[234:235], v[120:121], v[60:61] op_sel:[0,1,0]
	v_pk_fma_f32 v[62:63], v[236:237], v[120:121], v[62:63] op_sel:[0,1,0]
	v_pk_fma_f32 v[56:57], v[234:235], v[122:123], v[56:57] op_sel_hi:[1,0,1]
	v_pk_fma_f32 v[58:59], v[236:237], v[122:123], v[58:59] op_sel_hi:[1,0,1]
	v_pk_fma_f32 v[52:53], v[234:235], v[122:123], v[52:53] op_sel:[0,1,0]
	v_pk_fma_f32 v[54:55], v[236:237], v[122:123], v[54:55] op_sel:[0,1,0]
	v_pk_fma_f32 v[48:49], v[234:235], v[124:125], v[48:49] op_sel_hi:[1,0,1]
	v_pk_fma_f32 v[50:51], v[236:237], v[124:125], v[50:51] op_sel_hi:[1,0,1]
	v_pk_fma_f32 v[40:41], v[234:235], v[124:125], v[40:41] op_sel:[0,1,0]
	v_pk_fma_f32 v[42:43], v[236:237], v[124:125], v[42:43] op_sel:[0,1,0]
	v_pk_fma_f32 v[36:37], v[234:235], v[126:127], v[36:37] op_sel_hi:[1,0,1]
	v_pk_fma_f32 v[38:39], v[236:237], v[126:127], v[38:39] op_sel_hi:[1,0,1]
	v_pk_fma_f32 v[44:45], v[234:235], v[126:127], v[44:45] op_sel:[0,1,0]
	v_pk_fma_f32 v[46:47], v[236:237], v[126:127], v[46:47] op_sel:[0,1,0]
	ds_read_b128 v[120:123], v118 offset:3840
	ds_read_b128 v[124:127], v118 offset:3856
	s_waitcnt lgkmcnt(2)
	v_pk_mul_f32 v[234:235], v[234:235], v[136:137] op_sel_hi:[1,0]
	v_pk_mul_f32 v[236:237], v[236:237], v[136:137] op_sel_hi:[1,0]
	v_pk_fma_f32 v[234:235], v[0:1], v[128:129], v[234:235] op_sel_hi:[1,0,1]
	v_pk_fma_f32 v[236:237], v[2:3], v[128:129], v[236:237] op_sel_hi:[1,0,1]
	v_pk_fma_f32 v[234:235], v[4:5], v[128:129], v[234:235] op_sel:[0,1,0]
	v_pk_fma_f32 v[236:237], v[6:7], v[128:129], v[236:237] op_sel:[0,1,0]
	v_pk_fma_f32 v[234:235], v[8:9], v[130:131], v[234:235] op_sel_hi:[1,0,1]
	v_pk_fma_f32 v[236:237], v[10:11], v[130:131], v[236:237] op_sel_hi:[1,0,1]
	v_pk_fma_f32 v[234:235], v[12:13], v[130:131], v[234:235] op_sel:[0,1,0]
	v_pk_fma_f32 v[236:237], v[14:15], v[130:131], v[236:237] op_sel:[0,1,0]
	v_pk_fma_f32 v[234:235], v[20:21], v[132:133], v[234:235] op_sel_hi:[1,0,1]
	v_pk_fma_f32 v[236:237], v[22:23], v[132:133], v[236:237] op_sel_hi:[1,0,1]
	v_pk_fma_f32 v[234:235], v[24:25], v[132:133], v[234:235] op_sel:[0,1,0]
	v_pk_fma_f32 v[236:237], v[26:27], v[132:133], v[236:237] op_sel:[0,1,0]
	v_pk_fma_f32 v[234:235], v[28:29], v[134:135], v[234:235] op_sel_hi:[1,0,1]
	v_pk_fma_f32 v[236:237], v[30:31], v[134:135], v[236:237] op_sel_hi:[1,0,1]
	v_pk_fma_f32 v[234:235], v[32:33], v[134:135], v[234:235] op_sel:[0,1,0]
	v_pk_fma_f32 v[236:237], v[34:35], v[134:135], v[236:237] op_sel:[0,1,0]
	global_store_dwordx4 v248, v[234:237], s[14:15] nt
	v_add_u32_e32 v248, 0x20000, v248
	global_load_dwordx4 v[234:237], v248, s[12:13] nt
	ds_read_b128 v[128:131], v118 offset:3872
	ds_read_b128 v[132:135], v118 offset:3888
	ds_read_b32 v136, v16 offset:240
	s_waitcnt vmcnt(30) lgkmcnt(3)
	v_pk_fma_f32 v[64:65], v[238:239], v[120:121], v[64:65] op_sel_hi:[1,0,1]
	v_pk_fma_f32 v[66:67], v[240:241], v[120:121], v[66:67] op_sel_hi:[1,0,1]
	v_pk_fma_f32 v[60:61], v[238:239], v[120:121], v[60:61] op_sel:[0,1,0]
	v_pk_fma_f32 v[62:63], v[240:241], v[120:121], v[62:63] op_sel:[0,1,0]
	v_pk_fma_f32 v[56:57], v[238:239], v[122:123], v[56:57] op_sel_hi:[1,0,1]
	v_pk_fma_f32 v[58:59], v[240:241], v[122:123], v[58:59] op_sel_hi:[1,0,1]
	v_pk_fma_f32 v[52:53], v[238:239], v[122:123], v[52:53] op_sel:[0,1,0]
	v_pk_fma_f32 v[54:55], v[240:241], v[122:123], v[54:55] op_sel:[0,1,0]
	v_pk_fma_f32 v[48:49], v[238:239], v[124:125], v[48:49] op_sel_hi:[1,0,1]
	v_pk_fma_f32 v[50:51], v[240:241], v[124:125], v[50:51] op_sel_hi:[1,0,1]
	v_pk_fma_f32 v[40:41], v[238:239], v[124:125], v[40:41] op_sel:[0,1,0]
	v_pk_fma_f32 v[42:43], v[240:241], v[124:125], v[42:43] op_sel:[0,1,0]
	v_pk_fma_f32 v[36:37], v[238:239], v[126:127], v[36:37] op_sel_hi:[1,0,1]
	v_pk_fma_f32 v[38:39], v[240:241], v[126:127], v[38:39] op_sel_hi:[1,0,1]
	v_pk_fma_f32 v[44:45], v[238:239], v[126:127], v[44:45] op_sel:[0,1,0]
	v_pk_fma_f32 v[46:47], v[240:241], v[126:127], v[46:47] op_sel:[0,1,0]
	ds_read_b128 v[120:123], v118 offset:4096
	ds_read_b128 v[124:127], v118 offset:4112
	s_waitcnt lgkmcnt(2)
; #define LAS __attribute__((address_space(3)))
; template <int TY> __device__ __forceinline__ void sample_item(const Params& p, ldsp lds, int item) {
;     ...
; #pragma unroll 8
;     for (int d = dg; d < DK; d += NG) { const f32x4 s0 = __builtin_nontemporal_load((const f32x4*)(S0 + (size_t)d * DV + e4 * 4));
;         const f32x4 qa = *(const LAS f32x4*)(QK + d * 16), qb = *(const LAS f32x4*)(QK + d * 16 + 4), ka = *(const LAS f32x4*)(QK + d * 16 + 8), kb = *(const LAS f32x4*)(QK + d * 16 + 12);
;         const float dc = DECs[d];
;         o[0] += s0 * qa[0]; o[1] += s0 * qa[1]; o[2] += s0 * qa[2]; o[3] += s0 * qa[3]; o[4] += s0 * qb[0]; o[5] += s0 * qb[1]; o[6] += s0 * qb[2]; o[7] += s0 * qb[3];
;         f32x4 sn = s0 * dc; sn += v[0] * ka[0]; sn += v[1] * ka[1]; sn += v[2] * ka[2]; sn += v[3] * ka[3]; sn += v[4] * kb[0]; sn += v[5] * kb[1]; sn += v[6] * kb[2]; sn += v[7] * kb[3];
;         __builtin_nontemporal_store(sn, (f32x4*)(S1 + (size_t)d * DV + e4 * 4)); }
	v_pk_mul_f32 v[238:239], v[238:239], v[136:137] op_sel_hi:[1,0]
	v_pk_mul_f32 v[240:241], v[240:241], v[136:137] op_sel_hi:[1,0]
	v_pk_fma_f32 v[238:239], v[0:1], v[128:129], v[238:239] op_sel_hi:[1,0,1]
	v_pk_fma_f32 v[240:241], v[2:3], v[128:129], v[240:241] op_sel_hi:[1,0,1]
	v_pk_fma_f32 v[238:239], v[4:5], v[128:129], v[238:239] op_sel:[0,1,0]
	v_pk_fma_f32 v[240:241], v[6:7], v[128:129], v[240:241] op_sel:[0,1,0]
	v_pk_fma_f32 v[238:239], v[8:9], v[130:131], v[238:239] op_sel_hi:[1,0,1]
	v_pk_fma_f32 v[240:241], v[10:11], v[130:131], v[240:241] op_sel_hi:[1,0,1]
	v_pk_fma_f32 v[238:239], v[12:13], v[130:131], v[238:239] op_sel:[0,1,0]
	v_pk_fma_f32 v[240:241], v[14:15], v[130:131], v[240:241] op_sel:[0,1,0]
	v_pk_fma_f32 v[238:239], v[20:21], v[132:133], v[238:239] op_sel_hi:[1,0,1]
	v_pk_fma_f32 v[240:241], v[22:23], v[132:133], v[240:241] op_sel_hi:[1,0,1]
	v_pk_fma_f32 v[238:239], v[24:25], v[132:133], v[238:239] op_sel:[0,1,0]
	v_pk_fma_f32 v[240:241], v[26:27], v[132:133], v[240:241] op_sel:[0,1,0]
	v_pk_fma_f32 v[238:239], v[28:29], v[134:135], v[238:239] op_sel_hi:[1,0,1]
	v_pk_fma_f32 v[240:241], v[30:31], v[134:135], v[240:241] op_sel_hi:[1,0,1]
	v_pk_fma_f32 v[238:239], v[32:33], v[134:135], v[238:239] op_sel:[0,1,0]
	v_pk_fma_f32 v[240:241], v[34:35], v[134:135], v[240:241] op_sel:[0,1,0]
	global_store_dwordx4 v249, v[238:241], s[14:15] nt
	v_add_u32_e32 v249, 0x20000, v249
	global_load_dwordx4 v[238:241], v249, s[12:13] nt
	v_add_u32_e32 v118, 0x1000, v118
	v_add_u32_e32 v16, 0x100, v16
	s_add_i32 s16, s16, 1
	s_cmp_lt_u32 s16, 2
	s_cbranch_scc1 .Lsm2_stream_loop
	ds_read_b128 v[128:131], v118 offset:32
	ds_read_b128 v[132:135], v118 offset:48
	ds_read_b32 v136, v16 offset:0
	s_waitcnt vmcnt(30) lgkmcnt(3)
	v_pk_fma_f32 v[64:65], v[72:73], v[120:121], v[64:65] op_sel_hi:[1,0,1]
	v_pk_fma_f32 v[66:67], v[74:75], v[120:121], v[66:67] op_sel_hi:[1,0,1]
	v_pk_fma_f32 v[60:61], v[72:73], v[120:121], v[60:61] op_sel:[0,1,0]
	v_pk_fma_f32 v[62:63], v[74:75], v[120:121], v[62:63] op_sel:[0,1,0]
	v_pk_fma_f32 v[56:57], v[72:73], v[122:123], v[56:57] op_sel_hi:[1,0,1]
	v_pk_fma_f32 v[58:59], v[74:75], v[122:123], v[58:59] op_sel_hi:[1,0,1]
	v_pk_fma_f32 v[52:53], v[72:73], v[122:123], v[52:53] op_sel:[0,1,0]
	v_pk_fma_f32 v[54:55], v[74:75], v[122:123], v[54:55] op_sel:[0,1,0]
	v_pk_fma_f32 v[48:49], v[72:73], v[124:125], v[48:49] op_sel_hi:[1,0,1]
	v_pk_fma_f32 v[50:51], v[74:75], v[124:125], v[50:51] op_sel_hi:[1,0,1]
	v_pk_fma_f32 v[40:41], v[72:73], v[124:125], v[40:41] op_sel:[0,1,0]
	v_pk_fma_f32 v[42:43], v[74:75], v[124:125], v[42:43] op_sel:[0,1,0]
	v_pk_fma_f32 v[36:37], v[72:73], v[126:127], v[36:37] op_sel_hi:[1,0,1]
	v_pk_fma_f32 v[38:39], v[74:75], v[126:127], v[38:39] op_sel_hi:[1,0,1]
	v_pk_fma_f32 v[44:45], v[72:73], v[126:127], v[44:45] op_sel:[0,1,0]
	v_pk_fma_f32 v[46:47], v[74:75], v[126:127], v[46:47] op_sel:[0,1,0]
	ds_read_b128 v[120:123], v118 offset:256
	ds_read_b128 v[124:127], v118 offset:272
	s_waitcnt lgkmcnt(2)
	v_pk_mul_f32 v[72:73], v[72:73], v[136:137] op_sel_hi:[1,0]
	v_pk_mul_f32 v[74:75], v[74:75], v[136:137] op_sel_hi:[1,0]
	v_pk_fma_f32 v[72:73], v[0:1], v[128:129], v[72:73] op_sel_hi:[1,0,1]
	v_pk_fma_f32 v[74:75], v[2:3], v[128:129], v[74:75] op_sel_hi:[1,0,1]
	v_pk_fma_f32 v[72:73], v[4:5], v[128:129], v[72:73] op_sel:[0,1,0]
	v_pk_fma_f32 v[74:75], v[6:7], v[128:129], v[74:75] op_sel:[0,1,0]
	v_pk_fma_f32 v[72:73], v[8:9], v[130:131], v[72:73] op_sel_hi:[1,0,1]
	v_pk_fma_f32 v[74:75], v[10:11], v[130:131], v[74:75] op_sel_hi:[1,0,1]
	v_pk_fma_f32 v[72:73], v[12:13], v[130:131], v[72:73] op_sel:[0,1,0]
	v_pk_fma_f32 v[74:75], v[14:15], v[130:131], v[74:75] op_sel:[0,1,0]
	v_pk_fma_f32 v[72:73], v[20:21], v[132:133], v[72:73] op_sel_hi:[1,0,1]
	v_pk_fma_f32 v[74:75], v[22:23], v[132:133], v[74:75] op_sel_hi:[1,0,1]
	v_pk_fma_f32 v[72:73], v[24:25], v[132:133], v[72:73] op_sel:[0,1,0]
	v_pk_fma_f32 v[74:75], v[26:27], v[132:133], v[74:75] op_sel:[0,1,0]
	v_pk_fma_f32 v[72:73], v[28:29], v[134:135], v[72:73] op_sel_hi:[1,0,1]
	v_pk_fma_f32 v[74:75], v[30:31], v[134:135], v[74:75] op_sel_hi:[1,0,1]
	v_pk_fma_f32 v[72:73], v[32:33], v[134:135], v[72:73] op_sel:[0,1,0]
	v_pk_fma_f32 v[74:75], v[34:35], v[134:135], v[74:75] op_sel:[0,1,0]
	global_store_dwordx4 v104, v[72:75], s[14:15] nt
	ds_read_b128 v[128:131], v118 offset:288
	ds_read_b128 v[132:135], v118 offset:304
	ds_read_b32 v136, v16 offset:16
	s_waitcnt vmcnt(29) lgkmcnt(3)
	v_pk_fma_f32 v[64:65], v[76:77], v[120:121], v[64:65] op_sel_hi:[1,0,1]
	v_pk_fma_f32 v[66:67], v[78:79], v[120:121], v[66:67] op_sel_hi:[1,0,1]
	v_pk_fma_f32 v[60:61], v[76:77], v[120:121], v[60:61] op_sel:[0,1,0]
	v_pk_fma_f32 v[62:63], v[78:79], v[120:121], v[62:63] op_sel:[0,1,0]
	v_pk_fma_f32 v[56:57], v[76:77], v[122:123], v[56:57] op_sel_hi:[1,0,1]
	v_pk_fma_f32 v[58:59], v[78:79], v[122:123], v[58:59] op_sel_hi:[1,0,1]
	v_pk_fma_f32 v[52:53], v[76:77], v[122:123], v[52:53] op_sel:[0,1,0]
	v_pk_fma_f32 v[54:55], v[78:79], v[122:123], v[54:55] op_sel:[0,1,0]
	v_pk_fma_f32 v[48:49], v[76:77], v[124:125], v[48:49] op_sel_hi:[1,0,1]
	v_pk_fma_f32 v[50:51], v[78:79], v[124:125], v[50:51] op_sel_hi:[1,0,1]
	v_pk_fma_f32 v[40:41], v[76:77], v[124:125], v[40:41] op_sel:[0,1,0]
	v_pk_fma_f32 v[42:43], v[78:79], v[124:125], v[42:43] op_sel:[0,1,0]
	v_pk_fma_f32 v[36:37], v[76:77], v[126:127], v[36:37] op_sel_hi:[1,0,1]
	v_pk_fma_f32 v[38:39], v[78:79], v[126:127], v[38:39] op_sel_hi:[1,0,1]
	v_pk_fma_f32 v[44:45], v[76:77], v[126:127], v[44:45] op_sel:[0,1,0]
	v_pk_fma_f32 v[46:47], v[78:79], v[126:127], v[46:47] op_sel:[0,1,0]
	ds_read_b128 v[120:123], v118 offset:512
	ds_read_b128 v[124:127], v118 offset:528
	s_waitcnt lgkmcnt(2)
; #define LAS __attribute__((address_space(3)))
; template <int TY> __device__ __forceinline__ void sample_item(const Params& p, ldsp lds, int item) {
;     ...
; #pragma unroll 8
;     for (int d = dg; d < DK; d += NG) { const f32x4 s0 = __builtin_nontemporal_load((const f32x4*)(S0 + (size_t)d * DV + e4 * 4));
;         const f32x4 qa = *(const LAS f32x4*)(QK + d * 16), qb = *(const LAS f32x4*)(QK + d * 16 + 4), ka = *(const LAS f32x4*)(QK + d * 16 + 8), kb = *(const LAS f32x4*)(QK + d * 16 + 12);
;         const float dc = DECs[d];
;         o[0] += s0 * qa[0]; o[1] += s0 * qa[1]; o[2] += s0 * qa[2]; o[3] += s0 * qa[3]; o[4] += s0 * qb[0]; o[5] += s0 * qb[1]; o[6] += s0 * qb[2]; o[7] += s0 * qb[3];
;         f32x4 sn = s0 * dc; sn += v[0] * ka[0]; sn += v[1] * ka[1]; sn += v[2] * ka[2]; sn += v[3] * ka[3]; sn += v[4] * kb[0]; sn += v[5] * kb[1]; sn += v[6] * kb[2]; sn += v[7] * kb[3];
;         __builtin_nontemporal_store(sn, (f32x4*)(S1 + (size_t)d * DV + e4 * 4)); }
	v_pk_mul_f32 v[76:77], v[76:77], v[136:137] op_sel_hi:[1,0]
	v_pk_mul_f32 v[78:79], v[78:79], v[136:137] op_sel_hi:[1,0]
	v_pk_fma_f32 v[76:77], v[0:1], v[128:129], v[76:77] op_sel_hi:[1,0,1]
	v_pk_fma_f32 v[78:79], v[2:3], v[128:129], v[78:79] op_sel_hi:[1,0,1]
	v_pk_fma_f32 v[76:77], v[4:5], v[128:129], v[76:77] op_sel:[0,1,0]
	v_pk_fma_f32 v[78:79], v[6:7], v[128:129], v[78:79] op_sel:[0,1,0]
	v_pk_fma_f32 v[76:77], v[8:9], v[130:131], v[76:77] op_sel_hi:[1,0,1]
	v_pk_fma_f32 v[78:79], v[10:11], v[130:131], v[78:79] op_sel_hi:[1,0,1]
	v_pk_fma_f32 v[76:77], v[12:13], v[130:131], v[76:77] op_sel:[0,1,0]
	v_pk_fma_f32 v[78:79], v[14:15], v[130:131], v[78:79] op_sel:[0,1,0]
	v_pk_fma_f32 v[76:77], v[20:21], v[132:133], v[76:77] op_sel_hi:[1,0,1]
	v_pk_fma_f32 v[78:79], v[22:23], v[132:133], v[78:79] op_sel_hi:[1,0,1]
	v_pk_fma_f32 v[76:77], v[24:25], v[132:133], v[76:77] op_sel:[0,1,0]
	v_pk_fma_f32 v[78:79], v[26:27], v[132:133], v[78:79] op_sel:[0,1,0]
	v_pk_fma_f32 v[76:77], v[28:29], v[134:135], v[76:77] op_sel_hi:[1,0,1]
	v_pk_fma_f32 v[78:79], v[30:31], v[134:135], v[78:79] op_sel_hi:[1,0,1]
	v_pk_fma_f32 v[76:77], v[32:33], v[134:135], v[76:77] op_sel:[0,1,0]
	v_pk_fma_f32 v[78:79], v[34:35], v[134:135], v[78:79] op_sel:[0,1,0]
	global_store_dwordx4 v105, v[76:79], s[14:15] nt
	ds_read_b128 v[128:131], v118 offset:544
	ds_read_b128 v[132:135], v118 offset:560
	ds_read_b32 v136, v16 offset:32
	s_waitcnt vmcnt(28) lgkmcnt(3)
	v_pk_fma_f32 v[64:65], v[80:81], v[120:121], v[64:65] op_sel_hi:[1,0,1]
	v_pk_fma_f32 v[66:67], v[82:83], v[120:121], v[66:67] op_sel_hi:[1,0,1]
	v_pk_fma_f32 v[60:61], v[80:81], v[120:121], v[60:61] op_sel:[0,1,0]
	v_pk_fma_f32 v[62:63], v[82:83], v[120:121], v[62:63] op_sel:[0,1,0]
	v_pk_fma_f32 v[56:57], v[80:81], v[122:123], v[56:57] op_sel_hi:[1,0,1]
	v_pk_fma_f32 v[58:59], v[82:83], v[122:123], v[58:59] op_sel_hi:[1,0,1]
	v_pk_fma_f32 v[52:53], v[80:81], v[122:123], v[52:53] op_sel:[0,1,0]
	v_pk_fma_f32 v[54:55], v[82:83], v[122:123], v[54:55] op_sel:[0,1,0]
	v_pk_fma_f32 v[48:49], v[80:81], v[124:125], v[48:49] op_sel_hi:[1,0,1]
	v_pk_fma_f32 v[50:51], v[82:83], v[124:125], v[50:51] op_sel_hi:[1,0,1]
	v_pk_fma_f32 v[40:41], v[80:81], v[124:125], v[40:41] op_sel:[0,1,0]
	v_pk_fma_f32 v[42:43], v[82:83], v[124:125], v[42:43] op_sel:[0,1,0]
	v_pk_fma_f32 v[36:37], v[80:81], v[126:127], v[36:37] op_sel_hi:[1,0,1]
	v_pk_fma_f32 v[38:39], v[82:83], v[126:127], v[38:39] op_sel_hi:[1,0,1]
	v_pk_fma_f32 v[44:45], v[80:81], v[126:127], v[44:45] op_sel:[0,1,0]
	v_pk_fma_f32 v[46:47], v[82:83], v[126:127], v[46:47] op_sel:[0,1,0]
	ds_read_b128 v[120:123], v118 offset:768
	ds_read_b128 v[124:127], v118 offset:784
	s_waitcnt lgkmcnt(2)
	v_pk_mul_f32 v[80:81], v[80:81], v[136:137] op_sel_hi:[1,0]
	v_pk_mul_f32 v[82:83], v[82:83], v[136:137] op_sel_hi:[1,0]
	v_pk_fma_f32 v[80:81], v[0:1], v[128:129], v[80:81] op_sel_hi:[1,0,1]
	v_pk_fma_f32 v[82:83], v[2:3], v[128:129], v[82:83] op_sel_hi:[1,0,1]
	v_pk_fma_f32 v[80:81], v[4:5], v[128:129], v[80:81] op_sel:[0,1,0]
	v_pk_fma_f32 v[82:83], v[6:7], v[128:129], v[82:83] op_sel:[0,1,0]
	v_pk_fma_f32 v[80:81], v[8:9], v[130:131], v[80:81] op_sel_hi:[1,0,1]
	v_pk_fma_f32 v[82:83], v[10:11], v[130:131], v[82:83] op_sel_hi:[1,0,1]
	v_pk_fma_f32 v[80:81], v[12:13], v[130:131], v[80:81] op_sel:[0,1,0]
	v_pk_fma_f32 v[82:83], v[14:15], v[130:131], v[82:83] op_sel:[0,1,0]
	v_pk_fma_f32 v[80:81], v[20:21], v[132:133], v[80:81] op_sel_hi:[1,0,1]
	v_pk_fma_f32 v[82:83], v[22:23], v[132:133], v[82:83] op_sel_hi:[1,0,1]
	v_pk_fma_f32 v[80:81], v[24:25], v[132:133], v[80:81] op_sel:[0,1,0]
	v_pk_fma_f32 v[82:83], v[26:27], v[132:133], v[82:83] op_sel:[0,1,0]
	v_pk_fma_f32 v[80:81], v[28:29], v[134:135], v[80:81] op_sel_hi:[1,0,1]
	v_pk_fma_f32 v[82:83], v[30:31], v[134:135], v[82:83] op_sel_hi:[1,0,1]
	v_pk_fma_f32 v[80:81], v[32:33], v[134:135], v[80:81] op_sel:[0,1,0]
	v_pk_fma_f32 v[82:83], v[34:35], v[134:135], v[82:83] op_sel:[0,1,0]
	global_store_dwordx4 v106, v[80:83], s[14:15] nt
	ds_read_b128 v[128:131], v118 offset:800
	ds_read_b128 v[132:135], v118 offset:816
	ds_read_b32 v136, v16 offset:48
	s_waitcnt vmcnt(27) lgkmcnt(3)
	v_pk_fma_f32 v[64:65], v[84:85], v[120:121], v[64:65] op_sel_hi:[1,0,1]
	v_pk_fma_f32 v[66:67], v[86:87], v[120:121], v[66:67] op_sel_hi:[1,0,1]
	v_pk_fma_f32 v[60:61], v[84:85], v[120:121], v[60:61] op_sel:[0,1,0]
	v_pk_fma_f32 v[62:63], v[86:87], v[120:121], v[62:63] op_sel:[0,1,0]
	v_pk_fma_f32 v[56:57], v[84:85], v[122:123], v[56:57] op_sel_hi:[1,0,1]
	v_pk_fma_f32 v[58:59], v[86:87], v[122:123], v[58:59] op_sel_hi:[1,0,1]
	v_pk_fma_f32 v[52:53], v[84:85], v[122:123], v[52:53] op_sel:[0,1,0]
	v_pk_fma_f32 v[54:55], v[86:87], v[122:123], v[54:55] op_sel:[0,1,0]
	v_pk_fma_f32 v[48:49], v[84:85], v[124:125], v[48:49] op_sel_hi:[1,0,1]
	v_pk_fma_f32 v[50:51], v[86:87], v[124:125], v[50:51] op_sel_hi:[1,0,1]
	v_pk_fma_f32 v[40:41], v[84:85], v[124:125], v[40:41] op_sel:[0,1,0]
	v_pk_fma_f32 v[42:43], v[86:87], v[124:125], v[42:43] op_sel:[0,1,0]
	v_pk_fma_f32 v[36:37], v[84:85], v[126:127], v[36:37] op_sel_hi:[1,0,1]
	v_pk_fma_f32 v[38:39], v[86:87], v[126:127], v[38:39] op_sel_hi:[1,0,1]
	v_pk_fma_f32 v[44:45], v[84:85], v[126:127], v[44:45] op_sel:[0,1,0]
	v_pk_fma_f32 v[46:47], v[86:87], v[126:127], v[46:47] op_sel:[0,1,0]
	ds_read_b128 v[120:123], v118 offset:1024
	ds_read_b128 v[124:127], v118 offset:1040
	s_waitcnt lgkmcnt(2)
; #define LAS __attribute__((address_space(3)))
; template <int TY> __device__ __forceinline__ void sample_item(const Params& p, ldsp lds, int item) {
;     ...
; #pragma unroll 8
;     for (int d = dg; d < DK; d += NG) { const f32x4 s0 = __builtin_nontemporal_load((const f32x4*)(S0 + (size_t)d * DV + e4 * 4));
;         const f32x4 qa = *(const LAS f32x4*)(QK + d * 16), qb = *(const LAS f32x4*)(QK + d * 16 + 4), ka = *(const LAS f32x4*)(QK + d * 16 + 8), kb = *(const LAS f32x4*)(QK + d * 16 + 12);
;         const float dc = DECs[d];
;         o[0] += s0 * qa[0]; o[1] += s0 * qa[1]; o[2] += s0 * qa[2]; o[3] += s0 * qa[3]; o[4] += s0 * qb[0]; o[5] += s0 * qb[1]; o[6] += s0 * qb[2]; o[7] += s0 * qb[3];
;         f32x4 sn = s0 * dc; sn += v[0] * ka[0]; sn += v[1] * ka[1]; sn += v[2] * ka[2]; sn += v[3] * ka[3]; sn += v[4] * kb[0]; sn += v[5] * kb[1]; sn += v[6] * kb[2]; sn += v[7] * kb[3];
;         __builtin_nontemporal_store(sn, (f32x4*)(S1 + (size_t)d * DV + e4 * 4)); }
	v_pk_mul_f32 v[84:85], v[84:85], v[136:137] op_sel_hi:[1,0]
	v_pk_mul_f32 v[86:87], v[86:87], v[136:137] op_sel_hi:[1,0]
	v_pk_fma_f32 v[84:85], v[0:1], v[128:129], v[84:85] op_sel_hi:[1,0,1]
	v_pk_fma_f32 v[86:87], v[2:3], v[128:129], v[86:87] op_sel_hi:[1,0,1]
	v_pk_fma_f32 v[84:85], v[4:5], v[128:129], v[84:85] op_sel:[0,1,0]
	v_pk_fma_f32 v[86:87], v[6:7], v[128:129], v[86:87] op_sel:[0,1,0]
	v_pk_fma_f32 v[84:85], v[8:9], v[130:131], v[84:85] op_sel_hi:[1,0,1]
	v_pk_fma_f32 v[86:87], v[10:11], v[130:131], v[86:87] op_sel_hi:[1,0,1]
	v_pk_fma_f32 v[84:85], v[12:13], v[130:131], v[84:85] op_sel:[0,1,0]
	v_pk_fma_f32 v[86:87], v[14:15], v[130:131], v[86:87] op_sel:[0,1,0]
	v_pk_fma_f32 v[84:85], v[20:21], v[132:133], v[84:85] op_sel_hi:[1,0,1]
	v_pk_fma_f32 v[86:87], v[22:23], v[132:133], v[86:87] op_sel_hi:[1,0,1]
	v_pk_fma_f32 v[84:85], v[24:25], v[132:133], v[84:85] op_sel:[0,1,0]
	v_pk_fma_f32 v[86:87], v[26:27], v[132:133], v[86:87] op_sel:[0,1,0]
	v_pk_fma_f32 v[84:85], v[28:29], v[134:135], v[84:85] op_sel_hi:[1,0,1]
	v_pk_fma_f32 v[86:87], v[30:31], v[134:135], v[86:87] op_sel_hi:[1,0,1]
	v_pk_fma_f32 v[84:85], v[32:33], v[134:135], v[84:85] op_sel:[0,1,0]
	v_pk_fma_f32 v[86:87], v[34:35], v[134:135], v[86:87] op_sel:[0,1,0]
	global_store_dwordx4 v107, v[84:87], s[14:15] nt
	ds_read_b128 v[128:131], v118 offset:1056
	ds_read_b128 v[132:135], v118 offset:1072
	ds_read_b32 v136, v16 offset:64
	s_waitcnt vmcnt(26) lgkmcnt(3)
	v_pk_fma_f32 v[64:65], v[88:89], v[120:121], v[64:65] op_sel_hi:[1,0,1]
	v_pk_fma_f32 v[66:67], v[90:91], v[120:121], v[66:67] op_sel_hi:[1,0,1]
	v_pk_fma_f32 v[60:61], v[88:89], v[120:121], v[60:61] op_sel:[0,1,0]
	v_pk_fma_f32 v[62:63], v[90:91], v[120:121], v[62:63] op_sel:[0,1,0]
	v_pk_fma_f32 v[56:57], v[88:89], v[122:123], v[56:57] op_sel_hi:[1,0,1]
	v_pk_fma_f32 v[58:59], v[90:91], v[122:123], v[58:59] op_sel_hi:[1,0,1]
	v_pk_fma_f32 v[52:53], v[88:89], v[122:123], v[52:53] op_sel:[0,1,0]
	v_pk_fma_f32 v[54:55], v[90:91], v[122:123], v[54:55] op_sel:[0,1,0]
	v_pk_fma_f32 v[48:49], v[88:89], v[124:125], v[48:49] op_sel_hi:[1,0,1]
	v_pk_fma_f32 v[50:51], v[90:91], v[124:125], v[50:51] op_sel_hi:[1,0,1]
	v_pk_fma_f32 v[40:41], v[88:89], v[124:125], v[40:41] op_sel:[0,1,0]
	v_pk_fma_f32 v[42:43], v[90:91], v[124:125], v[42:43] op_sel:[0,1,0]
	v_pk_fma_f32 v[36:37], v[88:89], v[126:127], v[36:37] op_sel_hi:[1,0,1]
	v_pk_fma_f32 v[38:39], v[90:91], v[126:127], v[38:39] op_sel_hi:[1,0,1]
	v_pk_fma_f32 v[44:45], v[88:89], v[126:127], v[44:45] op_sel:[0,1,0]
	v_pk_fma_f32 v[46:47], v[90:91], v[126:127], v[46:47] op_sel:[0,1,0]
	ds_read_b128 v[120:123], v118 offset:1280
	ds_read_b128 v[124:127], v118 offset:1296
	s_waitcnt lgkmcnt(2)
	v_pk_mul_f32 v[88:89], v[88:89], v[136:137] op_sel_hi:[1,0]
	v_pk_mul_f32 v[90:91], v[90:91], v[136:137] op_sel_hi:[1,0]
	v_pk_fma_f32 v[88:89], v[0:1], v[128:129], v[88:89] op_sel_hi:[1,0,1]
	v_pk_fma_f32 v[90:91], v[2:3], v[128:129], v[90:91] op_sel_hi:[1,0,1]
	v_pk_fma_f32 v[88:89], v[4:5], v[128:129], v[88:89] op_sel:[0,1,0]
	v_pk_fma_f32 v[90:91], v[6:7], v[128:129], v[90:91] op_sel:[0,1,0]
	v_pk_fma_f32 v[88:89], v[8:9], v[130:131], v[88:89] op_sel_hi:[1,0,1]
	v_pk_fma_f32 v[90:91], v[10:11], v[130:131], v[90:91] op_sel_hi:[1,0,1]
	v_pk_fma_f32 v[88:89], v[12:13], v[130:131], v[88:89] op_sel:[0,1,0]
	v_pk_fma_f32 v[90:91], v[14:15], v[130:131], v[90:91] op_sel:[0,1,0]
	v_pk_fma_f32 v[88:89], v[20:21], v[132:133], v[88:89] op_sel_hi:[1,0,1]
	v_pk_fma_f32 v[90:91], v[22:23], v[132:133], v[90:91] op_sel_hi:[1,0,1]
	v_pk_fma_f32 v[88:89], v[24:25], v[132:133], v[88:89] op_sel:[0,1,0]
	v_pk_fma_f32 v[90:91], v[26:27], v[132:133], v[90:91] op_sel:[0,1,0]
	v_pk_fma_f32 v[88:89], v[28:29], v[134:135], v[88:89] op_sel_hi:[1,0,1]
	v_pk_fma_f32 v[90:91], v[30:31], v[134:135], v[90:91] op_sel_hi:[1,0,1]
	v_pk_fma_f32 v[88:89], v[32:33], v[134:135], v[88:89] op_sel:[0,1,0]
	v_pk_fma_f32 v[90:91], v[34:35], v[134:135], v[90:91] op_sel:[0,1,0]
	global_store_dwordx4 v108, v[88:91], s[14:15] nt
	ds_read_b128 v[128:131], v118 offset:1312
	ds_read_b128 v[132:135], v118 offset:1328
	ds_read_b32 v136, v16 offset:80
	s_waitcnt vmcnt(25) lgkmcnt(3)
	v_pk_fma_f32 v[64:65], v[92:93], v[120:121], v[64:65] op_sel_hi:[1,0,1]
	v_pk_fma_f32 v[66:67], v[94:95], v[120:121], v[66:67] op_sel_hi:[1,0,1]
	v_pk_fma_f32 v[60:61], v[92:93], v[120:121], v[60:61] op_sel:[0,1,0]
	v_pk_fma_f32 v[62:63], v[94:95], v[120:121], v[62:63] op_sel:[0,1,0]
	v_pk_fma_f32 v[56:57], v[92:93], v[122:123], v[56:57] op_sel_hi:[1,0,1]
	v_pk_fma_f32 v[58:59], v[94:95], v[122:123], v[58:59] op_sel_hi:[1,0,1]
	v_pk_fma_f32 v[52:53], v[92:93], v[122:123], v[52:53] op_sel:[0,1,0]
	v_pk_fma_f32 v[54:55], v[94:95], v[122:123], v[54:55] op_sel:[0,1,0]
	v_pk_fma_f32 v[48:49], v[92:93], v[124:125], v[48:49] op_sel_hi:[1,0,1]
	v_pk_fma_f32 v[50:51], v[94:95], v[124:125], v[50:51] op_sel_hi:[1,0,1]
	v_pk_fma_f32 v[40:41], v[92:93], v[124:125], v[40:41] op_sel:[0,1,0]
	v_pk_fma_f32 v[42:43], v[94:95], v[124:125], v[42:43] op_sel:[0,1,0]
	v_pk_fma_f32 v[36:37], v[92:93], v[126:127], v[36:37] op_sel_hi:[1,0,1]
	v_pk_fma_f32 v[38:39], v[94:95], v[126:127], v[38:39] op_sel_hi:[1,0,1]
	v_pk_fma_f32 v[44:45], v[92:93], v[126:127], v[44:45] op_sel:[0,1,0]
	v_pk_fma_f32 v[46:47], v[94:95], v[126:127], v[46:47] op_sel:[0,1,0]
	ds_read_b128 v[120:123], v118 offset:1536
	ds_read_b128 v[124:127], v118 offset:1552
	s_waitcnt lgkmcnt(2)
; #define LAS __attribute__((address_space(3)))
; template <int TY> __device__ __forceinline__ void sample_item(const Params& p, ldsp lds, int item) {
;     ...
; #pragma unroll 8
;     for (int d = dg; d < DK; d += NG) { const f32x4 s0 = __builtin_nontemporal_load((const f32x4*)(S0 + (size_t)d * DV + e4 * 4));
;         const f32x4 qa = *(const LAS f32x4*)(QK + d * 16), qb = *(const LAS f32x4*)(QK + d * 16 + 4), ka = *(const LAS f32x4*)(QK + d * 16 + 8), kb = *(const LAS f32x4*)(QK + d * 16 + 12);
;         const float dc = DECs[d];
;         o[0] += s0 * qa[0]; o[1] += s0 * qa[1]; o[2] += s0 * qa[2]; o[3] += s0 * qa[3]; o[4] += s0 * qb[0]; o[5] += s0 * qb[1]; o[6] += s0 * qb[2]; o[7] += s0 * qb[3];
;         f32x4 sn = s0 * dc; sn += v[0] * ka[0]; sn += v[1] * ka[1]; sn += v[2] * ka[2]; sn += v[3] * ka[3]; sn += v[4] * kb[0]; sn += v[5] * kb[1]; sn += v[6] * kb[2]; sn += v[7] * kb[3];
;         __builtin_nontemporal_store(sn, (f32x4*)(S1 + (size_t)d * DV + e4 * 4)); }
	v_pk_mul_f32 v[92:93], v[92:93], v[136:137] op_sel_hi:[1,0]
	v_pk_mul_f32 v[94:95], v[94:95], v[136:137] op_sel_hi:[1,0]
	v_pk_fma_f32 v[92:93], v[0:1], v[128:129], v[92:93] op_sel_hi:[1,0,1]
	v_pk_fma_f32 v[94:95], v[2:3], v[128:129], v[94:95] op_sel_hi:[1,0,1]
	v_pk_fma_f32 v[92:93], v[4:5], v[128:129], v[92:93] op_sel:[0,1,0]
	v_pk_fma_f32 v[94:95], v[6:7], v[128:129], v[94:95] op_sel:[0,1,0]
	v_pk_fma_f32 v[92:93], v[8:9], v[130:131], v[92:93] op_sel_hi:[1,0,1]
	v_pk_fma_f32 v[94:95], v[10:11], v[130:131], v[94:95] op_sel_hi:[1,0,1]
	v_pk_fma_f32 v[92:93], v[12:13], v[130:131], v[92:93] op_sel:[0,1,0]
	v_pk_fma_f32 v[94:95], v[14:15], v[130:131], v[94:95] op_sel:[0,1,0]
	v_pk_fma_f32 v[92:93], v[20:21], v[132:133], v[92:93] op_sel_hi:[1,0,1]
	v_pk_fma_f32 v[94:95], v[22:23], v[132:133], v[94:95] op_sel_hi:[1,0,1]
	v_pk_fma_f32 v[92:93], v[24:25], v[132:133], v[92:93] op_sel:[0,1,0]
	v_pk_fma_f32 v[94:95], v[26:27], v[132:133], v[94:95] op_sel:[0,1,0]
	v_pk_fma_f32 v[92:93], v[28:29], v[134:135], v[92:93] op_sel_hi:[1,0,1]
	v_pk_fma_f32 v[94:95], v[30:31], v[134:135], v[94:95] op_sel_hi:[1,0,1]
	v_pk_fma_f32 v[92:93], v[32:33], v[134:135], v[92:93] op_sel:[0,1,0]
	v_pk_fma_f32 v[94:95], v[34:35], v[134:135], v[94:95] op_sel:[0,1,0]
	global_store_dwordx4 v109, v[92:95], s[14:15] nt
	ds_read_b128 v[128:131], v118 offset:1568
	ds_read_b128 v[132:135], v118 offset:1584
	ds_read_b32 v136, v16 offset:96
	s_waitcnt vmcnt(24) lgkmcnt(3)
	v_pk_fma_f32 v[64:65], v[96:97], v[120:121], v[64:65] op_sel_hi:[1,0,1]
	v_pk_fma_f32 v[66:67], v[98:99], v[120:121], v[66:67] op_sel_hi:[1,0,1]
	v_pk_fma_f32 v[60:61], v[96:97], v[120:121], v[60:61] op_sel:[0,1,0]
	v_pk_fma_f32 v[62:63], v[98:99], v[120:121], v[62:63] op_sel:[0,1,0]
	v_pk_fma_f32 v[56:57], v[96:97], v[122:123], v[56:57] op_sel_hi:[1,0,1]
	v_pk_fma_f32 v[58:59], v[98:99], v[122:123], v[58:59] op_sel_hi:[1,0,1]
	v_pk_fma_f32 v[52:53], v[96:97], v[122:123], v[52:53] op_sel:[0,1,0]
	v_pk_fma_f32 v[54:55], v[98:99], v[122:123], v[54:55] op_sel:[0,1,0]
	v_pk_fma_f32 v[48:49], v[96:97], v[124:125], v[48:49] op_sel_hi:[1,0,1]
	v_pk_fma_f32 v[50:51], v[98:99], v[124:125], v[50:51] op_sel_hi:[1,0,1]
	v_pk_fma_f32 v[40:41], v[96:97], v[124:125], v[40:41] op_sel:[0,1,0]
	v_pk_fma_f32 v[42:43], v[98:99], v[124:125], v[42:43] op_sel:[0,1,0]
	v_pk_fma_f32 v[36:37], v[96:97], v[126:127], v[36:37] op_sel_hi:[1,0,1]
	v_pk_fma_f32 v[38:39], v[98:99], v[126:127], v[38:39] op_sel_hi:[1,0,1]
	v_pk_fma_f32 v[44:45], v[96:97], v[126:127], v[44:45] op_sel:[0,1,0]
	v_pk_fma_f32 v[46:47], v[98:99], v[126:127], v[46:47] op_sel:[0,1,0]
	ds_read_b128 v[120:123], v118 offset:1792
	ds_read_b128 v[124:127], v118 offset:1808
	s_waitcnt lgkmcnt(2)
	v_pk_mul_f32 v[96:97], v[96:97], v[136:137] op_sel_hi:[1,0]
	v_pk_mul_f32 v[98:99], v[98:99], v[136:137] op_sel_hi:[1,0]
	v_pk_fma_f32 v[96:97], v[0:1], v[128:129], v[96:97] op_sel_hi:[1,0,1]
	v_pk_fma_f32 v[98:99], v[2:3], v[128:129], v[98:99] op_sel_hi:[1,0,1]
	v_pk_fma_f32 v[96:97], v[4:5], v[128:129], v[96:97] op_sel:[0,1,0]
	v_pk_fma_f32 v[98:99], v[6:7], v[128:129], v[98:99] op_sel:[0,1,0]
	v_pk_fma_f32 v[96:97], v[8:9], v[130:131], v[96:97] op_sel_hi:[1,0,1]
	v_pk_fma_f32 v[98:99], v[10:11], v[130:131], v[98:99] op_sel_hi:[1,0,1]
	v_pk_fma_f32 v[96:97], v[12:13], v[130:131], v[96:97] op_sel:[0,1,0]
	v_pk_fma_f32 v[98:99], v[14:15], v[130:131], v[98:99] op_sel:[0,1,0]
	v_pk_fma_f32 v[96:97], v[20:21], v[132:133], v[96:97] op_sel_hi:[1,0,1]
	v_pk_fma_f32 v[98:99], v[22:23], v[132:133], v[98:99] op_sel_hi:[1,0,1]
	v_pk_fma_f32 v[96:97], v[24:25], v[132:133], v[96:97] op_sel:[0,1,0]
	v_pk_fma_f32 v[98:99], v[26:27], v[132:133], v[98:99] op_sel:[0,1,0]
	v_pk_fma_f32 v[96:97], v[28:29], v[134:135], v[96:97] op_sel_hi:[1,0,1]
	v_pk_fma_f32 v[98:99], v[30:31], v[134:135], v[98:99] op_sel_hi:[1,0,1]
	v_pk_fma_f32 v[96:97], v[32:33], v[134:135], v[96:97] op_sel:[0,1,0]
	v_pk_fma_f32 v[98:99], v[34:35], v[134:135], v[98:99] op_sel:[0,1,0]
	global_store_dwordx4 v110, v[96:99], s[14:15] nt
	ds_read_b128 v[128:131], v118 offset:1824
	ds_read_b128 v[132:135], v118 offset:1840
	ds_read_b32 v136, v16 offset:112
	s_waitcnt vmcnt(23) lgkmcnt(3)
	v_pk_fma_f32 v[64:65], v[100:101], v[120:121], v[64:65] op_sel_hi:[1,0,1]
	v_pk_fma_f32 v[66:67], v[102:103], v[120:121], v[66:67] op_sel_hi:[1,0,1]
	v_pk_fma_f32 v[60:61], v[100:101], v[120:121], v[60:61] op_sel:[0,1,0]
	v_pk_fma_f32 v[62:63], v[102:103], v[120:121], v[62:63] op_sel:[0,1,0]
	v_pk_fma_f32 v[56:57], v[100:101], v[122:123], v[56:57] op_sel_hi:[1,0,1]
	v_pk_fma_f32 v[58:59], v[102:103], v[122:123], v[58:59] op_sel_hi:[1,0,1]
	v_pk_fma_f32 v[52:53], v[100:101], v[122:123], v[52:53] op_sel:[0,1,0]
	v_pk_fma_f32 v[54:55], v[102:103], v[122:123], v[54:55] op_sel:[0,1,0]
	v_pk_fma_f32 v[48:49], v[100:101], v[124:125], v[48:49] op_sel_hi:[1,0,1]
	v_pk_fma_f32 v[50:51], v[102:103], v[124:125], v[50:51] op_sel_hi:[1,0,1]
	v_pk_fma_f32 v[40:41], v[100:101], v[124:125], v[40:41] op_sel:[0,1,0]
	v_pk_fma_f32 v[42:43], v[102:103], v[124:125], v[42:43] op_sel:[0,1,0]
	v_pk_fma_f32 v[36:37], v[100:101], v[126:127], v[36:37] op_sel_hi:[1,0,1]
	v_pk_fma_f32 v[38:39], v[102:103], v[126:127], v[38:39] op_sel_hi:[1,0,1]
	v_pk_fma_f32 v[44:45], v[100:101], v[126:127], v[44:45] op_sel:[0,1,0]
	v_pk_fma_f32 v[46:47], v[102:103], v[126:127], v[46:47] op_sel:[0,1,0]
	ds_read_b128 v[120:123], v118 offset:2048
	ds_read_b128 v[124:127], v118 offset:2064
	s_waitcnt lgkmcnt(2)
; #define LAS __attribute__((address_space(3)))
; template <int TY> __device__ __forceinline__ void sample_item(const Params& p, ldsp lds, int item) {
;     ...
; #pragma unroll 8
;     for (int d = dg; d < DK; d += NG) { const f32x4 s0 = __builtin_nontemporal_load((const f32x4*)(S0 + (size_t)d * DV + e4 * 4));
;         const f32x4 qa = *(const LAS f32x4*)(QK + d * 16), qb = *(const LAS f32x4*)(QK + d * 16 + 4), ka = *(const LAS f32x4*)(QK + d * 16 + 8), kb = *(const LAS f32x4*)(QK + d * 16 + 12);
;         const float dc = DECs[d];
;         o[0] += s0 * qa[0]; o[1] += s0 * qa[1]; o[2] += s0 * qa[2]; o[3] += s0 * qa[3]; o[4] += s0 * qb[0]; o[5] += s0 * qb[1]; o[6] += s0 * qb[2]; o[7] += s0 * qb[3];
;         f32x4 sn = s0 * dc; sn += v[0] * ka[0]; sn += v[1] * ka[1]; sn += v[2] * ka[2]; sn += v[3] * ka[3]; sn += v[4] * kb[0]; sn += v[5] * kb[1]; sn += v[6] * kb[2]; sn += v[7] * kb[3];
;         __builtin_nontemporal_store(sn, (f32x4*)(S1 + (size_t)d * DV + e4 * 4)); }
	v_pk_mul_f32 v[100:101], v[100:101], v[136:137] op_sel_hi:[1,0]
	v_pk_mul_f32 v[102:103], v[102:103], v[136:137] op_sel_hi:[1,0]
	v_pk_fma_f32 v[100:101], v[0:1], v[128:129], v[100:101] op_sel_hi:[1,0,1]
	v_pk_fma_f32 v[102:103], v[2:3], v[128:129], v[102:103] op_sel_hi:[1,0,1]
	v_pk_fma_f32 v[100:101], v[4:5], v[128:129], v[100:101] op_sel:[0,1,0]
	v_pk_fma_f32 v[102:103], v[6:7], v[128:129], v[102:103] op_sel:[0,1,0]
	v_pk_fma_f32 v[100:101], v[8:9], v[130:131], v[100:101] op_sel_hi:[1,0,1]
	v_pk_fma_f32 v[102:103], v[10:11], v[130:131], v[102:103] op_sel_hi:[1,0,1]
	v_pk_fma_f32 v[100:101], v[12:13], v[130:131], v[100:101] op_sel:[0,1,0]
	v_pk_fma_f32 v[102:103], v[14:15], v[130:131], v[102:103] op_sel:[0,1,0]
	v_pk_fma_f32 v[100:101], v[20:21], v[132:133], v[100:101] op_sel_hi:[1,0,1]
	v_pk_fma_f32 v[102:103], v[22:23], v[132:133], v[102:103] op_sel_hi:[1,0,1]
	v_pk_fma_f32 v[100:101], v[24:25], v[132:133], v[100:101] op_sel:[0,1,0]
	v_pk_fma_f32 v[102:103], v[26:27], v[132:133], v[102:103] op_sel:[0,1,0]
	v_pk_fma_f32 v[100:101], v[28:29], v[134:135], v[100:101] op_sel_hi:[1,0,1]
	v_pk_fma_f32 v[102:103], v[30:31], v[134:135], v[102:103] op_sel_hi:[1,0,1]
	v_pk_fma_f32 v[100:101], v[32:33], v[134:135], v[100:101] op_sel:[0,1,0]
	v_pk_fma_f32 v[102:103], v[34:35], v[134:135], v[102:103] op_sel:[0,1,0]
	global_store_dwordx4 v111, v[100:103], s[14:15] nt
	ds_read_b128 v[128:131], v118 offset:2080
	ds_read_b128 v[132:135], v118 offset:2096
	ds_read_b32 v136, v16 offset:128
	s_waitcnt vmcnt(22) lgkmcnt(3)
	v_pk_fma_f32 v[64:65], v[210:211], v[120:121], v[64:65] op_sel_hi:[1,0,1]
	v_pk_fma_f32 v[66:67], v[212:213], v[120:121], v[66:67] op_sel_hi:[1,0,1]
	v_pk_fma_f32 v[60:61], v[210:211], v[120:121], v[60:61] op_sel:[0,1,0]
	v_pk_fma_f32 v[62:63], v[212:213], v[120:121], v[62:63] op_sel:[0,1,0]
	v_pk_fma_f32 v[56:57], v[210:211], v[122:123], v[56:57] op_sel_hi:[1,0,1]
	v_pk_fma_f32 v[58:59], v[212:213], v[122:123], v[58:59] op_sel_hi:[1,0,1]
	v_pk_fma_f32 v[52:53], v[210:211], v[122:123], v[52:53] op_sel:[0,1,0]
	v_pk_fma_f32 v[54:55], v[212:213], v[122:123], v[54:55] op_sel:[0,1,0]
	v_pk_fma_f32 v[48:49], v[210:211], v[124:125], v[48:49] op_sel_hi:[1,0,1]
	v_pk_fma_f32 v[50:51], v[212:213], v[124:125], v[50:51] op_sel_hi:[1,0,1]
	v_pk_fma_f32 v[40:41], v[210:211], v[124:125], v[40:41] op_sel:[0,1,0]
	v_pk_fma_f32 v[42:43], v[212:213], v[124:125], v[42:43] op_sel:[0,1,0]
	v_pk_fma_f32 v[36:37], v[210:211], v[126:127], v[36:37] op_sel_hi:[1,0,1]
	v_pk_fma_f32 v[38:39], v[212:213], v[126:127], v[38:39] op_sel_hi:[1,0,1]
	v_pk_fma_f32 v[44:45], v[210:211], v[126:127], v[44:45] op_sel:[0,1,0]
	v_pk_fma_f32 v[46:47], v[212:213], v[126:127], v[46:47] op_sel:[0,1,0]
	ds_read_b128 v[120:123], v118 offset:2304
	ds_read_b128 v[124:127], v118 offset:2320
	s_waitcnt lgkmcnt(2)
	v_pk_mul_f32 v[210:211], v[210:211], v[136:137] op_sel_hi:[1,0]
	v_pk_mul_f32 v[212:213], v[212:213], v[136:137] op_sel_hi:[1,0]
	v_pk_fma_f32 v[210:211], v[0:1], v[128:129], v[210:211] op_sel_hi:[1,0,1]
	v_pk_fma_f32 v[212:213], v[2:3], v[128:129], v[212:213] op_sel_hi:[1,0,1]
	v_pk_fma_f32 v[210:211], v[4:5], v[128:129], v[210:211] op_sel:[0,1,0]
	v_pk_fma_f32 v[212:213], v[6:7], v[128:129], v[212:213] op_sel:[0,1,0]
	v_pk_fma_f32 v[210:211], v[8:9], v[130:131], v[210:211] op_sel_hi:[1,0,1]
	v_pk_fma_f32 v[212:213], v[10:11], v[130:131], v[212:213] op_sel_hi:[1,0,1]
	v_pk_fma_f32 v[210:211], v[12:13], v[130:131], v[210:211] op_sel:[0,1,0]
	v_pk_fma_f32 v[212:213], v[14:15], v[130:131], v[212:213] op_sel:[0,1,0]
	v_pk_fma_f32 v[210:211], v[20:21], v[132:133], v[210:211] op_sel_hi:[1,0,1]
	v_pk_fma_f32 v[212:213], v[22:23], v[132:133], v[212:213] op_sel_hi:[1,0,1]
	v_pk_fma_f32 v[210:211], v[24:25], v[132:133], v[210:211] op_sel:[0,1,0]
	v_pk_fma_f32 v[212:213], v[26:27], v[132:133], v[212:213] op_sel:[0,1,0]
	v_pk_fma_f32 v[210:211], v[28:29], v[134:135], v[210:211] op_sel_hi:[1,0,1]
	v_pk_fma_f32 v[212:213], v[30:31], v[134:135], v[212:213] op_sel_hi:[1,0,1]
	v_pk_fma_f32 v[210:211], v[32:33], v[134:135], v[210:211] op_sel:[0,1,0]
	v_pk_fma_f32 v[212:213], v[34:35], v[134:135], v[212:213] op_sel:[0,1,0]
	global_store_dwordx4 v242, v[210:213], s[14:15] nt
	ds_read_b128 v[128:131], v118 offset:2336
	ds_read_b128 v[132:135], v118 offset:2352
	ds_read_b32 v136, v16 offset:144
	s_waitcnt vmcnt(21) lgkmcnt(3)
	v_pk_fma_f32 v[64:65], v[214:215], v[120:121], v[64:65] op_sel_hi:[1,0,1]
	v_pk_fma_f32 v[66:67], v[216:217], v[120:121], v[66:67] op_sel_hi:[1,0,1]
	v_pk_fma_f32 v[60:61], v[214:215], v[120:121], v[60:61] op_sel:[0,1,0]
	v_pk_fma_f32 v[62:63], v[216:217], v[120:121], v[62:63] op_sel:[0,1,0]
	v_pk_fma_f32 v[56:57], v[214:215], v[122:123], v[56:57] op_sel_hi:[1,0,1]
	v_pk_fma_f32 v[58:59], v[216:217], v[122:123], v[58:59] op_sel_hi:[1,0,1]
	v_pk_fma_f32 v[52:53], v[214:215], v[122:123], v[52:53] op_sel:[0,1,0]
	v_pk_fma_f32 v[54:55], v[216:217], v[122:123], v[54:55] op_sel:[0,1,0]
	v_pk_fma_f32 v[48:49], v[214:215], v[124:125], v[48:49] op_sel_hi:[1,0,1]
	v_pk_fma_f32 v[50:51], v[216:217], v[124:125], v[50:51] op_sel_hi:[1,0,1]
	v_pk_fma_f32 v[40:41], v[214:215], v[124:125], v[40:41] op_sel:[0,1,0]
	v_pk_fma_f32 v[42:43], v[216:217], v[124:125], v[42:43] op_sel:[0,1,0]
	v_pk_fma_f32 v[36:37], v[214:215], v[126:127], v[36:37] op_sel_hi:[1,0,1]
	v_pk_fma_f32 v[38:39], v[216:217], v[126:127], v[38:39] op_sel_hi:[1,0,1]
	v_pk_fma_f32 v[44:45], v[214:215], v[126:127], v[44:45] op_sel:[0,1,0]
	v_pk_fma_f32 v[46:47], v[216:217], v[126:127], v[46:47] op_sel:[0,1,0]
	ds_read_b128 v[120:123], v118 offset:2560
	ds_read_b128 v[124:127], v118 offset:2576
	s_waitcnt lgkmcnt(2)
; #define LAS __attribute__((address_space(3)))
; template <int TY> __device__ __forceinline__ void sample_item(const Params& p, ldsp lds, int item) {
;     ...
; #pragma unroll 8
;     for (int d = dg; d < DK; d += NG) { const f32x4 s0 = __builtin_nontemporal_load((const f32x4*)(S0 + (size_t)d * DV + e4 * 4));
;         const f32x4 qa = *(const LAS f32x4*)(QK + d * 16), qb = *(const LAS f32x4*)(QK + d * 16 + 4), ka = *(const LAS f32x4*)(QK + d * 16 + 8), kb = *(const LAS f32x4*)(QK + d * 16 + 12);
;         const float dc = DECs[d];
;         o[0] += s0 * qa[0]; o[1] += s0 * qa[1]; o[2] += s0 * qa[2]; o[3] += s0 * qa[3]; o[4] += s0 * qb[0]; o[5] += s0 * qb[1]; o[6] += s0 * qb[2]; o[7] += s0 * qb[3];
;         f32x4 sn = s0 * dc; sn += v[0] * ka[0]; sn += v[1] * ka[1]; sn += v[2] * ka[2]; sn += v[3] * ka[3]; sn += v[4] * kb[0]; sn += v[5] * kb[1]; sn += v[6] * kb[2]; sn += v[7] * kb[3];
;         __builtin_nontemporal_store(sn, (f32x4*)(S1 + (size_t)d * DV + e4 * 4)); }
	v_pk_mul_f32 v[214:215], v[214:215], v[136:137] op_sel_hi:[1,0]
	v_pk_mul_f32 v[216:217], v[216:217], v[136:137] op_sel_hi:[1,0]
	v_pk_fma_f32 v[214:215], v[0:1], v[128:129], v[214:215] op_sel_hi:[1,0,1]
	v_pk_fma_f32 v[216:217], v[2:3], v[128:129], v[216:217] op_sel_hi:[1,0,1]
	v_pk_fma_f32 v[214:215], v[4:5], v[128:129], v[214:215] op_sel:[0,1,0]
	v_pk_fma_f32 v[216:217], v[6:7], v[128:129], v[216:217] op_sel:[0,1,0]
	v_pk_fma_f32 v[214:215], v[8:9], v[130:131], v[214:215] op_sel_hi:[1,0,1]
	v_pk_fma_f32 v[216:217], v[10:11], v[130:131], v[216:217] op_sel_hi:[1,0,1]
	v_pk_fma_f32 v[214:215], v[12:13], v[130:131], v[214:215] op_sel:[0,1,0]
	v_pk_fma_f32 v[216:217], v[14:15], v[130:131], v[216:217] op_sel:[0,1,0]
	v_pk_fma_f32 v[214:215], v[20:21], v[132:133], v[214:215] op_sel_hi:[1,0,1]
	v_pk_fma_f32 v[216:217], v[22:23], v[132:133], v[216:217] op_sel_hi:[1,0,1]
	v_pk_fma_f32 v[214:215], v[24:25], v[132:133], v[214:215] op_sel:[0,1,0]
	v_pk_fma_f32 v[216:217], v[26:27], v[132:133], v[216:217] op_sel:[0,1,0]
	v_pk_fma_f32 v[214:215], v[28:29], v[134:135], v[214:215] op_sel_hi:[1,0,1]
	v_pk_fma_f32 v[216:217], v[30:31], v[134:135], v[216:217] op_sel_hi:[1,0,1]
	v_pk_fma_f32 v[214:215], v[32:33], v[134:135], v[214:215] op_sel:[0,1,0]
	v_pk_fma_f32 v[216:217], v[34:35], v[134:135], v[216:217] op_sel:[0,1,0]
	global_store_dwordx4 v243, v[214:217], s[14:15] nt
	ds_read_b128 v[128:131], v118 offset:2592
	ds_read_b128 v[132:135], v118 offset:2608
	ds_read_b32 v136, v16 offset:160
	s_waitcnt vmcnt(20) lgkmcnt(3)
	v_pk_fma_f32 v[64:65], v[218:219], v[120:121], v[64:65] op_sel_hi:[1,0,1]
	v_pk_fma_f32 v[66:67], v[220:221], v[120:121], v[66:67] op_sel_hi:[1,0,1]
	v_pk_fma_f32 v[60:61], v[218:219], v[120:121], v[60:61] op_sel:[0,1,0]
	v_pk_fma_f32 v[62:63], v[220:221], v[120:121], v[62:63] op_sel:[0,1,0]
	v_pk_fma_f32 v[56:57], v[218:219], v[122:123], v[56:57] op_sel_hi:[1,0,1]
	v_pk_fma_f32 v[58:59], v[220:221], v[122:123], v[58:59] op_sel_hi:[1,0,1]
	v_pk_fma_f32 v[52:53], v[218:219], v[122:123], v[52:53] op_sel:[0,1,0]
	v_pk_fma_f32 v[54:55], v[220:221], v[122:123], v[54:55] op_sel:[0,1,0]
	v_pk_fma_f32 v[48:49], v[218:219], v[124:125], v[48:49] op_sel_hi:[1,0,1]
	v_pk_fma_f32 v[50:51], v[220:221], v[124:125], v[50:51] op_sel_hi:[1,0,1]
	v_pk_fma_f32 v[40:41], v[218:219], v[124:125], v[40:41] op_sel:[0,1,0]
	v_pk_fma_f32 v[42:43], v[220:221], v[124:125], v[42:43] op_sel:[0,1,0]
	v_pk_fma_f32 v[36:37], v[218:219], v[126:127], v[36:37] op_sel_hi:[1,0,1]
	v_pk_fma_f32 v[38:39], v[220:221], v[126:127], v[38:39] op_sel_hi:[1,0,1]
	v_pk_fma_f32 v[44:45], v[218:219], v[126:127], v[44:45] op_sel:[0,1,0]
	v_pk_fma_f32 v[46:47], v[220:221], v[126:127], v[46:47] op_sel:[0,1,0]
	ds_read_b128 v[120:123], v118 offset:2816
	ds_read_b128 v[124:127], v118 offset:2832
	s_waitcnt lgkmcnt(2)
	v_pk_mul_f32 v[218:219], v[218:219], v[136:137] op_sel_hi:[1,0]
	v_pk_mul_f32 v[220:221], v[220:221], v[136:137] op_sel_hi:[1,0]
	v_pk_fma_f32 v[218:219], v[0:1], v[128:129], v[218:219] op_sel_hi:[1,0,1]
	v_pk_fma_f32 v[220:221], v[2:3], v[128:129], v[220:221] op_sel_hi:[1,0,1]
	v_pk_fma_f32 v[218:219], v[4:5], v[128:129], v[218:219] op_sel:[0,1,0]
	v_pk_fma_f32 v[220:221], v[6:7], v[128:129], v[220:221] op_sel:[0,1,0]
	v_pk_fma_f32 v[218:219], v[8:9], v[130:131], v[218:219] op_sel_hi:[1,0,1]
	v_pk_fma_f32 v[220:221], v[10:11], v[130:131], v[220:221] op_sel_hi:[1,0,1]
	v_pk_fma_f32 v[218:219], v[12:13], v[130:131], v[218:219] op_sel:[0,1,0]
	v_pk_fma_f32 v[220:221], v[14:15], v[130:131], v[220:221] op_sel:[0,1,0]
	v_pk_fma_f32 v[218:219], v[20:21], v[132:133], v[218:219] op_sel_hi:[1,0,1]
	v_pk_fma_f32 v[220:221], v[22:23], v[132:133], v[220:221] op_sel_hi:[1,0,1]
	v_pk_fma_f32 v[218:219], v[24:25], v[132:133], v[218:219] op_sel:[0,1,0]
	v_pk_fma_f32 v[220:221], v[26:27], v[132:133], v[220:221] op_sel:[0,1,0]
	v_pk_fma_f32 v[218:219], v[28:29], v[134:135], v[218:219] op_sel_hi:[1,0,1]
	v_pk_fma_f32 v[220:221], v[30:31], v[134:135], v[220:221] op_sel_hi:[1,0,1]
	v_pk_fma_f32 v[218:219], v[32:33], v[134:135], v[218:219] op_sel:[0,1,0]
	v_pk_fma_f32 v[220:221], v[34:35], v[134:135], v[220:221] op_sel:[0,1,0]
	global_store_dwordx4 v244, v[218:221], s[14:15] nt
	ds_read_b128 v[128:131], v118 offset:2848
	ds_read_b128 v[132:135], v118 offset:2864
	ds_read_b32 v136, v16 offset:176
	s_waitcnt vmcnt(19) lgkmcnt(3)
	v_pk_fma_f32 v[64:65], v[222:223], v[120:121], v[64:65] op_sel_hi:[1,0,1]
	v_pk_fma_f32 v[66:67], v[224:225], v[120:121], v[66:67] op_sel_hi:[1,0,1]
	v_pk_fma_f32 v[60:61], v[222:223], v[120:121], v[60:61] op_sel:[0,1,0]
	v_pk_fma_f32 v[62:63], v[224:225], v[120:121], v[62:63] op_sel:[0,1,0]
	v_pk_fma_f32 v[56:57], v[222:223], v[122:123], v[56:57] op_sel_hi:[1,0,1]
	v_pk_fma_f32 v[58:59], v[224:225], v[122:123], v[58:59] op_sel_hi:[1,0,1]
	v_pk_fma_f32 v[52:53], v[222:223], v[122:123], v[52:53] op_sel:[0,1,0]
	v_pk_fma_f32 v[54:55], v[224:225], v[122:123], v[54:55] op_sel:[0,1,0]
	v_pk_fma_f32 v[48:49], v[222:223], v[124:125], v[48:49] op_sel_hi:[1,0,1]
	v_pk_fma_f32 v[50:51], v[224:225], v[124:125], v[50:51] op_sel_hi:[1,0,1]
	v_pk_fma_f32 v[40:41], v[222:223], v[124:125], v[40:41] op_sel:[0,1,0]
	v_pk_fma_f32 v[42:43], v[224:225], v[124:125], v[42:43] op_sel:[0,1,0]
	v_pk_fma_f32 v[36:37], v[222:223], v[126:127], v[36:37] op_sel_hi:[1,0,1]
	v_pk_fma_f32 v[38:39], v[224:225], v[126:127], v[38:39] op_sel_hi:[1,0,1]
	v_pk_fma_f32 v[44:45], v[222:223], v[126:127], v[44:45] op_sel:[0,1,0]
	v_pk_fma_f32 v[46:47], v[224:225], v[126:127], v[46:47] op_sel:[0,1,0]
	ds_read_b128 v[120:123], v118 offset:3072
	ds_read_b128 v[124:127], v118 offset:3088
	s_waitcnt lgkmcnt(2)
; #define LAS __attribute__((address_space(3)))
; template <int TY> __device__ __forceinline__ void sample_item(const Params& p, ldsp lds, int item) {
;     ...
; #pragma unroll 8
;     for (int d = dg; d < DK; d += NG) { const f32x4 s0 = __builtin_nontemporal_load((const f32x4*)(S0 + (size_t)d * DV + e4 * 4));
;         const f32x4 qa = *(const LAS f32x4*)(QK + d * 16), qb = *(const LAS f32x4*)(QK + d * 16 + 4), ka = *(const LAS f32x4*)(QK + d * 16 + 8), kb = *(const LAS f32x4*)(QK + d * 16 + 12);
;         const float dc = DECs[d];
;         o[0] += s0 * qa[0]; o[1] += s0 * qa[1]; o[2] += s0 * qa[2]; o[3] += s0 * qa[3]; o[4] += s0 * qb[0]; o[5] += s0 * qb[1]; o[6] += s0 * qb[2]; o[7] += s0 * qb[3];
;         f32x4 sn = s0 * dc; sn += v[0] * ka[0]; sn += v[1] * ka[1]; sn += v[2] * ka[2]; sn += v[3] * ka[3]; sn += v[4] * kb[0]; sn += v[5] * kb[1]; sn += v[6] * kb[2]; sn += v[7] * kb[3];
;         __builtin_nontemporal_store(sn, (f32x4*)(S1 + (size_t)d * DV + e4 * 4)); }
	v_pk_mul_f32 v[222:223], v[222:223], v[136:137] op_sel_hi:[1,0]
	v_pk_mul_f32 v[224:225], v[224:225], v[136:137] op_sel_hi:[1,0]
	v_pk_fma_f32 v[222:223], v[0:1], v[128:129], v[222:223] op_sel_hi:[1,0,1]
	v_pk_fma_f32 v[224:225], v[2:3], v[128:129], v[224:225] op_sel_hi:[1,0,1]
	v_pk_fma_f32 v[222:223], v[4:5], v[128:129], v[222:223] op_sel:[0,1,0]
	v_pk_fma_f32 v[224:225], v[6:7], v[128:129], v[224:225] op_sel:[0,1,0]
	v_pk_fma_f32 v[222:223], v[8:9], v[130:131], v[222:223] op_sel_hi:[1,0,1]
	v_pk_fma_f32 v[224:225], v[10:11], v[130:131], v[224:225] op_sel_hi:[1,0,1]
	v_pk_fma_f32 v[222:223], v[12:13], v[130:131], v[222:223] op_sel:[0,1,0]
	v_pk_fma_f32 v[224:225], v[14:15], v[130:131], v[224:225] op_sel:[0,1,0]
	v_pk_fma_f32 v[222:223], v[20:21], v[132:133], v[222:223] op_sel_hi:[1,0,1]
	v_pk_fma_f32 v[224:225], v[22:23], v[132:133], v[224:225] op_sel_hi:[1,0,1]
	v_pk_fma_f32 v[222:223], v[24:25], v[132:133], v[222:223] op_sel:[0,1,0]
	v_pk_fma_f32 v[224:225], v[26:27], v[132:133], v[224:225] op_sel:[0,1,0]
	v_pk_fma_f32 v[222:223], v[28:29], v[134:135], v[222:223] op_sel_hi:[1,0,1]
	v_pk_fma_f32 v[224:225], v[30:31], v[134:135], v[224:225] op_sel_hi:[1,0,1]
	v_pk_fma_f32 v[222:223], v[32:33], v[134:135], v[222:223] op_sel:[0,1,0]
	v_pk_fma_f32 v[224:225], v[34:35], v[134:135], v[224:225] op_sel:[0,1,0]
	global_store_dwordx4 v245, v[222:225], s[14:15] nt
	ds_read_b128 v[128:131], v118 offset:3104
	ds_read_b128 v[132:135], v118 offset:3120
	ds_read_b32 v136, v16 offset:192
	s_waitcnt vmcnt(18) lgkmcnt(3)
	v_pk_fma_f32 v[64:65], v[226:227], v[120:121], v[64:65] op_sel_hi:[1,0,1]
	v_pk_fma_f32 v[66:67], v[228:229], v[120:121], v[66:67] op_sel_hi:[1,0,1]
	v_pk_fma_f32 v[60:61], v[226:227], v[120:121], v[60:61] op_sel:[0,1,0]
	v_pk_fma_f32 v[62:63], v[228:229], v[120:121], v[62:63] op_sel:[0,1,0]
	v_pk_fma_f32 v[56:57], v[226:227], v[122:123], v[56:57] op_sel_hi:[1,0,1]
	v_pk_fma_f32 v[58:59], v[228:229], v[122:123], v[58:59] op_sel_hi:[1,0,1]
	v_pk_fma_f32 v[52:53], v[226:227], v[122:123], v[52:53] op_sel:[0,1,0]
	v_pk_fma_f32 v[54:55], v[228:229], v[122:123], v[54:55] op_sel:[0,1,0]
	v_pk_fma_f32 v[48:49], v[226:227], v[124:125], v[48:49] op_sel_hi:[1,0,1]
	v_pk_fma_f32 v[50:51], v[228:229], v[124:125], v[50:51] op_sel_hi:[1,0,1]
	v_pk_fma_f32 v[40:41], v[226:227], v[124:125], v[40:41] op_sel:[0,1,0]
	v_pk_fma_f32 v[42:43], v[228:229], v[124:125], v[42:43] op_sel:[0,1,0]
	v_pk_fma_f32 v[36:37], v[226:227], v[126:127], v[36:37] op_sel_hi:[1,0,1]
	v_pk_fma_f32 v[38:39], v[228:229], v[126:127], v[38:39] op_sel_hi:[1,0,1]
	v_pk_fma_f32 v[44:45], v[226:227], v[126:127], v[44:45] op_sel:[0,1,0]
	v_pk_fma_f32 v[46:47], v[228:229], v[126:127], v[46:47] op_sel:[0,1,0]
	ds_read_b128 v[120:123], v118 offset:3328
	ds_read_b128 v[124:127], v118 offset:3344
	s_waitcnt lgkmcnt(2)
	v_pk_mul_f32 v[226:227], v[226:227], v[136:137] op_sel_hi:[1,0]
	v_pk_mul_f32 v[228:229], v[228:229], v[136:137] op_sel_hi:[1,0]
	v_pk_fma_f32 v[226:227], v[0:1], v[128:129], v[226:227] op_sel_hi:[1,0,1]
	v_pk_fma_f32 v[228:229], v[2:3], v[128:129], v[228:229] op_sel_hi:[1,0,1]
	v_pk_fma_f32 v[226:227], v[4:5], v[128:129], v[226:227] op_sel:[0,1,0]
	v_pk_fma_f32 v[228:229], v[6:7], v[128:129], v[228:229] op_sel:[0,1,0]
	v_pk_fma_f32 v[226:227], v[8:9], v[130:131], v[226:227] op_sel_hi:[1,0,1]
	v_pk_fma_f32 v[228:229], v[10:11], v[130:131], v[228:229] op_sel_hi:[1,0,1]
	v_pk_fma_f32 v[226:227], v[12:13], v[130:131], v[226:227] op_sel:[0,1,0]
	v_pk_fma_f32 v[228:229], v[14:15], v[130:131], v[228:229] op_sel:[0,1,0]
	v_pk_fma_f32 v[226:227], v[20:21], v[132:133], v[226:227] op_sel_hi:[1,0,1]
	v_pk_fma_f32 v[228:229], v[22:23], v[132:133], v[228:229] op_sel_hi:[1,0,1]
	v_pk_fma_f32 v[226:227], v[24:25], v[132:133], v[226:227] op_sel:[0,1,0]
	v_pk_fma_f32 v[228:229], v[26:27], v[132:133], v[228:229] op_sel:[0,1,0]
	v_pk_fma_f32 v[226:227], v[28:29], v[134:135], v[226:227] op_sel_hi:[1,0,1]
	v_pk_fma_f32 v[228:229], v[30:31], v[134:135], v[228:229] op_sel_hi:[1,0,1]
	v_pk_fma_f32 v[226:227], v[32:33], v[134:135], v[226:227] op_sel:[0,1,0]
	v_pk_fma_f32 v[228:229], v[34:35], v[134:135], v[228:229] op_sel:[0,1,0]
	global_store_dwordx4 v246, v[226:229], s[14:15] nt
	ds_read_b128 v[128:131], v118 offset:3360
	ds_read_b128 v[132:135], v118 offset:3376
	ds_read_b32 v136, v16 offset:208
	s_waitcnt vmcnt(17) lgkmcnt(3)
	v_pk_fma_f32 v[64:65], v[230:231], v[120:121], v[64:65] op_sel_hi:[1,0,1]
	v_pk_fma_f32 v[66:67], v[232:233], v[120:121], v[66:67] op_sel_hi:[1,0,1]
	v_pk_fma_f32 v[60:61], v[230:231], v[120:121], v[60:61] op_sel:[0,1,0]
	v_pk_fma_f32 v[62:63], v[232:233], v[120:121], v[62:63] op_sel:[0,1,0]
	v_pk_fma_f32 v[56:57], v[230:231], v[122:123], v[56:57] op_sel_hi:[1,0,1]
	v_pk_fma_f32 v[58:59], v[232:233], v[122:123], v[58:59] op_sel_hi:[1,0,1]
	v_pk_fma_f32 v[52:53], v[230:231], v[122:123], v[52:53] op_sel:[0,1,0]
	v_pk_fma_f32 v[54:55], v[232:233], v[122:123], v[54:55] op_sel:[0,1,0]
	v_pk_fma_f32 v[48:49], v[230:231], v[124:125], v[48:49] op_sel_hi:[1,0,1]
	v_pk_fma_f32 v[50:51], v[232:233], v[124:125], v[50:51] op_sel_hi:[1,0,1]
	v_pk_fma_f32 v[40:41], v[230:231], v[124:125], v[40:41] op_sel:[0,1,0]
	v_pk_fma_f32 v[42:43], v[232:233], v[124:125], v[42:43] op_sel:[0,1,0]
	v_pk_fma_f32 v[36:37], v[230:231], v[126:127], v[36:37] op_sel_hi:[1,0,1]
	v_pk_fma_f32 v[38:39], v[232:233], v[126:127], v[38:39] op_sel_hi:[1,0,1]
	v_pk_fma_f32 v[44:45], v[230:231], v[126:127], v[44:45] op_sel:[0,1,0]
	v_pk_fma_f32 v[46:47], v[232:233], v[126:127], v[46:47] op_sel:[0,1,0]
	ds_read_b128 v[120:123], v118 offset:3584
	ds_read_b128 v[124:127], v118 offset:3600
	s_waitcnt lgkmcnt(2)
; #define LAS __attribute__((address_space(3)))
; template <int TY> __device__ __forceinline__ void sample_item(const Params& p, ldsp lds, int item) {
;     ...
; #pragma unroll 8
;     for (int d = dg; d < DK; d += NG) { const f32x4 s0 = __builtin_nontemporal_load((const f32x4*)(S0 + (size_t)d * DV + e4 * 4));
;         const f32x4 qa = *(const LAS f32x4*)(QK + d * 16), qb = *(const LAS f32x4*)(QK + d * 16 + 4), ka = *(const LAS f32x4*)(QK + d * 16 + 8), kb = *(const LAS f32x4*)(QK + d * 16 + 12);
;         const float dc = DECs[d];
;         o[0] += s0 * qa[0]; o[1] += s0 * qa[1]; o[2] += s0 * qa[2]; o[3] += s0 * qa[3]; o[4] += s0 * qb[0]; o[5] += s0 * qb[1]; o[6] += s0 * qb[2]; o[7] += s0 * qb[3];
;         f32x4 sn = s0 * dc; sn += v[0] * ka[0]; sn += v[1] * ka[1]; sn += v[2] * ka[2]; sn += v[3] * ka[3]; sn += v[4] * kb[0]; sn += v[5] * kb[1]; sn += v[6] * kb[2]; sn += v[7] * kb[3];
;         __builtin_nontemporal_store(sn, (f32x4*)(S1 + (size_t)d * DV + e4 * 4)); }
	v_pk_mul_f32 v[230:231], v[230:231], v[136:137] op_sel_hi:[1,0]
	v_pk_mul_f32 v[232:233], v[232:233], v[136:137] op_sel_hi:[1,0]
	v_pk_fma_f32 v[230:231], v[0:1], v[128:129], v[230:231] op_sel_hi:[1,0,1]
	v_pk_fma_f32 v[232:233], v[2:3], v[128:129], v[232:233] op_sel_hi:[1,0,1]
	v_pk_fma_f32 v[230:231], v[4:5], v[128:129], v[230:231] op_sel:[0,1,0]
	v_pk_fma_f32 v[232:233], v[6:7], v[128:129], v[232:233] op_sel:[0,1,0]
	v_pk_fma_f32 v[230:231], v[8:9], v[130:131], v[230:231] op_sel_hi:[1,0,1]
	v_pk_fma_f32 v[232:233], v[10:11], v[130:131], v[232:233] op_sel_hi:[1,0,1]
	v_pk_fma_f32 v[230:231], v[12:13], v[130:131], v[230:231] op_sel:[0,1,0]
	v_pk_fma_f32 v[232:233], v[14:15], v[130:131], v[232:233] op_sel:[0,1,0]
	v_pk_fma_f32 v[230:231], v[20:21], v[132:133], v[230:231] op_sel_hi:[1,0,1]
	v_pk_fma_f32 v[232:233], v[22:23], v[132:133], v[232:233] op_sel_hi:[1,0,1]
	v_pk_fma_f32 v[230:231], v[24:25], v[132:133], v[230:231] op_sel:[0,1,0]
	v_pk_fma_f32 v[232:233], v[26:27], v[132:133], v[232:233] op_sel:[0,1,0]
	v_pk_fma_f32 v[230:231], v[28:29], v[134:135], v[230:231] op_sel_hi:[1,0,1]
	v_pk_fma_f32 v[232:233], v[30:31], v[134:135], v[232:233] op_sel_hi:[1,0,1]
	v_pk_fma_f32 v[230:231], v[32:33], v[134:135], v[230:231] op_sel:[0,1,0]
	v_pk_fma_f32 v[232:233], v[34:35], v[134:135], v[232:233] op_sel:[0,1,0]
	global_store_dwordx4 v247, v[230:233], s[14:15] nt
	ds_read_b128 v[128:131], v118 offset:3616
	ds_read_b128 v[132:135], v118 offset:3632
	ds_read_b32 v136, v16 offset:224
	s_waitcnt vmcnt(16) lgkmcnt(3)
	v_pk_fma_f32 v[64:65], v[234:235], v[120:121], v[64:65] op_sel_hi:[1,0,1]
	v_pk_fma_f32 v[66:67], v[236:237], v[120:121], v[66:67] op_sel_hi:[1,0,1]
	v_pk_fma_f32 v[60:61], v[234:235], v[120:121], v[60:61] op_sel:[0,1,0]
	v_pk_fma_f32 v[62:63], v[236:237], v[120:121], v[62:63] op_sel:[0,1,0]
	v_pk_fma_f32 v[56:57], v[234:235], v[122:123], v[56:57] op_sel_hi:[1,0,1]
	v_pk_fma_f32 v[58:59], v[236:237], v[122:123], v[58:59] op_sel_hi:[1,0,1]
	v_pk_fma_f32 v[52:53], v[234:235], v[122:123], v[52:53] op_sel:[0,1,0]
	v_pk_fma_f32 v[54:55], v[236:237], v[122:123], v[54:55] op_sel:[0,1,0]
	v_pk_fma_f32 v[48:49], v[234:235], v[124:125], v[48:49] op_sel_hi:[1,0,1]
	v_pk_fma_f32 v[50:51], v[236:237], v[124:125], v[50:51] op_sel_hi:[1,0,1]
	v_pk_fma_f32 v[40:41], v[234:235], v[124:125], v[40:41] op_sel:[0,1,0]
	v_pk_fma_f32 v[42:43], v[236:237], v[124:125], v[42:43] op_sel:[0,1,0]
	v_pk_fma_f32 v[36:37], v[234:235], v[126:127], v[36:37] op_sel_hi:[1,0,1]
	v_pk_fma_f32 v[38:39], v[236:237], v[126:127], v[38:39] op_sel_hi:[1,0,1]
	v_pk_fma_f32 v[44:45], v[234:235], v[126:127], v[44:45] op_sel:[0,1,0]
	v_pk_fma_f32 v[46:47], v[236:237], v[126:127], v[46:47] op_sel:[0,1,0]
	ds_read_b128 v[120:123], v118 offset:3840
	ds_read_b128 v[124:127], v118 offset:3856
	s_waitcnt lgkmcnt(2)
	v_pk_mul_f32 v[234:235], v[234:235], v[136:137] op_sel_hi:[1,0]
	v_pk_mul_f32 v[236:237], v[236:237], v[136:137] op_sel_hi:[1,0]
	v_pk_fma_f32 v[234:235], v[0:1], v[128:129], v[234:235] op_sel_hi:[1,0,1]
	v_pk_fma_f32 v[236:237], v[2:3], v[128:129], v[236:237] op_sel_hi:[1,0,1]
	v_pk_fma_f32 v[234:235], v[4:5], v[128:129], v[234:235] op_sel:[0,1,0]
	v_pk_fma_f32 v[236:237], v[6:7], v[128:129], v[236:237] op_sel:[0,1,0]
	v_pk_fma_f32 v[234:235], v[8:9], v[130:131], v[234:235] op_sel_hi:[1,0,1]
	v_pk_fma_f32 v[236:237], v[10:11], v[130:131], v[236:237] op_sel_hi:[1,0,1]
	v_pk_fma_f32 v[234:235], v[12:13], v[130:131], v[234:235] op_sel:[0,1,0]
	v_pk_fma_f32 v[236:237], v[14:15], v[130:131], v[236:237] op_sel:[0,1,0]
	v_pk_fma_f32 v[234:235], v[20:21], v[132:133], v[234:235] op_sel_hi:[1,0,1]
	v_pk_fma_f32 v[236:237], v[22:23], v[132:133], v[236:237] op_sel_hi:[1,0,1]
	v_pk_fma_f32 v[234:235], v[24:25], v[132:133], v[234:235] op_sel:[0,1,0]
	v_pk_fma_f32 v[236:237], v[26:27], v[132:133], v[236:237] op_sel:[0,1,0]
	v_pk_fma_f32 v[234:235], v[28:29], v[134:135], v[234:235] op_sel_hi:[1,0,1]
	v_pk_fma_f32 v[236:237], v[30:31], v[134:135], v[236:237] op_sel_hi:[1,0,1]
	v_pk_fma_f32 v[234:235], v[32:33], v[134:135], v[234:235] op_sel:[0,1,0]
	v_pk_fma_f32 v[236:237], v[34:35], v[134:135], v[236:237] op_sel:[0,1,0]
	global_store_dwordx4 v248, v[234:237], s[14:15] nt
	ds_read_b128 v[128:131], v118 offset:3872
	ds_read_b128 v[132:135], v118 offset:3888
	ds_read_b32 v136, v16 offset:240
	s_waitcnt vmcnt(15) lgkmcnt(3)
	v_pk_fma_f32 v[64:65], v[238:239], v[120:121], v[64:65] op_sel_hi:[1,0,1]
	v_pk_fma_f32 v[66:67], v[240:241], v[120:121], v[66:67] op_sel_hi:[1,0,1]
	v_pk_fma_f32 v[60:61], v[238:239], v[120:121], v[60:61] op_sel:[0,1,0]
	v_pk_fma_f32 v[62:63], v[240:241], v[120:121], v[62:63] op_sel:[0,1,0]
	v_pk_fma_f32 v[56:57], v[238:239], v[122:123], v[56:57] op_sel_hi:[1,0,1]
	v_pk_fma_f32 v[58:59], v[240:241], v[122:123], v[58:59] op_sel_hi:[1,0,1]
	v_pk_fma_f32 v[52:53], v[238:239], v[122:123], v[52:53] op_sel:[0,1,0]
	v_pk_fma_f32 v[54:55], v[240:241], v[122:123], v[54:55] op_sel:[0,1,0]
	v_pk_fma_f32 v[48:49], v[238:239], v[124:125], v[48:49] op_sel_hi:[1,0,1]
	v_pk_fma_f32 v[50:51], v[240:241], v[124:125], v[50:51] op_sel_hi:[1,0,1]
	v_pk_fma_f32 v[40:41], v[238:239], v[124:125], v[40:41] op_sel:[0,1,0]
	v_pk_fma_f32 v[42:43], v[240:241], v[124:125], v[42:43] op_sel:[0,1,0]
	v_pk_fma_f32 v[36:37], v[238:239], v[126:127], v[36:37] op_sel_hi:[1,0,1]
	v_pk_fma_f32 v[38:39], v[240:241], v[126:127], v[38:39] op_sel_hi:[1,0,1]
	v_pk_fma_f32 v[44:45], v[238:239], v[126:127], v[44:45] op_sel:[0,1,0]
	v_pk_fma_f32 v[46:47], v[240:241], v[126:127], v[46:47] op_sel:[0,1,0]
	s_waitcnt lgkmcnt(0)
	v_pk_mul_f32 v[238:239], v[238:239], v[136:137] op_sel_hi:[1,0]
	v_pk_mul_f32 v[240:241], v[240:241], v[136:137] op_sel_hi:[1,0]
	v_pk_fma_f32 v[238:239], v[0:1], v[128:129], v[238:239] op_sel_hi:[1,0,1]
	v_pk_fma_f32 v[240:241], v[2:3], v[128:129], v[240:241] op_sel_hi:[1,0,1]
	v_pk_fma_f32 v[238:239], v[4:5], v[128:129], v[238:239] op_sel:[0,1,0]
	v_pk_fma_f32 v[240:241], v[6:7], v[128:129], v[240:241] op_sel:[0,1,0]
	v_pk_fma_f32 v[238:239], v[8:9], v[130:131], v[238:239] op_sel_hi:[1,0,1]
	v_pk_fma_f32 v[240:241], v[10:11], v[130:131], v[240:241] op_sel_hi:[1,0,1]
	v_pk_fma_f32 v[238:239], v[12:13], v[130:131], v[238:239] op_sel:[0,1,0]
	v_pk_fma_f32 v[240:241], v[14:15], v[130:131], v[240:241] op_sel:[0,1,0]
	v_pk_fma_f32 v[238:239], v[20:21], v[132:133], v[238:239] op_sel_hi:[1,0,1]
	v_pk_fma_f32 v[240:241], v[22:23], v[132:133], v[240:241] op_sel_hi:[1,0,1]
	v_pk_fma_f32 v[238:239], v[24:25], v[132:133], v[238:239] op_sel:[0,1,0]
	v_pk_fma_f32 v[240:241], v[26:27], v[132:133], v[240:241] op_sel:[0,1,0]
	v_pk_fma_f32 v[238:239], v[28:29], v[134:135], v[238:239] op_sel_hi:[1,0,1]
	v_pk_fma_f32 v[240:241], v[30:31], v[134:135], v[240:241] op_sel_hi:[1,0,1]
	v_pk_fma_f32 v[238:239], v[32:33], v[134:135], v[238:239] op_sel:[0,1,0]
	v_pk_fma_f32 v[240:241], v[34:35], v[134:135], v[240:241] op_sel:[0,1,0]
	global_store_dwordx4 v249, v[238:241], s[14:15] nt
	s_or_b64 exec, exec, s[10:11]
